# v38 + packed f32 VOP3P ops in the attention regions split into single v_fma/v_mul/v_add (bit-identical)
# speedup vs baseline: 1.0050x; 1.0050x over previous
.LBB0_494:
	s_add_i32 s8, s18, s20
	s_add_i32 s8, s8, 1
	s_cmp_lt_i32 s8, 0
	s_cselect_b64 s[2:3], -1, 0
	s_or_b64 s[2:3], s[2:3], s[0:1]
	s_and_b64 vcc, exec, s[2:3]
	s_cbranch_vccnz .LBB0_498
	s_add_i32 s0, s13, s11
	s_and_b32 s21, s0, 0xc000
	v_add_u32_e32 v151, s21, v159
	v_add_u32_e32 v168, v151, v160
	ds_read_b128 v[66:69], v168
	v_add_u32_e32 v169, v151, v161
	ds_read_b128 v[180:183], v169
	v_add_u32_e32 v179, v151, v162
	v_add_u32_e32 v151, v151, v164
	s_waitcnt lgkmcnt(1)
	v_mfma_f32_32x32x16_bf16 v[82:97], v[66:69], v[98:101], 0
	ds_read_b128 v[66:69], v168 offset:8192
	s_waitcnt lgkmcnt(1)
	v_mfma_f32_32x32x16_bf16 v[82:97], v[180:183], v[102:105], v[82:97]
	ds_read_b128 v[180:183], v169 offset:8192
	s_waitcnt lgkmcnt(1)
	v_mfma_f32_32x32x16_bf16 v[66:81], v[66:69], v[98:101], 0
	s_waitcnt lgkmcnt(0)
	v_mfma_f32_32x32x16_bf16 v[66:81], v[180:183], v[102:105], v[66:81]
	ds_read_b128 v[180:183], v179
	s_waitcnt lgkmcnt(0)
	v_mfma_f32_32x32x16_bf16 v[82:97], v[180:183], v[106:109], v[82:97]
	ds_read_b128 v[180:183], v179 offset:8192
	s_waitcnt lgkmcnt(0)
	v_mfma_f32_32x32x16_bf16 v[66:81], v[180:183], v[106:109], v[66:81]
	ds_read_b128 v[180:183], v151
	s_waitcnt lgkmcnt(0)
	v_mfma_f32_32x32x16_bf16 v[82:97], v[180:183], v[110:113], v[82:97]
	ds_read_b128 v[180:183], v151 offset:8192
	s_waitcnt lgkmcnt(0)
	v_mfma_f32_32x32x16_bf16 v[66:81], v[180:183], v[110:113], v[66:81]
	ds_read_b128 v[180:183], v168 offset:128
	s_waitcnt lgkmcnt(0)
	v_mfma_f32_32x32x16_bf16 v[82:97], v[180:183], v[114:117], v[82:97]
	ds_read_b128 v[180:183], v168 offset:8320
	s_waitcnt lgkmcnt(0)
	v_mfma_f32_32x32x16_bf16 v[66:81], v[180:183], v[114:117], v[66:81]
	ds_read_b128 v[180:183], v169 offset:128
	s_waitcnt lgkmcnt(0)
	v_mfma_f32_32x32x16_bf16 v[82:97], v[180:183], v[118:121], v[82:97]
	ds_read_b128 v[180:183], v169 offset:8320
	s_waitcnt lgkmcnt(0)
	v_mfma_f32_32x32x16_bf16 v[66:81], v[180:183], v[118:121], v[66:81]
	ds_read_b128 v[180:183], v179 offset:128
	s_waitcnt lgkmcnt(0)
	v_mfma_f32_32x32x16_bf16 v[82:97], v[180:183], v[122:125], v[82:97]
	ds_read_b128 v[180:183], v179 offset:8320
	s_waitcnt lgkmcnt(0)
	v_mfma_f32_32x32x16_bf16 v[66:81], v[180:183], v[122:125], v[66:81]
	ds_read_b128 v[180:183], v151 offset:128
	s_waitcnt lgkmcnt(0)
	v_mfma_f32_32x32x16_bf16 v[82:97], v[180:183], v[126:129], v[82:97]
	ds_read_b128 v[180:183], v151 offset:8320
	s_waitcnt lgkmcnt(0)
	v_mfma_f32_32x32x16_bf16 v[66:81], v[180:183], v[126:129], v[66:81]
	s_add_i32 s0, s19, s9
	s_nop 7
	v_mul_f32_e64 v96, v96, s12
	v_mul_f32_e64 v97, v97, s12
	v_mul_f32_e64 v94, v94, s12
	v_mul_f32_e64 v95, v95, s12
	v_mul_f32 v92, v92, s12
	v_mul_f32 v93, v93, s12
	v_mul_f32 v90, v90, s12
	v_mul_f32 v91, v91, s12
	v_mul_f32 v88, v88, s12
	v_mul_f32 v89, v89, s12
	v_mul_f32 v86, v86, s12
	v_mul_f32 v87, v87, s12
	v_mul_f32 v84, v84, s12
	v_mul_f32 v85, v85, s12
	v_mul_f32 v82, v82, s12
	v_mul_f32 v83, v83, s12
	v_mul_f32 v80, v80, s12
	v_mul_f32 v81, v81, s12
	v_mul_f32 v78, v78, s12
	v_mul_f32 v79, v79, s12
	v_mul_f32 v76, v76, s12
	v_mul_f32 v77, v77, s12
	v_mul_f32 v74, v74, s12
	v_mul_f32 v75, v75, s12
	v_mul_f32 v72, v72, s12
	v_mul_f32 v73, v73, s12
	v_mul_f32 v70, v70, s12
	v_mul_f32 v71, v71, s12
	v_mul_f32 v68, v68, s12
	v_mul_f32 v69, v69, s12
	s_cmp_lt_i32 s0, s27
	v_mul_f32 v66, v66, s12
	v_mul_f32 v67, v67, s12
	s_cbranch_scc1 .LBB0_497
	v_cmp_gt_i32_e64 s[2:3], 26, v167
	v_cmp_gt_i32_e32 vcc, 27, v167
	v_cmp_gt_i32_e64 s[96:97], 25, v167
	v_cmp_gt_i32_e64 s[94:95], 24, v167
	v_cndmask_b32_e32 v97, v97, v175, vcc
	s_and_b64 vcc, vcc, s[2:3]
	v_cndmask_b32_e32 v96, v96, v175, vcc
	s_and_b64 vcc, vcc, s[96:97]
	v_cmp_gt_i32_e64 s[92:93], 19, v167
	v_cndmask_b32_e32 v95, v95, v175, vcc
	s_and_b64 vcc, vcc, s[94:95]
	v_cmp_gt_i32_e64 s[90:91], 18, v167
	v_cndmask_b32_e32 v94, v94, v175, vcc
	s_and_b64 vcc, vcc, s[92:93]
	v_cmp_gt_i32_e64 s[88:89], 17, v167
	v_cndmask_b32_e32 v93, v93, v175, vcc
	s_and_b64 vcc, vcc, s[90:91]
	v_cmp_gt_i32_e64 s[86:87], 16, v167
	v_cndmask_b32_e32 v92, v92, v175, vcc
	s_and_b64 vcc, vcc, s[88:89]
	v_cmp_gt_i32_e64 s[84:85], 11, v167
	v_cndmask_b32_e32 v91, v91, v175, vcc
	s_and_b64 vcc, vcc, s[86:87]
	v_cmp_gt_i32_e64 s[82:83], 10, v167
	v_cndmask_b32_e32 v90, v90, v175, vcc
	s_and_b64 vcc, vcc, s[84:85]
	v_cmp_gt_i32_e64 s[80:81], 9, v167
	v_cndmask_b32_e32 v89, v89, v175, vcc
	s_and_b64 vcc, vcc, s[82:83]
	v_cmp_gt_i32_e64 s[78:79], 8, v167
	v_cndmask_b32_e32 v88, v88, v175, vcc
	s_and_b64 vcc, vcc, s[80:81]
	v_cmp_gt_i32_e64 s[76:77], 3, v167
	v_cndmask_b32_e32 v87, v87, v175, vcc
	s_and_b64 vcc, vcc, s[78:79]
	v_cmp_gt_i32_e64 s[74:75], 2, v167
	v_cndmask_b32_e32 v86, v86, v175, vcc
	s_and_b64 vcc, vcc, s[76:77]
	v_cmp_gt_i32_e64 s[72:73], 1, v167
	v_cndmask_b32_e32 v85, v85, v175, vcc
	s_and_b64 vcc, vcc, s[74:75]
	v_cmp_gt_i32_e64 s[70:71], 0, v167
	v_cndmask_b32_e32 v84, v84, v175, vcc
	s_and_b64 vcc, vcc, s[72:73]
	v_cndmask_b32_e32 v83, v83, v175, vcc
	s_and_b64 vcc, vcc, s[70:71]
	v_cmp_gt_i32_e64 s[68:69], 58, v167
	v_cndmask_b32_e32 v82, v82, v175, vcc
	v_cmp_gt_i32_e32 vcc, 59, v167
	v_cmp_gt_i32_e64 s[66:67], 57, v167
	v_cmp_gt_i32_e64 s[64:65], 56, v167
	v_cndmask_b32_e32 v81, v81, v175, vcc
	s_and_b64 vcc, vcc, s[68:69]
	v_cndmask_b32_e32 v80, v80, v175, vcc
	s_and_b64 vcc, vcc, s[66:67]
	v_cmp_gt_i32_e64 s[62:63], 51, v167
	v_cndmask_b32_e32 v79, v79, v175, vcc
	s_and_b64 vcc, vcc, s[64:65]
	v_cmp_gt_i32_e64 s[60:61], 50, v167
	v_cndmask_b32_e32 v78, v78, v175, vcc
	s_and_b64 vcc, vcc, s[62:63]
	v_cmp_gt_i32_e64 s[58:59], 49, v167
	v_cndmask_b32_e32 v77, v77, v175, vcc
	s_and_b64 vcc, vcc, s[60:61]
	v_cmp_gt_i32_e64 s[56:57], 48, v167
	v_cndmask_b32_e32 v76, v76, v175, vcc
	s_and_b64 vcc, vcc, s[58:59]
	v_cmp_gt_i32_e64 s[54:55], 43, v167
	v_cndmask_b32_e32 v75, v75, v175, vcc
	s_and_b64 vcc, vcc, s[56:57]
	v_cmp_gt_i32_e64 s[52:53], 42, v167
	v_cndmask_b32_e32 v74, v74, v175, vcc
	s_and_b64 vcc, vcc, s[54:55]
	v_cmp_gt_i32_e64 s[50:51], 41, v167
	v_cndmask_b32_e32 v73, v73, v175, vcc
	s_and_b64 vcc, vcc, s[52:53]
	v_cmp_gt_i32_e64 s[48:49], 40, v167
	v_cndmask_b32_e32 v72, v72, v175, vcc
	s_and_b64 vcc, vcc, s[50:51]
	v_cmp_gt_i32_e64 s[46:47], 35, v167
	v_cndmask_b32_e32 v71, v71, v175, vcc
	s_and_b64 vcc, vcc, s[48:49]
	v_cmp_gt_i32_e64 s[44:45], 34, v167
	v_cndmask_b32_e32 v70, v70, v175, vcc
	s_and_b64 vcc, vcc, s[46:47]
	v_cmp_gt_i32_e64 s[42:43], 33, v167
	v_cndmask_b32_e32 v69, v69, v175, vcc
	s_and_b64 vcc, vcc, s[44:45]
	v_cmp_gt_i32_e64 s[0:1], 32, v167
	v_cndmask_b32_e32 v68, v68, v175, vcc
	s_and_b64 vcc, vcc, s[42:43]
	v_readlane_b32 s88, v242, 2
	v_cndmask_b32_e32 v67, v67, v175, vcc
	s_and_b64 vcc, vcc, s[0:1]
	s_movk_i32 s93, 0x6018
	s_mov_b32 s92, 0xf800000
	s_mov_b64 s[90:91], s[16:17]
	v_readlane_b32 s89, v242, 3
	v_readlane_b32 s86, v242, 0
	s_movk_i32 s83, 0x6000
	s_mov_b32 s56, s30
	v_cndmask_b32_e32 v66, v66, v175, vcc
	v_readlane_b32 s87, v242, 1
.LBB0_497:
	v_exp_f32_e64 v151, -|v85|
	v_cmp_lt_f32_e32 vcc, 0, v85
	v_add_f32_e32 v168, 1.0, v151
	v_rcp_f32_e32 v168, v168
	s_nop 0
	v_mul_f32_e32 v151, v151, v168
	v_cndmask_b32_e32 v85, v151, v168, vcc
	v_cndmask_b32_e32 v151, v168, v151, vcc
	v_exp_f32_e64 v168, -|v69|
	v_cmp_lt_f32_e32 vcc, 0, v69
	v_add_f32_e32 v169, 1.0, v168
	v_rcp_f32_e32 v169, v169
	s_nop 0
	v_mul_f32_e32 v168, v168, v169
	v_cndmask_b32_e32 v69, v168, v169, vcc
	v_cndmask_b32_e32 v168, v169, v168, vcc
	v_exp_f32_e64 v169, -|v84|
	v_cmp_lt_f32_e32 vcc, 0, v84
	v_add_f32_e32 v179, 1.0, v169
	v_rcp_f32_e32 v179, v179
	s_nop 0
	v_mul_f32_e32 v169, v169, v179
	v_cndmask_b32_e32 v84, v169, v179, vcc
	v_cndmask_b32_e32 v169, v179, v169, vcc
	v_mul_f32_e32 v84, v151, v84
	v_mul_f32_e32 v151, v151, v169
	v_exp_f32_e64 v169, -|v68|
	v_cmp_lt_f32_e32 vcc, 0, v68
	v_add_f32_e32 v179, 1.0, v169
	v_rcp_f32_e32 v179, v179
	s_nop 0
	v_mul_f32_e32 v169, v169, v179
	v_cndmask_b32_e32 v68, v169, v179, vcc
	v_cndmask_b32_e32 v169, v179, v169, vcc
	v_mul_f32_e32 v68, v168, v68
	v_mul_f32_e32 v168, v168, v169
	v_exp_f32_e64 v169, -|v83|
	v_cmp_lt_f32_e32 vcc, 0, v83
	v_add_f32_e32 v179, 1.0, v169
	v_rcp_f32_e32 v179, v179
	s_nop 0
	v_mul_f32_e32 v169, v169, v179
	v_cndmask_b32_e32 v83, v169, v179, vcc
	v_cndmask_b32_e32 v169, v179, v169, vcc
	v_mul_f32_e32 v83, v83, v151
	v_mul_f32_e32 v151, v169, v151
	v_exp_f32_e64 v169, -|v67|
	v_cmp_lt_f32_e32 vcc, 0, v67
	v_add_f32_e32 v179, 1.0, v169
	v_rcp_f32_e32 v179, v179
	s_nop 0
	v_mul_f32_e32 v169, v169, v179
	v_cndmask_b32_e32 v67, v169, v179, vcc
	v_cndmask_b32_e32 v169, v179, v169, vcc
	v_mul_f32_e32 v67, v67, v168
	v_mul_f32_e32 v169, v169, v168
	v_exp_f32_e64 v168, -|v82|
	v_cmp_lt_f32_e32 vcc, 0, v82
	v_add_f32_e32 v179, 1.0, v168
	v_rcp_f32_e32 v179, v179
	s_nop 0
	v_mul_f32_e32 v168, v168, v179
	v_cndmask_b32_e32 v82, v168, v179, vcc
	v_cndmask_b32_e32 v168, v179, v168, vcc
	v_mul_f32_e32 v82, v82, v151
	v_mul_f32_e32 v168, v168, v151
	v_exp_f32_e64 v151, -|v66|
	v_cmp_lt_f32_e32 vcc, 0, v66
	v_add_f32_e32 v179, 1.0, v151
	v_rcp_f32_e32 v179, v179
	s_nop 0
	v_mul_f32_e32 v151, v151, v179
	v_cndmask_b32_e32 v66, v151, v179, vcc
	v_cndmask_b32_e32 v151, v179, v151, vcc
	v_mul_f32_e32 v66, v66, v169
	v_mul_f32_e32 v169, v151, v169
	v_exp_f32_e64 v151, -|v89|
	v_cmp_lt_f32_e32 vcc, 0, v89
	v_add_f32_e32 v179, 1.0, v151
	v_rcp_f32_e32 v179, v179
	s_nop 0
	v_mul_f32_e32 v151, v151, v179
	v_cndmask_b32_e32 v89, v151, v179, vcc
	v_cndmask_b32_e32 v151, v179, v151, vcc
	v_exp_f32_e64 v179, -|v73|
	v_cmp_lt_f32_e32 vcc, 0, v73
	v_add_f32_e32 v180, 1.0, v179
	v_rcp_f32_e32 v180, v180
	s_nop 0
	v_mul_f32_e32 v179, v179, v180
	v_cndmask_b32_e32 v73, v179, v180, vcc
	v_cndmask_b32_e32 v179, v180, v179, vcc
	v_exp_f32_e64 v180, -|v88|
	v_cmp_lt_f32_e32 vcc, 0, v88
	v_add_f32_e32 v181, 1.0, v180
	v_rcp_f32_e32 v181, v181
	s_nop 0
	v_mul_f32_e32 v180, v180, v181
	v_cndmask_b32_e32 v88, v180, v181, vcc
	v_cndmask_b32_e32 v180, v181, v180, vcc
	v_mul_f32_e32 v88, v151, v88
	v_mul_f32_e32 v151, v151, v180
	v_exp_f32_e64 v180, -|v72|
	v_cmp_lt_f32_e32 vcc, 0, v72
	v_add_f32_e32 v181, 1.0, v180
	v_rcp_f32_e32 v181, v181
	s_nop 0
	v_mul_f32_e32 v180, v180, v181
	v_cndmask_b32_e32 v72, v180, v181, vcc
	v_cndmask_b32_e32 v180, v181, v180, vcc
	v_mul_f32_e32 v72, v179, v72
	v_mul_f32_e32 v179, v179, v180
	v_exp_f32_e64 v180, -|v87|
	v_cmp_lt_f32_e32 vcc, 0, v87
	v_add_f32_e32 v181, 1.0, v180
	v_rcp_f32_e32 v181, v181
	s_nop 0
	v_mul_f32_e32 v180, v180, v181
	v_cndmask_b32_e32 v87, v180, v181, vcc
	v_cndmask_b32_e32 v180, v181, v180, vcc
	v_mul_f32_e32 v87, v87, v151
	v_mul_f32_e32 v151, v180, v151
	v_exp_f32_e64 v180, -|v71|
	v_cmp_lt_f32_e32 vcc, 0, v71
	v_add_f32_e32 v181, 1.0, v180
	v_rcp_f32_e32 v181, v181
	s_nop 0
	v_mul_f32_e32 v180, v180, v181
	v_cndmask_b32_e32 v71, v180, v181, vcc
	v_cndmask_b32_e32 v180, v181, v180, vcc
	v_mul_f32_e32 v71, v71, v179
	v_mul_f32_e32 v180, v180, v179
	v_exp_f32_e64 v179, -|v86|
	v_cmp_lt_f32_e32 vcc, 0, v86
	v_add_f32_e32 v181, 1.0, v179
	v_rcp_f32_e32 v181, v181
	s_nop 0
	v_mul_f32_e32 v179, v179, v181
	v_cndmask_b32_e32 v86, v179, v181, vcc
	v_cndmask_b32_e32 v179, v181, v179, vcc
	v_mul_f32_e32 v86, v86, v151
	v_mul_f32_e32 v179, v179, v151
	v_exp_f32_e64 v151, -|v70|
	v_cmp_lt_f32_e32 vcc, 0, v70
	v_add_f32_e32 v181, 1.0, v151
	v_rcp_f32_e32 v181, v181
	s_nop 0
	v_mul_f32_e32 v151, v151, v181
	v_cndmask_b32_e32 v70, v151, v181, vcc
	v_cndmask_b32_e32 v151, v181, v151, vcc
	v_mul_f32_e32 v70, v70, v180
	v_mul_f32_e32 v180, v151, v180
	v_exp_f32_e64 v151, -|v93|
	v_cmp_lt_f32_e32 vcc, 0, v93
	v_add_f32_e32 v181, 1.0, v151
	v_rcp_f32_e32 v181, v181
	s_nop 0
	v_mul_f32_e32 v151, v151, v181
	v_cndmask_b32_e32 v93, v151, v181, vcc
	v_cndmask_b32_e32 v151, v181, v151, vcc
	v_exp_f32_e64 v181, -|v77|
	v_cmp_lt_f32_e32 vcc, 0, v77
	v_add_f32_e32 v182, 1.0, v181
	v_rcp_f32_e32 v182, v182
	s_nop 0
	v_mul_f32_e32 v181, v181, v182
	v_cndmask_b32_e32 v77, v181, v182, vcc
	v_cndmask_b32_e32 v181, v182, v181, vcc
	v_exp_f32_e64 v182, -|v92|
	v_cmp_lt_f32_e32 vcc, 0, v92
	v_add_f32_e32 v183, 1.0, v182
	v_rcp_f32_e32 v183, v183
	s_nop 0
	v_mul_f32_e32 v182, v182, v183
	v_cndmask_b32_e32 v92, v182, v183, vcc
	v_cndmask_b32_e32 v182, v183, v182, vcc
	v_mul_f32_e32 v92, v151, v92
	v_mul_f32_e32 v151, v151, v182
	v_exp_f32_e64 v182, -|v76|
	v_cmp_lt_f32_e32 vcc, 0, v76
	v_add_f32_e32 v183, 1.0, v182
	v_rcp_f32_e32 v183, v183
	s_nop 0
	v_mul_f32_e32 v182, v182, v183
	v_cndmask_b32_e32 v76, v182, v183, vcc
	v_cndmask_b32_e32 v182, v183, v182, vcc
	v_mul_f32_e32 v76, v181, v76
	v_mul_f32_e32 v181, v181, v182
	v_exp_f32_e64 v182, -|v91|
	v_cmp_lt_f32_e32 vcc, 0, v91
	v_add_f32_e32 v183, 1.0, v182
	v_rcp_f32_e32 v183, v183
	s_nop 0
	v_mul_f32_e32 v182, v182, v183
	v_cndmask_b32_e32 v91, v182, v183, vcc
	v_cndmask_b32_e32 v182, v183, v182, vcc
	v_mul_f32_e32 v91, v91, v151
	v_mul_f32_e32 v151, v182, v151
	v_exp_f32_e64 v182, -|v75|
	v_cmp_lt_f32_e32 vcc, 0, v75
	v_add_f32_e32 v183, 1.0, v182
	v_rcp_f32_e32 v183, v183
	s_nop 0
	v_mul_f32_e32 v182, v182, v183
	v_cndmask_b32_e32 v75, v182, v183, vcc
	v_cndmask_b32_e32 v182, v183, v182, vcc
	v_mul_f32_e32 v75, v75, v181
	v_mul_f32_e32 v182, v182, v181
	v_exp_f32_e64 v181, -|v90|
	v_cmp_lt_f32_e32 vcc, 0, v90
	v_add_f32_e32 v183, 1.0, v181
	v_rcp_f32_e32 v183, v183
	s_nop 0
	v_mul_f32_e32 v181, v181, v183
	v_cndmask_b32_e32 v90, v181, v183, vcc
	v_cndmask_b32_e32 v181, v183, v181, vcc
	v_mul_f32_e32 v90, v90, v151
	v_mul_f32_e32 v181, v181, v151
	v_exp_f32_e64 v151, -|v74|
	v_cmp_lt_f32_e32 vcc, 0, v74
	v_add_f32_e32 v183, 1.0, v151
	v_rcp_f32_e32 v183, v183
	s_nop 0
	v_mul_f32_e32 v151, v151, v183
	v_cndmask_b32_e32 v74, v151, v183, vcc
	v_cndmask_b32_e32 v151, v183, v151, vcc
	v_mul_f32_e32 v74, v74, v182
	v_mul_f32_e32 v151, v151, v182
	v_exp_f32_e64 v182, -|v97|
	v_cmp_lt_f32_e32 vcc, 0, v97
	v_add_f32_e32 v183, 1.0, v182
	v_rcp_f32_e32 v183, v183
	s_nop 0
	v_mul_f32_e32 v182, v182, v183
	v_cndmask_b32_e32 v97, v182, v183, vcc
	v_cndmask_b32_e32 v182, v183, v182, vcc
	v_exp_f32_e64 v183, -|v81|
	v_cmp_lt_f32_e32 vcc, 0, v81
	v_add_f32_e32 v184, 1.0, v183
	v_rcp_f32_e32 v184, v184
	s_nop 0
	v_mul_f32_e32 v183, v183, v184
	v_cndmask_b32_e32 v185, v183, v184, vcc
	v_cndmask_b32_e32 v81, v184, v183, vcc
	v_exp_f32_e64 v183, -|v96|
	v_cmp_lt_f32_e32 vcc, 0, v96
	v_add_f32_e32 v184, 1.0, v183
	v_rcp_f32_e32 v184, v184
	s_nop 0
	v_mul_f32_e32 v183, v183, v184
	v_cndmask_b32_e32 v96, v183, v184, vcc
	v_cndmask_b32_e32 v183, v184, v183, vcc
	v_mul_f32_e32 v96, v182, v96
	v_mul_f32_e32 v182, v182, v183
	v_exp_f32_e64 v183, -|v80|
	v_cmp_lt_f32_e32 vcc, 0, v80
	v_add_f32_e32 v184, 1.0, v183
	v_rcp_f32_e32 v184, v184
	s_nop 0
	v_mul_f32_e32 v183, v183, v184
	v_cndmask_b32_e32 v80, v183, v184, vcc
	v_mul_f32_e32 v186, v81, v80
	v_cndmask_b32_e32 v80, v184, v183, vcc
	v_mul_f32_e32 v80, v81, v80
	v_exp_f32_e64 v81, -|v95|
	v_cmp_lt_f32_e32 vcc, 0, v95
	v_add_f32_e32 v183, 1.0, v81
	v_rcp_f32_e32 v183, v183
	s_nop 0
	v_mul_f32_e32 v81, v81, v183
	v_cndmask_b32_e32 v95, v81, v183, vcc
	v_cndmask_b32_e32 v81, v183, v81, vcc
	v_mul_f32_e32 v95, v95, v182
	v_mul_f32_e32 v81, v81, v182
	v_exp_f32_e64 v182, -|v79|
	v_cmp_lt_f32_e32 vcc, 0, v79
	v_add_f32_e32 v183, 1.0, v182
	v_rcp_f32_e32 v183, v183
	s_nop 0
	v_mul_f32_e32 v182, v182, v183
	v_cndmask_b32_e32 v79, v182, v183, vcc
	v_mul_f32_e32 v184, v79, v80
	v_cndmask_b32_e32 v79, v183, v182, vcc
	v_mul_f32_e32 v79, v79, v80
	v_exp_f32_e64 v80, -|v94|
	v_cmp_lt_f32_e32 vcc, 0, v94
	v_add_f32_e32 v182, 1.0, v80
	v_rcp_f32_e32 v182, v182
	s_nop 0
	v_mul_f32_e32 v80, v80, v182
	v_cndmask_b32_e32 v94, v80, v182, vcc
	v_cndmask_b32_e32 v80, v182, v80, vcc
	v_mul_f32_e32 v182, v80, v81
	v_exp_f32_e64 v80, -|v78|
	v_mul_f32_e32 v94, v94, v81
	v_cmp_lt_f32_e32 vcc, 0, v78
	v_add_f32_e32 v81, 1.0, v80
	v_rcp_f32_e32 v81, v81
	s_nop 0
	v_mul_f32_e32 v80, v80, v81
	v_cndmask_b32_e32 v78, v80, v81, vcc
	v_mul_f32_e32 v183, v78, v79
	v_cndmask_b32_e32 v78, v81, v80, vcc
	v_mul_f32_e32 v78, v78, v79
	v_mov_b32_e32 v79, v78
	s_nop 1
	v_permlane32_swap_b32_e32 v78, v79
	v_mul_f32_e32 v80, v150, v79
	v_mul_f32_e32 v78, v78, v79
	v_mov_b32_e32 v79, v151
	s_nop 1
	v_permlane32_swap_b32_e32 v151, v79
	v_cndmask_b32_e64 v187, v150, v80, s[38:39]
	v_pk_mul_f32 v[80:81], v[150:151], v[78:79]
	s_nop 0
	v_mul_f32_e32 v78, v80, v79
	v_cndmask_b32_e64 v151, v80, v78, s[38:39]
	v_pk_mul_f32 v[78:79], v[80:81], v[80:81] op_sel:[0,1] op_sel_hi:[1,0]
	v_mov_b32_e32 v81, v169
	v_mov_b32_e32 v79, v180
	s_nop 1
	v_permlane32_swap_b32_e32 v180, v79
	v_mul_f32_e32 v80, v78, v79
	v_permlane32_swap_b32_e32 v169, v81
	v_cndmask_b32_e64 v188, v78, v80, s[38:39]
	v_mul_f32_e32 v80, v180, v79
	v_mov_b32_e32 v79, v169
	v_pk_mul_f32 v[78:79], v[78:79], v[80:81]
	s_nop 0
	v_mul_f32_e32 v80, v78, v81
	v_cndmask_b32_e64 v169, v78, v80, s[38:39]
	v_pk_mul_f32 v[78:79], v[78:79], v[78:79] op_sel:[0,1] op_sel_hi:[1,0]
	v_mov_b32_e32 v81, v181
	v_mov_b32_e32 v79, v182
	s_nop 1
	v_permlane32_swap_b32_e32 v182, v79
	v_mul_f32_e32 v80, v78, v79
	v_permlane32_swap_b32_e32 v181, v81
	v_cndmask_b32_e64 v180, v78, v80, s[38:39]
	v_mul_f32_e32 v80, v182, v79
	v_mov_b32_e32 v79, v181
	v_mul_f32 v78, v78, v80
	v_mul_f32 v79, v79, v81
	s_nop 0
	v_mul_f32_e32 v80, v78, v81
	v_cndmask_b32_e64 v181, v78, v80, s[38:39]
	v_pk_mul_f32 v[78:79], v[78:79], v[78:79] op_sel:[0,1] op_sel_hi:[1,0]
	v_mov_b32_e32 v81, v168
	v_mov_b32_e32 v79, v179
	s_nop 1
	v_permlane32_swap_b32_e32 v179, v79
	v_mul_f32_e32 v80, v78, v79
	v_permlane32_swap_b32_e32 v168, v81
	v_cndmask_b32_e64 v182, v78, v80, s[38:39]
	v_mul_f32_e32 v80, v179, v79
	v_mov_b32_e32 v79, v168
	v_mul_f32 v78, v78, v80
	v_mul_f32 v79, v79, v81
	s_nop 0
	v_mul_f32_e32 v80, v78, v81
	v_mul_f32_e32 v150, v78, v79
	v_cndmask_b32_e64 v80, v78, v80, s[38:39]
	v_cmp_eq_f32_e32 vcc, 0, v150
	v_mul_f32_e32 v78, v82, v80
	v_mul_f32_e32 v79, v66, v169
	v_mul_f32_e32 v66, v83, v80
	v_mul_f32_e32 v81, v67, v169
	v_mul_f32_e32 v67, v84, v80
	v_mul_f32_e32 v82, v68, v169
	v_mul_f32_e32 v68, v85, v80
	v_mul_f32_e32 v80, v69, v169
	v_mul_f32_e32 v69, v86, v182
	v_mul_f32_e32 v83, v188, v70
	v_mul_f32_e32 v70, v87, v182
	v_mul_f32_e32 v84, v71, v188
	v_mul_f32_e32 v71, v88, v182
	v_mul_f32_e32 v85, v72, v188
	v_mul_f32_e32 v72, v89, v182
	v_mul_f32_e32 v86, v73, v188
	v_mul_f32_e32 v73, v90, v181
	v_mul_f32_e32 v87, v151, v74
	v_mul_f32_e32 v74, v91, v181
	v_mul_f32_e32 v88, v151, v75
	v_mul_f32_e32 v75, v92, v181
	v_mul_f32_e32 v89, v76, v151
	v_mul_f32_e32 v76, v93, v181
	v_mul_f32_e32 v90, v77, v151
	v_mul_f32_e32 v77, v94, v180
	s_cmp_eq_u64 vcc, exec
	v_mul_f32_e32 v91, v187, v183
	v_mul_f32_e32 v92, v95, v180
	v_mul_f32_e32 v93, v187, v184
	v_mul_f32_e32 v94, v96, v180
	v_mul_f32_e32 v95, v187, v186
	v_mul_f32_e32 v96, v97, v180
	v_mul_f32_e32 v97, v187, v185
	s_cselect_b64 s[0:1], -1, 0
	v_cvt_pk_bf16_f32 v66, v78, v66
	v_cvt_pk_bf16_f32 v67, v67, v68
	v_cvt_pk_bf16_f32 v68, v69, v70
	v_cvt_pk_bf16_f32 v69, v71, v72
	v_cvt_pk_bf16_f32 v70, v73, v74
	v_cvt_pk_bf16_f32 v71, v75, v76
	v_cvt_pk_bf16_f32 v72, v77, v92
	v_cvt_pk_bf16_f32 v73, v94, v96
	v_cvt_pk_bf16_f32 v74, v79, v81
	v_cvt_pk_bf16_f32 v75, v82, v80
	v_cvt_pk_bf16_f32 v76, v83, v84
	v_cvt_pk_bf16_f32 v77, v85, v86
	v_cvt_pk_bf16_f32 v78, v87, v88
	v_cvt_pk_bf16_f32 v79, v89, v90
	v_cvt_pk_bf16_f32 v80, v91, v93
	v_cvt_pk_bf16_f32 v81, v95, v97
	s_nop 0
	v_permlane32_swap_b32_e32 v66, v68
	v_permlane32_swap_b32_e32 v67, v69
	v_permlane32_swap_b32_e32 v70, v72
	v_permlane32_swap_b32_e32 v71, v73
	v_permlane32_swap_b32_e32 v74, v76
	v_permlane32_swap_b32_e32 v75, v77
	v_permlane32_swap_b32_e32 v78, v80
	v_permlane32_swap_b32_e32 v79, v81
	v_add_u32_e32 v151, s21, v165
	ds_read_b64_tr_b16 v[82:83], v151 offset:0
	ds_read_b64_tr_b16 v[84:85], v151 offset:0x800
	ds_read_b64_tr_b16 v[86:87], v151 offset:0x1000
	ds_read_b64_tr_b16 v[88:89], v151 offset:0x1800
	ds_read_b64_tr_b16 v[90:91], v151 offset:0x2000
	ds_read_b64_tr_b16 v[92:93], v151 offset:0x2800
	ds_read_b64_tr_b16 v[94:95], v151 offset:0x3000
	ds_read_b64_tr_b16 v[96:97], v151 offset:0x3800
	s_nop 0
	s_waitcnt lgkmcnt(6)
	v_mfma_f32_32x32x16_bf16 v[50:65], v[66:69], v[82:85], v[50:65]
	ds_read_b64_tr_b16 v[82:83], v151 offset:0x200
	ds_read_b64_tr_b16 v[84:85], v151 offset:0xa00
	s_waitcnt lgkmcnt(6)
	v_mfma_f32_32x32x16_bf16 v[50:65], v[70:73], v[86:89], v[50:65]
	ds_read_b64_tr_b16 v[86:87], v151 offset:0x1200
	ds_read_b64_tr_b16 v[88:89], v151 offset:0x1a00
	s_waitcnt lgkmcnt(6)
	v_mfma_f32_32x32x16_bf16 v[50:65], v[74:77], v[90:93], v[50:65]
	ds_read_b64_tr_b16 v[90:91], v151 offset:0x2200
	ds_read_b64_tr_b16 v[92:93], v151 offset:0x2a00
	s_waitcnt lgkmcnt(6)
	v_mfma_f32_32x32x16_bf16 v[50:65], v[78:81], v[94:97], v[50:65]
	ds_read_b64_tr_b16 v[94:95], v151 offset:0x3200
	ds_read_b64_tr_b16 v[96:97], v151 offset:0x3a00
	s_waitcnt lgkmcnt(6)
	v_mfma_f32_32x32x16_bf16 v[34:49], v[66:69], v[82:85], v[34:49]
	ds_read_b64_tr_b16 v[82:83], v151 offset:0x400
	ds_read_b64_tr_b16 v[84:85], v151 offset:0xc00
	s_waitcnt lgkmcnt(6)
	v_mfma_f32_32x32x16_bf16 v[34:49], v[70:73], v[86:89], v[34:49]
	ds_read_b64_tr_b16 v[86:87], v151 offset:0x1400
	ds_read_b64_tr_b16 v[88:89], v151 offset:0x1c00
	s_waitcnt lgkmcnt(6)
	v_mfma_f32_32x32x16_bf16 v[34:49], v[74:77], v[90:93], v[34:49]
	ds_read_b64_tr_b16 v[90:91], v151 offset:0x2400
	ds_read_b64_tr_b16 v[92:93], v151 offset:0x2c00
	s_waitcnt lgkmcnt(6)
	v_mfma_f32_32x32x16_bf16 v[34:49], v[78:81], v[94:97], v[34:49]
	ds_read_b64_tr_b16 v[94:95], v151 offset:0x3400
	ds_read_b64_tr_b16 v[96:97], v151 offset:0x3c00
	s_waitcnt lgkmcnt(6)
	v_mfma_f32_32x32x16_bf16 v[18:33], v[66:69], v[82:85], v[18:33]
	ds_read_b64_tr_b16 v[82:83], v151 offset:0x600
	ds_read_b64_tr_b16 v[84:85], v151 offset:0xe00
	s_waitcnt lgkmcnt(6)
	v_mfma_f32_32x32x16_bf16 v[18:33], v[70:73], v[86:89], v[18:33]
	ds_read_b64_tr_b16 v[86:87], v151 offset:0x1600
	ds_read_b64_tr_b16 v[88:89], v151 offset:0x1e00
	s_waitcnt lgkmcnt(6)
	v_mfma_f32_32x32x16_bf16 v[18:33], v[74:77], v[90:93], v[18:33]
	ds_read_b64_tr_b16 v[90:91], v151 offset:0x2600
	ds_read_b64_tr_b16 v[92:93], v151 offset:0x2e00
	s_waitcnt lgkmcnt(6)
	v_mfma_f32_32x32x16_bf16 v[18:33], v[78:81], v[94:97], v[18:33]
	ds_read_b64_tr_b16 v[94:95], v151 offset:0x3600
	ds_read_b64_tr_b16 v[96:97], v151 offset:0x3e00
	s_waitcnt lgkmcnt(6)
	v_mfma_f32_32x32x16_bf16 v[2:17], v[66:69], v[82:85], v[2:17]
	s_waitcnt lgkmcnt(4)
	v_mfma_f32_32x32x16_bf16 v[2:17], v[70:73], v[86:89], v[2:17]
	s_waitcnt lgkmcnt(2)
	v_mfma_f32_32x32x16_bf16 v[2:17], v[74:77], v[90:93], v[2:17]
	s_waitcnt lgkmcnt(0)
	v_mfma_f32_32x32x16_bf16 v[2:17], v[78:81], v[94:97], v[2:17]

.LBB0_639:
	s_or_b64 exec, exec, s[0:1]
	s_abs_i32 s0, s13
	v_readlane_b32 s1, v243, 0
	s_mul_hi_u32 s1, s0, s1
	v_readlane_b32 s4, v243, 53
	s_mul_i32 s2, s1, s4
	s_sub_i32 s0, s0, s2
	s_ashr_i32 s8, s13, 31
	s_add_i32 s2, s1, 1
	s_sub_i32 s3, s0, s4
	s_cmp_ge_u32 s0, s4
	s_cselect_b32 s1, s2, s1
	s_cselect_b32 s0, s3, s0
	s_add_i32 s2, s1, 1
	s_cmp_ge_u32 s0, s4
	s_cselect_b32 s0, s2, s1
	s_xor_b32 s11, s0, s8
	s_sub_i32 s9, s11, s8
	s_mul_i32 s0, s9, s4
	s_sub_i32 s0, s13, s0
	v_readlane_b32 s1, v243, 54
	s_add_i32 s0, s0, s1
	s_ashr_i32 s1, s0, 31
	s_lshl_b64 s[2:3], s[0:1], 13
	v_readlane_b32 s4, v245, 11
	v_mov_b32_e32 v180, v0
	v_readlane_b32 s5, v245, 12
	s_add_u32 s2, s4, s2
	s_addc_u32 s3, s5, s3
	v_lshlrev_b32_e32 v6, 2, v180
	v_ashrrev_i32_e32 v7, 31, v6
	v_lshl_add_u64 v[2:3], v[6:7], 2, s[2:3]
	global_load_dwordx4 v[2:5], v[2:3], off
	v_and_b32_e32 v7, 64, v176
	v_add_u32_e32 v1, -1, v176
	v_cmp_lt_i32_e32 vcc, v1, v7
	v_and_b32_e32 v169, 63, v180
	v_add_u32_e32 v8, -2, v176
	v_cndmask_b32_e32 v1, v1, v176, vcc
	v_lshlrev_b32_e32 v1, 2, v1
	v_cmp_eq_u32_e32 vcc, 0, v169
	v_readfirstlane_b32 s13, v180
	s_ashr_i32 s5, s13, 6
	s_waitcnt vmcnt(0)
	v_add_f32_e32 v3, v2, v3
	v_add_f32_e32 v4, v4, v3
	v_add_f32_e32 v5, v5, v4
	ds_bpermute_b32 v1, v1, v5
	s_waitcnt lgkmcnt(0)
	v_add_f32_e32 v1, v5, v1
	v_cndmask_b32_e32 v1, v1, v5, vcc
	v_cmp_lt_i32_e32 vcc, v8, v7
	s_nop 1
	v_cndmask_b32_e32 v8, v8, v176, vcc
	v_lshlrev_b32_e32 v8, 2, v8
	ds_bpermute_b32 v8, v8, v1
	v_cmp_gt_u32_e32 vcc, 2, v169
	s_waitcnt lgkmcnt(0)
	v_add_f32_e32 v8, v1, v8
	v_cndmask_b32_e32 v1, v8, v1, vcc
	v_add_u32_e32 v8, -4, v176
	v_cmp_lt_i32_e32 vcc, v8, v7
	s_nop 1
	v_cndmask_b32_e32 v8, v8, v176, vcc
	v_lshlrev_b32_e32 v8, 2, v8
	ds_bpermute_b32 v8, v8, v1
	v_cmp_gt_u32_e32 vcc, 4, v169
	s_waitcnt lgkmcnt(0)
	v_add_f32_e32 v8, v1, v8
	v_cndmask_b32_e32 v1, v8, v1, vcc
	v_add_u32_e32 v8, -8, v176
	v_cmp_lt_i32_e32 vcc, v8, v7
	s_nop 1
	v_cndmask_b32_e32 v8, v8, v176, vcc
	v_lshlrev_b32_e32 v8, 2, v8
	ds_bpermute_b32 v8, v8, v1
	v_cmp_gt_u32_e32 vcc, 8, v169
	s_waitcnt lgkmcnt(0)
	v_add_f32_e32 v8, v1, v8
	v_cndmask_b32_e32 v1, v8, v1, vcc
	v_add_u32_e32 v8, -16, v176
	v_cmp_lt_i32_e32 vcc, v8, v7
	s_nop 1
	v_cndmask_b32_e32 v8, v8, v176, vcc
	v_lshlrev_b32_e32 v8, 2, v8
	ds_bpermute_b32 v8, v8, v1
	v_cmp_gt_u32_e32 vcc, 16, v169
	s_waitcnt lgkmcnt(0)
	v_add_f32_e32 v8, v1, v8
	v_cndmask_b32_e32 v1, v8, v1, vcc
	v_subrev_u32_e32 v8, 32, v176
	v_cmp_lt_i32_e32 vcc, v8, v7
	s_nop 1
	v_cndmask_b32_e32 v7, v8, v176, vcc
	v_lshlrev_b32_e32 v7, 2, v7
	ds_bpermute_b32 v7, v7, v1
	v_cmp_eq_u32_e32 vcc, 63, v169
	s_waitcnt lgkmcnt(0)
	v_add_f32_e32 v7, v1, v7
	s_and_saveexec_b64 s[2:3], vcc
	s_lshl_b32 s1, s5, 2
	s_add_i32 s1, s1, 0
	s_add_i32 s1, s1, 0x12840
	v_mov_b32_e32 v8, s1
	ds_write_b32 v8, v7
	s_or_b64 exec, exec, s[2:3]
	s_mul_hi_i32 s1, s0, 0x2aaaaaab
	s_lshr_b32 s2, s1, 31
	s_add_i32 s18, s1, s2
	s_lshl_b32 s2, s9, 8
	s_mul_i32 s1, s18, 6
	s_ashr_i32 s19, s18, 31
	s_sub_i32 s2, 0x700, s2
	s_sub_i32 s3, s0, s1
	s_lshl_b64 s[0:1], s[18:19], 11
	s_ashr_i32 s4, s2, 31
	s_add_u32 s96, s0, s2
	s_addc_u32 s97, s1, s4
	s_mul_i32 s0, s97, 0x3000
	s_mul_hi_u32 s1, s96, 0x3000
	s_add_i32 s1, s1, s0
	s_mul_i32 s0, s96, 0x3000
	v_readlane_b32 s20, v245, 14
	s_add_u32 s4, s20, s0
	v_readlane_b32 s21, v245, 15
	s_addc_u32 s19, s21, s1
	s_lshl_b32 s0, s3, 7
	s_ashr_i32 s1, s0, 31
	s_lshl_b64 s[34:35], s[0:1], 1
	s_add_u32 s0, s4, s34
	s_addc_u32 s1, s19, s35
	s_add_u32 s0, s0, 0x1e00
	s_addc_u32 s1, s1, 0
	s_mul_i32 s4, s18, 0x1800000
	s_mul_hi_i32 s3, s18, 0x1800000
	s_add_u32 s4, s20, s4
	s_addc_u32 s3, s21, s3
	s_add_u32 s4, s4, s34
	s_addc_u32 s3, s3, s35
	s_add_u32 s22, s4, 0x2400
	s_addc_u32 s23, s3, 0
	s_add_u32 s28, s4, 0x2a00
	s_addc_u32 s29, s3, 0
	v_lshlrev_b32_e32 v22, 3, v180
	v_cmp_gt_u32_e64 s[38:39], 32, v169
	s_add_i32 s3, 0, 0x12840
	v_and_b32_e32 v8, 0x78, v22
	v_cndmask_b32_e64 v1, v7, v1, s[38:39]
	v_mov_b32_e32 v7, s3
	v_lshlrev_b32_e32 v50, 1, v8
	s_waitcnt lgkmcnt(0)
	s_barrier
	ds_read_b128 v[8:11], v7
	s_ashr_i32 s3, s2, 8
	v_readlane_b32 s4, v243, 56
	s_cmp_gt_i32 s5, 0
	s_cselect_b64 vcc, -1, 0
	v_mov_b32_e32 v7, s4
	ds_read_b128 v[12:15], v7
	s_waitcnt lgkmcnt(1)
	v_add_f32_e32 v7, 0, v8
	s_cmp_gt_i32 s3, -1
	v_cndmask_b32_e32 v8, 0, v7, vcc
	s_cselect_b64 vcc, -1, 0
	s_cmp_gt_i32 s5, 1
	v_cndmask_b32_e32 v7, 0, v7, vcc
	v_add_f32_e32 v16, v9, v8
	s_cselect_b64 vcc, -1, 0
	s_cmp_lt_i32 s3, 1
	v_cndmask_b32_e32 v8, v8, v16, vcc
	v_add_f32_e32 v9, v9, v7
	s_cselect_b64 vcc, -1, 0
	s_cmp_gt_i32 s5, 2
	v_cndmask_b32_e32 v7, v9, v7, vcc
	v_add_f32_e32 v9, v10, v8
	s_cselect_b64 vcc, -1, 0
	s_cmp_lt_i32 s3, 2
	v_cndmask_b32_e32 v8, v8, v9, vcc
	v_add_f32_e32 v9, v10, v7
	s_cselect_b64 vcc, -1, 0
	s_cmp_gt_i32 s5, 3
	v_cndmask_b32_e32 v7, v9, v7, vcc
	v_add_f32_e32 v9, v11, v8
	s_cselect_b64 vcc, -1, 0
	s_cmp_lt_i32 s3, 3
	v_cndmask_b32_e32 v8, v8, v9, vcc
	v_add_f32_e32 v9, v11, v7
	s_cselect_b64 vcc, -1, 0
	s_cmp_gt_i32 s5, 4
	v_cndmask_b32_e32 v7, v9, v7, vcc
	s_waitcnt lgkmcnt(0)
	v_add_f32_e32 v9, v12, v8
	s_cselect_b64 vcc, -1, 0
	s_cmp_lt_i32 s3, 4
	v_cndmask_b32_e32 v8, v8, v9, vcc
	v_add_f32_e32 v9, v12, v7
	s_cselect_b64 vcc, -1, 0
	s_cmp_gt_i32 s5, 5
	v_cndmask_b32_e32 v7, v9, v7, vcc
	v_add_f32_e32 v9, v13, v8
	s_cselect_b64 vcc, -1, 0
	s_cmp_lt_i32 s3, 5
	v_cndmask_b32_e32 v8, v8, v9, vcc
	v_add_f32_e32 v9, v13, v7
	s_cselect_b64 vcc, -1, 0
	s_cmp_gt_i32 s5, 6
	v_cndmask_b32_e32 v7, v9, v7, vcc
	v_add_f32_e32 v9, v14, v8
	s_cselect_b64 vcc, -1, 0
	s_cmp_lt_i32 s3, 6
	v_cndmask_b32_e32 v8, v8, v9, vcc
	v_add_f32_e32 v9, v14, v7
	s_cselect_b64 vcc, -1, 0
	s_cmp_gt_i32 s5, 7
	v_cndmask_b32_e32 v7, v9, v7, vcc
	v_add_f32_e32 v9, v15, v8
	s_cselect_b64 vcc, -1, 0
	s_cmp_lt_i32 s3, 7
	v_cndmask_b32_e32 v8, v8, v9, vcc
	v_add_f32_e32 v9, v15, v7
	s_cselect_b64 vcc, -1, 0
	v_sub_f32_e32 v1, v1, v5
	v_cndmask_b32_e32 v7, v9, v7, vcc
	v_add_f32_e32 v1, v1, v8
	v_sub_f32_e32 v8, v1, v7
	v_ashrrev_i32_e32 v192, 4, v180
	v_add_f32 v2, v2, v8
	v_add_f32 v3, v3, v8
	v_add_f32 v4, v4, v8
	v_add_f32 v5, v5, v8
	s_mov_b32 s4, 0x3fb8aa3b
	v_readlane_b32 s3, v243, 57
	v_add_u32_e32 v23, 32, v192
	v_mul_f32 v4, v4, s4
	v_mul_f32 v5, v5, s4
	v_mul_f32 v2, v2, s4
	v_mul_f32 v3, v3, s4
	v_lshl_add_u32 v1, v6, 2, s3
	v_mov_b64_e32 v[18:19], s[28:29]
	v_mov_b64_e32 v[20:21], s[22:23]
	ds_write_b128 v1, v[2:5]
	v_mad_i64_i32 v[2:3], s[18:19], v192, s33, v[18:19]
	v_mov_b32_e32 v51, v163
	v_mad_i64_i32 v[6:7], s[18:19], v192, s33, v[20:21]
	v_mad_i64_i32 v[8:9], s[18:19], v23, s33, v[20:21]
	v_lshl_add_u64 v[2:3], v[2:3], 0, v[50:51]
	v_lshl_add_u64 v[6:7], v[6:7], 0, v[50:51]
	v_lshl_add_u64 v[10:11], v[8:9], 0, v[50:51]
	s_waitcnt lgkmcnt(0)
	s_barrier
	global_load_dwordx4 v[2:5], v[2:3], off
	s_nop 0
	global_load_dwordx4 v[6:9], v[6:7], off
	s_nop 0
	global_load_dwordx4 v[10:13], v[10:11], off
	v_mad_i64_i32 v[14:15], s[18:19], v23, s33, v[18:19]
	v_lshl_add_u64 v[14:15], v[14:15], 0, v[50:51]
	global_load_dwordx4 v[14:17], v[14:15], off
	v_and_b32_e32 v1, 0xfffff0, v192
	v_lshlrev_b32_e32 v24, 1, v192
	v_and_or_b32 v1, v24, 8, v1
	v_lshrrev_b32_e32 v24, 1, v192
	v_and_b32_e32 v25, 3, v192
	v_and_or_b32 v24, v24, 4, v25
	v_and_b32_e32 v25, 0xfffff0, v23
	v_lshlrev_b32_e32 v23, 1, v23
	v_and_or_b32 v23, v23, 8, v25
	v_lshrrev_b32_e32 v1, 1, v1
	v_bfe_u32 v22, v22, 5, 2
	v_lshrrev_b32_e32 v23, 1, v23
	v_or_b32_e32 v1, v1, v22
	v_or_b32_e32 v22, v23, v22
	v_lshlrev_b32_e32 v23, 8, v192
	v_and_b32_e32 v25, 0x70, v180
	v_lshlrev_b32_e32 v1, 9, v1
	v_lshlrev_b32_e32 v24, 6, v24
	v_lshlrev_b32_e32 v22, 9, v22
	v_bitop3_b32 v25, v50, v23, v25 bitop3:0xde
	v_and_b32_e32 v182, 31, v180
	v_and_b32_e32 v23, 48, v50
	s_lshl_b32 s4, s5, 5
	v_lshrrev_b32_e32 v181, 5, v169
	v_or3_b32 v1, v1, v24, v23
	v_or3_b32 v24, v22, v24, v23
	v_or_b32_e32 v26, s4, v182
	v_mov_b64_e32 v[22:23], s[0:1]
	v_mad_i64_i32 v[22:23], s[0:1], v26, s33, v[22:23]
	v_lshlrev_b32_e32 v162, 4, v181
	v_lshl_add_u64 v[22:23], v[22:23], 0, v[162:163]
	global_load_dwordx4 v[142:145], v[22:23], off
	global_load_dwordx4 v[138:141], v[22:23], off offset:32
	global_load_dwordx4 v[134:137], v[22:23], off offset:64
	global_load_dwordx4 v[130:133], v[22:23], off offset:96
	global_load_dwordx4 v[126:129], v[22:23], off offset:128
	global_load_dwordx4 v[122:125], v[22:23], off offset:160
	global_load_dwordx4 v[118:121], v[22:23], off offset:192
	global_load_dwordx4 v[114:117], v[22:23], off offset:224
	v_add_u32_e32 v193, 0, v25
	v_add_u32_e32 v194, 0, v1
	v_add_u32_e32 v1, 64, v192
	s_waitcnt vmcnt(10)
	ds_write_b128 v193, v[6:9] offset:32768
	s_waitcnt vmcnt(9)
	ds_write_b128 v193, v[10:13] offset:40960
	ds_write_b128 v194, v[2:5]
	v_mad_i64_i32 v[2:3], s[0:1], v1, s33, v[18:19]
	v_add_u32_e32 v6, 0x60, v192
	v_add_u32_e32 v195, 0, v24
	v_lshl_add_u64 v[2:3], v[2:3], 0, v[50:51]
	v_mad_i64_i32 v[4:5], s[0:1], v6, s33, v[18:19]
	s_waitcnt vmcnt(8)
	ds_write_b128 v195, v[14:17]
	s_waitcnt lgkmcnt(0)
	s_barrier
	v_lshl_add_u64 v[4:5], v[4:5], 0, v[50:51]
	global_load_dwordx4 v[38:41], v[2:3], off
	global_load_dwordx4 v[34:37], v[4:5], off
	v_mad_i64_i32 v[2:3], s[0:1], v1, s33, v[20:21]
	v_lshl_add_u64 v[2:3], v[2:3], 0, v[50:51]
	v_mad_i64_i32 v[4:5], s[0:1], v6, s33, v[20:21]
	v_lshl_add_u64 v[4:5], v[4:5], 0, v[50:51]
	global_load_dwordx4 v[46:49], v[2:3], off
	global_load_dwordx4 v[42:45], v[4:5], off
	v_lshlrev_b32_e32 v186, 2, v181
	v_sub_u32_e32 v1, v182, v186
	v_lshlrev_b32_e32 v179, 4, v180
	s_movk_i32 s0, 0x70
	v_and_b32_e32 v2, 0x70, v179
	v_lshl_add_u32 v3, v182, 8, 0
	v_bitop3_b32 v4, v162, v179, s0 bitop3:0x78
	v_add_u32_e32 v191, v3, v4
	v_bitop3_b32 v4, v162, v2, 32 bitop3:0x36
	s_movk_i32 s0, 0x60
	v_add_u32_e32 v190, v3, v4
	v_bitop3_b32 v4, v162, v2, 64 bitop3:0x36
	v_bitop3_b32 v2, v162, v2, s0 bitop3:0x36
	v_add_u32_e32 v189, v3, v4
	v_add_u32_e32 v188, v3, v2
	ds_read_b128 v[2:5], v191 offset:32768
	ds_read_b128 v[6:9], v191 offset:40960
	s_waitcnt vmcnt(11) lgkmcnt(1)
	v_mfma_f32_32x32x16_bf16 v[18:33], v[2:5], v[142:145], 0
	ds_read_b128 v[52:55], v190 offset:32768
	ds_read_b128 v[56:59], v190 offset:40960
	v_add_u32_e32 v51, s3, v162
	s_add_i32 s27, s4, s2
	v_add_u32_e32 v187, s27, v1
	s_cmp_gt_i32 s27, 62
	s_waitcnt lgkmcnt(2)
	v_mfma_f32_32x32x16_bf16 v[2:17], v[6:9], v[142:145], 0
	s_waitcnt vmcnt(10) lgkmcnt(1)
	v_mfma_f32_32x32x16_bf16 v[18:33], v[52:55], v[138:141], v[18:33]
	s_waitcnt lgkmcnt(0)
	v_mfma_f32_32x32x16_bf16 v[2:17], v[56:59], v[138:141], v[2:17]
	ds_read_b128 v[52:55], v189 offset:32768
	ds_read_b128 v[56:59], v189 offset:40960
	s_waitcnt vmcnt(9) lgkmcnt(1)
	v_mfma_f32_32x32x16_bf16 v[18:33], v[52:55], v[134:137], v[18:33]
	s_waitcnt lgkmcnt(0)
	v_mfma_f32_32x32x16_bf16 v[2:17], v[56:59], v[134:137], v[2:17]
	ds_read_b128 v[52:55], v188 offset:32768
	ds_read_b128 v[56:59], v188 offset:40960
	s_waitcnt vmcnt(8) lgkmcnt(1)
	v_mfma_f32_32x32x16_bf16 v[18:33], v[52:55], v[130:133], v[18:33]
	s_waitcnt lgkmcnt(0)
	v_mfma_f32_32x32x16_bf16 v[2:17], v[56:59], v[130:133], v[2:17]
	ds_read_b128 v[52:55], v191 offset:32896
	ds_read_b128 v[56:59], v191 offset:41088
	s_waitcnt vmcnt(7) lgkmcnt(1)
	v_mfma_f32_32x32x16_bf16 v[18:33], v[52:55], v[126:129], v[18:33]
	s_waitcnt lgkmcnt(0)
	v_mfma_f32_32x32x16_bf16 v[2:17], v[56:59], v[126:129], v[2:17]
	ds_read_b128 v[52:55], v190 offset:32896
	ds_read_b128 v[56:59], v190 offset:41088
	s_waitcnt vmcnt(6) lgkmcnt(1)
	v_mfma_f32_32x32x16_bf16 v[18:33], v[52:55], v[122:125], v[18:33]
	s_waitcnt lgkmcnt(0)
	v_mfma_f32_32x32x16_bf16 v[2:17], v[56:59], v[122:125], v[2:17]
	ds_read_b128 v[52:55], v189 offset:32896
	ds_read_b128 v[56:59], v189 offset:41088
	s_waitcnt vmcnt(5) lgkmcnt(1)
	v_mfma_f32_32x32x16_bf16 v[18:33], v[52:55], v[118:121], v[18:33]
	s_waitcnt lgkmcnt(0)
	v_mfma_f32_32x32x16_bf16 v[2:17], v[56:59], v[118:121], v[2:17]
	ds_read_b128 v[52:55], v188 offset:32896
	ds_read_b128 v[56:59], v188 offset:41088
	s_waitcnt vmcnt(4) lgkmcnt(1)
	v_mfma_f32_32x32x16_bf16 v[18:33], v[52:55], v[114:117], v[18:33]
	v_add_u32_e32 v52, 0, v162
	v_add_u32_e32 v80, 0x10880, v52
	s_waitcnt lgkmcnt(0)
	v_mfma_f32_32x32x16_bf16 v[2:17], v[56:59], v[114:117], v[2:17]
	ds_read_b128 v[52:55], v51
	ds_read_b128 v[56:59], v51 offset:32
	ds_read_b128 v[60:63], v80
	ds_read_b128 v[64:67], v80 offset:32
	ds_read_b128 v[68:71], v51 offset:64
	ds_read_b128 v[72:75], v80 offset:64
	ds_read_b128 v[76:79], v51 offset:96
	ds_read_b128 v[80:83], v80 offset:96
	s_waitcnt lgkmcnt(7)
	v_xor_b32_e32 v55, 0x80000000, v55
	v_xor_b32_e32 v54, 0x80000000, v54
	s_waitcnt lgkmcnt(6)
	v_xor_b32_e32 v59, 0x80000000, v59
	v_xor_b32_e32 v58, 0x80000000, v58
	s_waitcnt lgkmcnt(3)
	v_xor_b32_e32 v71, 0x80000000, v71
	v_xor_b32_e32 v70, 0x80000000, v70
	s_waitcnt lgkmcnt(1)
	v_xor_b32_e32 v79, 0x80000000, v79
	v_xor_b32_e32 v78, 0x80000000, v78
	v_fma_f32 v24, v24, s12, v58
	v_fma_f32 v25, v25, s12, v59
	v_fma_f32 v22, v22, s12, -v56
	v_fma_f32 v23, v23, s12, -v57
	v_fma_f32 v20, v20, s12, v54
	v_fma_f32 v21, v21, s12, v55
	v_fma_f32 v18, v18, s12, -v52
	v_fma_f32 v19, v19, s12, -v53
	v_xor_b32_e32 v53, 0x80000000, v63
	v_xor_b32_e32 v52, 0x80000000, v62
	v_xor_b32_e32 v55, 0x80000000, v67
	v_xor_b32_e32 v54, 0x80000000, v66
	v_xor_b32_e32 v57, 0x80000000, v75
	v_xor_b32_e32 v56, 0x80000000, v74
	s_waitcnt lgkmcnt(0)
	v_xor_b32_e32 v59, 0x80000000, v83
	v_xor_b32_e32 v58, 0x80000000, v82
	v_fma_f32 v32, v32, s12, v78
	v_fma_f32 v33, v33, s12, v79
	v_fma_f32 v30, v30, s12, -v76
	v_fma_f32 v31, v31, s12, -v77
	v_fma_f32 v28, v28, s12, v70
	v_fma_f32 v29, v29, s12, v71
	v_fma_f32 v26, v26, s12, -v68
	v_fma_f32 v27, v27, s12, -v69
	v_fma_f32 v16, v16, s12, v58
	v_fma_f32 v17, v17, s12, v59
	v_fma_f32 v14, v14, s12, -v80
	v_fma_f32 v15, v15, s12, -v81
	v_fma_f32 v12, v12, s12, v56
	v_fma_f32 v13, v13, s12, v57
	v_fma_f32 v10, v10, s12, -v72
	v_fma_f32 v11, v11, s12, -v73
	v_fma_f32 v8, v8, s12, v54
	v_fma_f32 v9, v9, s12, v55
	v_fma_f32 v6, v6, s12, -v64
	v_fma_f32 v7, v7, s12, -v65
	v_fma_f32 v4, v4, s12, v52
	v_fma_f32 v5, v5, s12, v53
	v_fma_f32 v2, v2, s12, -v60
	v_fma_f32 v3, v3, s12, -v61
	s_cbranch_scc1 .LBB0_643
	v_cmp_gt_i32_e64 s[92:93], 26, v187
	v_cmp_gt_i32_e64 s[94:95], 27, v187
	v_cmp_gt_i32_e64 s[90:91], 25, v187
	s_and_b64 s[92:93], s[94:95], s[92:93]
	v_cmp_gt_i32_e64 s[88:89], 24, v187
	s_and_b64 s[90:91], s[92:93], s[90:91]
	v_cmp_gt_i32_e64 s[86:87], 19, v187
	s_and_b64 s[88:89], s[90:91], s[88:89]
	v_cmp_gt_i32_e64 s[84:85], 18, v187
	s_and_b64 s[86:87], s[88:89], s[86:87]
	v_cmp_gt_i32_e64 s[82:83], 17, v187
	s_and_b64 s[84:85], s[86:87], s[84:85]
	v_cmp_gt_i32_e64 s[80:81], 16, v187
	s_and_b64 s[82:83], s[84:85], s[82:83]
	v_cmp_gt_i32_e64 s[78:79], 11, v187
	s_and_b64 s[80:81], s[82:83], s[80:81]
	v_cmp_gt_i32_e64 s[76:77], 10, v187
	s_and_b64 s[78:79], s[80:81], s[78:79]
	v_cmp_gt_i32_e64 s[74:75], 9, v187
	s_and_b64 s[76:77], s[78:79], s[76:77]
	v_cmp_gt_i32_e64 s[72:73], 8, v187
	s_and_b64 s[74:75], s[76:77], s[74:75]
	v_cmp_gt_i32_e64 s[70:71], 3, v187
	s_and_b64 s[72:73], s[74:75], s[72:73]
	v_cmp_gt_i32_e64 s[68:69], 2, v187
	s_and_b64 s[70:71], s[72:73], s[70:71]
	v_cmp_gt_i32_e64 s[2:3], 1, v187
	s_and_b64 s[68:69], s[70:71], s[68:69]
	v_cmp_gt_i32_e64 s[0:1], 0, v187
	s_and_b64 s[2:3], s[68:69], s[2:3]
	s_and_b64 s[0:1], s[2:3], s[0:1]
	v_cmp_gt_i32_e64 s[66:67], 58, v187
	v_cndmask_b32_e64 v18, v18, v175, s[0:1]
	v_cmp_gt_i32_e64 s[0:1], 59, v187
	v_cmp_gt_i32_e64 s[64:65], 57, v187
	v_cmp_gt_i32_e64 s[62:63], 56, v187
	v_cndmask_b32_e64 v17, v17, v175, s[0:1]
	s_and_b64 s[0:1], s[0:1], s[66:67]
	v_cndmask_b32_e64 v16, v16, v175, s[0:1]
	s_and_b64 s[0:1], s[0:1], s[64:65]
	v_cmp_gt_i32_e64 s[60:61], 51, v187
	v_cndmask_b32_e64 v15, v15, v175, s[0:1]
	s_and_b64 s[0:1], s[0:1], s[62:63]
	v_cmp_gt_i32_e64 s[58:59], 50, v187
	v_cndmask_b32_e64 v14, v14, v175, s[0:1]
	s_and_b64 s[0:1], s[0:1], s[60:61]
	v_cmp_gt_i32_e64 s[56:57], 49, v187
	v_cndmask_b32_e64 v13, v13, v175, s[0:1]
	s_and_b64 s[0:1], s[0:1], s[58:59]
	v_cmp_gt_i32_e64 s[54:55], 48, v187
	v_cndmask_b32_e64 v12, v12, v175, s[0:1]
	s_and_b64 s[0:1], s[0:1], s[56:57]
	v_cmp_gt_i32_e64 s[52:53], 43, v187
	v_cndmask_b32_e64 v11, v11, v175, s[0:1]
	s_and_b64 s[0:1], s[0:1], s[54:55]
	v_cmp_gt_i32_e64 s[50:51], 42, v187
	v_cndmask_b32_e64 v10, v10, v175, s[0:1]
	s_and_b64 s[0:1], s[0:1], s[52:53]
	v_cmp_gt_i32_e64 s[48:49], 41, v187
	v_cndmask_b32_e64 v9, v9, v175, s[0:1]
	s_and_b64 s[0:1], s[0:1], s[50:51]
	v_cmp_gt_i32_e64 s[46:47], 40, v187
	v_cndmask_b32_e64 v8, v8, v175, s[0:1]
	s_and_b64 s[0:1], s[0:1], s[48:49]
	v_cmp_gt_i32_e64 s[44:45], 35, v187
	v_cndmask_b32_e64 v7, v7, v175, s[0:1]
	s_and_b64 s[0:1], s[0:1], s[46:47]
	v_cmp_gt_i32_e64 s[42:43], 34, v187
	v_cndmask_b32_e64 v6, v6, v175, s[0:1]
	s_and_b64 s[0:1], s[0:1], s[44:45]
	v_cmp_gt_i32_e64 s[40:41], 33, v187
	v_cndmask_b32_e64 v5, v5, v175, s[0:1]
	s_and_b64 s[0:1], s[0:1], s[42:43]
	v_cmp_gt_i32_e32 vcc, 32, v187
	v_cndmask_b32_e64 v4, v4, v175, s[0:1]
	s_and_b64 s[0:1], s[0:1], s[40:41]
	v_cndmask_b32_e64 v30, v30, v175, s[88:89]
	v_readlane_b32 s88, v242, 2
	s_and_b64 vcc, s[0:1], vcc
	v_cndmask_b32_e64 v33, v33, v175, s[94:95]
	v_cndmask_b32_e64 v32, v32, v175, s[92:93]
	s_movk_i32 s93, 0x6018
	s_mov_b32 s92, 0xf800000
	v_cndmask_b32_e64 v31, v31, v175, s[90:91]
	s_mov_b64 s[90:91], s[16:17]
	v_readlane_b32 s89, v242, 3
	v_cndmask_b32_e64 v29, v29, v175, s[86:87]
	v_readlane_b32 s86, v242, 0
	v_cndmask_b32_e64 v28, v28, v175, s[84:85]
	v_cndmask_b32_e64 v27, v27, v175, s[82:83]
	s_movk_i32 s83, 0x6000
	v_cndmask_b32_e64 v26, v26, v175, s[80:81]
	v_cndmask_b32_e64 v25, v25, v175, s[78:79]
	v_cndmask_b32_e64 v24, v24, v175, s[76:77]
	v_cndmask_b32_e64 v23, v23, v175, s[74:75]
	v_cndmask_b32_e64 v22, v22, v175, s[72:73]
	v_cndmask_b32_e64 v21, v21, v175, s[70:71]
	v_cndmask_b32_e64 v20, v20, v175, s[68:69]
	v_cndmask_b32_e64 v19, v19, v175, s[2:3]
	s_mov_b32 s56, s30
	v_cndmask_b32_e64 v3, v3, v175, s[0:1]
	v_cndmask_b32_e32 v2, v2, v175, vcc
	v_readlane_b32 s87, v242, 1

.LBB0_645:
	v_add_u32_e32 v218, s11, v192
	v_add_u32_e32 v81, 1, v218
	v_mad_i64_i32 v[82:83], s[0:1], v81, s33, v[164:165]
	v_add_u32_e32 v86, 33, v218
	v_mad_i64_i32 v[84:85], s[0:1], v86, s33, v[164:165]
	global_load_dwordx4 v[146:149], v[82:83], off
	global_load_dwordx4 v[150:153], v[84:85], off
	v_mad_i64_i32 v[82:83], s[0:1], v81, s33, v[166:167]
	v_mad_i64_i32 v[84:85], s[0:1], v86, s33, v[166:167]
	global_load_dwordx4 v[154:157], v[82:83], off
	global_load_dwordx4 v[158:161], v[84:85], off
	ds_read_b128 v[228:231], v191 offset:49152
	ds_read_b128 v[232:235], v190 offset:49152
	ds_read_b128 v[236:239], v191 offset:57344
	ds_read_b128 v[248:251], v190 offset:57344
	ds_read_b128 v[252:255], v189 offset:49152
	s_waitcnt lgkmcnt(4)
	v_mfma_f32_32x32x16_bf16 v[98:113], v[228:231], v[142:145], 0
	ds_read_b128 v[228:231], v189 offset:57344
	s_waitcnt lgkmcnt(4)
	v_mfma_f32_32x32x16_bf16 v[98:113], v[232:235], v[138:141], v[98:113]
	ds_read_b128 v[232:235], v188 offset:49152
	s_waitcnt lgkmcnt(4)
	v_mfma_f32_32x32x16_bf16 v[82:97], v[236:239], v[142:145], 0
	ds_read_b128 v[236:239], v188 offset:57344
	s_waitcnt lgkmcnt(4)
	v_mfma_f32_32x32x16_bf16 v[82:97], v[248:251], v[138:141], v[82:97]
	ds_read_b128 v[248:251], v191 offset:49280
	s_waitcnt lgkmcnt(4)
	v_mfma_f32_32x32x16_bf16 v[98:113], v[252:255], v[134:137], v[98:113]
	ds_read_b128 v[252:255], v191 offset:57472
	s_waitcnt lgkmcnt(4)
	v_mfma_f32_32x32x16_bf16 v[82:97], v[228:231], v[134:137], v[82:97]
	ds_read_b128 v[228:231], v190 offset:49280
	s_waitcnt lgkmcnt(4)
	v_mfma_f32_32x32x16_bf16 v[98:113], v[232:235], v[130:133], v[98:113]
	ds_read_b128 v[232:235], v190 offset:57472
	s_waitcnt lgkmcnt(4)
	v_mfma_f32_32x32x16_bf16 v[82:97], v[236:239], v[130:133], v[82:97]
	ds_read_b128 v[236:239], v189 offset:49280
	s_waitcnt lgkmcnt(4)
	v_mfma_f32_32x32x16_bf16 v[98:113], v[248:251], v[126:129], v[98:113]
	ds_read_b128 v[248:251], v189 offset:57472
	s_waitcnt lgkmcnt(4)
	v_mfma_f32_32x32x16_bf16 v[82:97], v[252:255], v[126:129], v[82:97]
	ds_read_b128 v[252:255], v188 offset:49280
	s_waitcnt lgkmcnt(4)
	v_mfma_f32_32x32x16_bf16 v[98:113], v[228:231], v[122:125], v[98:113]
	ds_read_b128 v[228:231], v188 offset:57472
	s_waitcnt lgkmcnt(4)
	v_mfma_f32_32x32x16_bf16 v[82:97], v[232:235], v[122:125], v[82:97]
	s_waitcnt lgkmcnt(3)
	v_mfma_f32_32x32x16_bf16 v[98:113], v[236:239], v[118:121], v[98:113]
	s_waitcnt lgkmcnt(2)
	v_mfma_f32_32x32x16_bf16 v[82:97], v[248:251], v[118:121], v[82:97]
	s_waitcnt lgkmcnt(1)
	v_mfma_f32_32x32x16_bf16 v[98:113], v[252:255], v[114:117], v[98:113]
	s_waitcnt lgkmcnt(0)
	v_mfma_f32_32x32x16_bf16 v[82:97], v[228:231], v[114:117], v[82:97]
	v_exp_f32_e32 v226, v66
	v_add_f32_e32 v66, 0, v215
	v_add_f32_e32 v66, v217, v66
	v_add_f32_e32 v66, v213, v66
	v_add_f32_e32 v66, v216, v66
	v_add_f32_e32 v66, v211, v66
	v_add_f32_e32 v66, v214, v66
	v_add_f32_e32 v66, v210, v66
	v_add_f32_e32 v66, v212, v66
	v_add_f32_e32 v66, v207, v66
	v_add_f32_e32 v66, v209, v66
	v_add_f32_e32 v66, v205, v66
	v_add_f32_e32 v66, v208, v66
	v_exp_f32_e32 v80, v80
	v_add_f32_e32 v66, v203, v66
	v_exp_f32_e32 v1, v1
	v_add_f32_e32 v66, v206, v66
	v_exp_f32_e32 v78, v78
	v_add_f32_e32 v66, v202, v66
	v_exp_f32_e32 v79, v79
	v_add_f32_e32 v66, v204, v66
	v_exp_f32_e32 v76, v76
	v_add_f32_e32 v66, v80, v66
	v_exp_f32_e32 v77, v77
	v_add_f32_e32 v66, v1, v66
	v_exp_f32_e32 v81, v74
	v_add_f32_e32 v66, v78, v66
	v_exp_f32_e32 v219, v75
	v_add_f32_e32 v66, v79, v66
	v_exp_f32_e32 v220, v72
	v_add_f32_e32 v66, v76, v66
	v_exp_f32_e32 v221, v73
	v_add_f32_e32 v66, v77, v66
	v_exp_f32_e32 v222, v70
	v_add_f32_e32 v66, v81, v66
	v_exp_f32_e32 v223, v71
	v_add_f32_e32 v66, v219, v66
	v_exp_f32_e32 v224, v68
	v_add_f32_e32 v66, v220, v66
	v_exp_f32_e32 v225, v69
	v_add_f32_e32 v66, v221, v66
	v_add_f32_e32 v66, v222, v66
	v_exp_f32_e32 v227, v67
	v_add_f32_e32 v66, v223, v66
	v_add_f32_e32 v66, v224, v66
	v_add_f32_e32 v66, v225, v66
	v_add_f32_e32 v66, v226, v66
	v_add_f32_e32 v200, v227, v66
	v_mov_b32_e32 v201, v200
	v_cvt_pk_bf16_f32 v66, v215, v217
	v_cvt_pk_bf16_f32 v67, v213, v216
	v_cvt_pk_bf16_f32 v68, v211, v214
	v_cvt_pk_bf16_f32 v69, v210, v212
	v_cvt_pk_bf16_f32 v70, v207, v209
	v_cvt_pk_bf16_f32 v71, v205, v208
	v_cvt_pk_bf16_f32 v72, v203, v206
	v_cvt_pk_bf16_f32 v73, v202, v204
	v_cvt_pk_bf16_f32 v74, v80, v1
	v_cvt_pk_bf16_f32 v75, v78, v79
	v_cvt_pk_bf16_f32 v76, v76, v77
	v_cvt_pk_bf16_f32 v77, v81, v219
	v_cvt_pk_bf16_f32 v78, v220, v221
	v_cvt_pk_bf16_f32 v79, v222, v223
	v_cvt_pk_bf16_f32 v80, v224, v225
	v_cvt_pk_bf16_f32 v81, v226, v227
	s_nop 1
	v_permlane32_swap_b32_e32 v200, v201
	v_permlane32_swap_b32_e32 v66, v68
	v_permlane32_swap_b32_e32 v67, v69
	v_permlane32_swap_b32_e32 v70, v72
	v_permlane32_swap_b32_e32 v71, v73
	v_permlane32_swap_b32_e32 v74, v76
	v_permlane32_swap_b32_e32 v75, v77
	v_permlane32_swap_b32_e32 v78, v80
	v_permlane32_swap_b32_e32 v79, v81
	ds_read_b64_tr_b16 v[202:203], v183 offset:0
	ds_read_b64_tr_b16 v[204:205], v183 offset:0x800
	ds_read_b64_tr_b16 v[206:207], v183 offset:0x1000
	ds_read_b64_tr_b16 v[208:209], v183 offset:0x1800
	ds_read_b64_tr_b16 v[210:211], v183 offset:0x2000
	ds_read_b64_tr_b16 v[212:213], v183 offset:0x2800
	ds_read_b64_tr_b16 v[214:215], v183 offset:0x3000
	ds_read_b64_tr_b16 v[216:217], v183 offset:0x3800
	s_nop 0
	s_waitcnt lgkmcnt(6)
	v_mfma_f32_32x32x16_bf16 v[50:65], v[66:69], v[202:205], v[50:65]
	ds_read_b64_tr_b16 v[202:203], v183 offset:0x200
	ds_read_b64_tr_b16 v[204:205], v183 offset:0xa00
	s_waitcnt lgkmcnt(6)
	v_mfma_f32_32x32x16_bf16 v[50:65], v[70:73], v[206:209], v[50:65]
	ds_read_b64_tr_b16 v[206:207], v183 offset:0x1200
	ds_read_b64_tr_b16 v[208:209], v183 offset:0x1a00
	s_waitcnt lgkmcnt(6)
	v_mfma_f32_32x32x16_bf16 v[50:65], v[74:77], v[210:213], v[50:65]
	ds_read_b64_tr_b16 v[210:211], v183 offset:0x2200
	ds_read_b64_tr_b16 v[212:213], v183 offset:0x2a00
	s_waitcnt lgkmcnt(6)
	v_mfma_f32_32x32x16_bf16 v[50:65], v[78:81], v[214:217], v[50:65]
	ds_read_b64_tr_b16 v[214:215], v183 offset:0x3200
	ds_read_b64_tr_b16 v[216:217], v183 offset:0x3a00
	s_waitcnt lgkmcnt(6)
	v_mfma_f32_32x32x16_bf16 v[34:49], v[66:69], v[202:205], v[34:49]
	ds_read_b64_tr_b16 v[202:203], v183 offset:0x400
	ds_read_b64_tr_b16 v[204:205], v183 offset:0xc00
	s_waitcnt lgkmcnt(6)
	v_mfma_f32_32x32x16_bf16 v[34:49], v[70:73], v[206:209], v[34:49]
	ds_read_b64_tr_b16 v[206:207], v183 offset:0x1400
	ds_read_b64_tr_b16 v[208:209], v183 offset:0x1c00
	s_waitcnt lgkmcnt(6)
	v_mfma_f32_32x32x16_bf16 v[34:49], v[74:77], v[210:213], v[34:49]
	ds_read_b64_tr_b16 v[210:211], v183 offset:0x2400
	ds_read_b64_tr_b16 v[212:213], v183 offset:0x2c00
	s_waitcnt lgkmcnt(6)
	v_mfma_f32_32x32x16_bf16 v[34:49], v[78:81], v[214:217], v[34:49]
	ds_read_b64_tr_b16 v[214:215], v183 offset:0x3400
	ds_read_b64_tr_b16 v[216:217], v183 offset:0x3c00
	s_waitcnt lgkmcnt(6)
	v_mfma_f32_32x32x16_bf16 v[18:33], v[66:69], v[202:205], v[18:33]
	ds_read_b64_tr_b16 v[202:203], v183 offset:0x600
	ds_read_b64_tr_b16 v[204:205], v183 offset:0xe00
	s_waitcnt lgkmcnt(6)
	v_mfma_f32_32x32x16_bf16 v[18:33], v[70:73], v[206:209], v[18:33]
	ds_read_b64_tr_b16 v[206:207], v183 offset:0x1600
	ds_read_b64_tr_b16 v[208:209], v183 offset:0x1e00
	s_waitcnt lgkmcnt(6)
	v_mfma_f32_32x32x16_bf16 v[18:33], v[74:77], v[210:213], v[18:33]
	ds_read_b64_tr_b16 v[210:211], v183 offset:0x2600
	ds_read_b64_tr_b16 v[212:213], v183 offset:0x2e00
	s_waitcnt lgkmcnt(6)
	v_mfma_f32_32x32x16_bf16 v[18:33], v[78:81], v[214:217], v[18:33]
	ds_read_b64_tr_b16 v[214:215], v183 offset:0x3600
	ds_read_b64_tr_b16 v[216:217], v183 offset:0x3e00
	s_waitcnt lgkmcnt(6)
	v_mfma_f32_32x32x16_bf16 v[2:17], v[66:69], v[202:205], v[2:17]
	s_waitcnt lgkmcnt(4)
	v_mfma_f32_32x32x16_bf16 v[2:17], v[70:73], v[206:209], v[2:17]
	s_waitcnt lgkmcnt(2)
	v_mfma_f32_32x32x16_bf16 v[2:17], v[74:77], v[210:213], v[2:17]
	s_waitcnt lgkmcnt(0)
	v_mfma_f32_32x32x16_bf16 v[2:17], v[78:81], v[214:217], v[2:17]
	ds_read_b128 v[66:69], v198
	ds_read_b128 v[70:73], v198 offset:32
	ds_read_b128 v[202:205], v198 offset:128
	ds_read_b128 v[206:209], v198 offset:160
	ds_read_b128 v[76:79], v198 offset:64
	ds_read_b128 v[210:213], v198 offset:96
	ds_read_b128 v[214:217], v198 offset:192
	ds_read_b128 v[220:223], v198 offset:224
	s_waitcnt lgkmcnt(7)
	v_xor_b32_e32 v69, 0x80000000, v69
	s_waitcnt lgkmcnt(3)
	v_xor_b32_e32 v225, 0x80000000, v79
	v_xor_b32_e32 v224, 0x80000000, v78
	v_xor_b32_e32 v68, 0x80000000, v68
	v_xor_b32_e32 v73, 0x80000000, v73
	v_xor_b32_e32 v72, 0x80000000, v72
	s_waitcnt lgkmcnt(2)
	v_xor_b32_e32 v81, 0x80000000, v213
	v_xor_b32_e32 v80, 0x80000000, v212
	v_fma_f32 v74, v110, s12, -v210
	v_fma_f32 v75, v111, s12, -v211
	v_fma_f32 v78, v106, s12, -v76
	v_fma_f32 v79, v107, s12, -v77
	v_fma_f32 v102, v102, s12, -v70
	v_fma_f32 v103, v103, s12, -v71
	v_fma_f32 v106, v108, s12, v224
	v_fma_f32 v107, v109, s12, v225
	v_xor_b32_e32 v109, 0x80000000, v205
	v_xor_b32_e32 v108, 0x80000000, v204
	v_xor_b32_e32 v111, 0x80000000, v209
	v_xor_b32_e32 v110, 0x80000000, v208
	s_waitcnt lgkmcnt(1)
	v_xor_b32_e32 v77, 0x80000000, v217
	v_xor_b32_e32 v76, 0x80000000, v216
	s_waitcnt lgkmcnt(0)
	v_xor_b32_e32 v71, 0x80000000, v223
	v_xor_b32_e32 v70, 0x80000000, v222
	v_fma_f32 v80, v112, s12, v80
	v_fma_f32 v81, v113, s12, v81
	v_fma_f32 v104, v104, s12, v72
	v_fma_f32 v105, v105, s12, v73
	v_fma_f32 v100, v100, s12, v68
	v_fma_f32 v101, v101, s12, v69
	v_fma_f32 v98, v98, s12, -v66
	v_fma_f32 v99, v99, s12, -v67
	v_fma_f32 v66, v94, s12, -v220
	v_fma_f32 v67, v95, s12, -v221
	v_fma_f32 v68, v90, s12, -v214
	v_fma_f32 v69, v91, s12, -v215
	v_fma_f32 v72, v86, s12, -v206
	v_fma_f32 v73, v87, s12, -v207
	v_fma_f32 v70, v96, s12, v70
	v_fma_f32 v71, v97, s12, v71
	v_fma_f32 v76, v92, s12, v76
	v_fma_f32 v77, v93, s12, v77
	v_fma_f32 v86, v88, s12, v110
	v_fma_f32 v87, v89, s12, v111
	v_fma_f32 v84, v84, s12, v108
	v_fma_f32 v85, v85, s12, v109
	s_cmp_le_i32 s11, s27
	v_fma_f32 v82, v82, s12, -v202
	v_fma_f32 v83, v83, s12, -v203
	s_cbranch_scc1 .LBB0_647
	v_add_u32_e32 v1, 64, v199
	v_cmp_gt_i32_e64 s[92:93], 26, v1
	v_cmp_gt_i32_e64 s[94:95], 27, v1
	v_cmp_gt_i32_e64 s[90:91], 25, v1
	s_and_b64 s[92:93], s[94:95], s[92:93]
	v_cmp_gt_i32_e64 s[88:89], 24, v1
	s_and_b64 s[90:91], s[92:93], s[90:91]
	v_cmp_gt_i32_e64 s[86:87], 19, v1
	s_and_b64 s[88:89], s[90:91], s[88:89]
	v_cmp_gt_i32_e64 s[84:85], 18, v1
	s_and_b64 s[86:87], s[88:89], s[86:87]
	v_cmp_gt_i32_e64 s[82:83], 17, v1
	s_and_b64 s[84:85], s[86:87], s[84:85]
	v_cmp_gt_i32_e64 s[80:81], 16, v1
	s_and_b64 s[82:83], s[84:85], s[82:83]
	v_cmp_gt_i32_e64 s[78:79], 11, v1
	s_and_b64 s[80:81], s[82:83], s[80:81]
	v_cmp_gt_i32_e64 s[76:77], 10, v1
	s_and_b64 s[78:79], s[80:81], s[78:79]
	v_cmp_gt_i32_e64 s[74:75], 9, v1
	s_and_b64 s[76:77], s[78:79], s[76:77]
	v_cmp_gt_i32_e64 s[72:73], 8, v1
	s_and_b64 s[74:75], s[76:77], s[74:75]
	v_cmp_gt_i32_e64 s[70:71], 3, v1
	s_and_b64 s[72:73], s[74:75], s[72:73]
	v_cmp_gt_i32_e64 s[68:69], 2, v1
	s_and_b64 s[70:71], s[72:73], s[70:71]
	v_cmp_gt_i32_e64 s[2:3], 1, v1
	s_and_b64 s[68:69], s[70:71], s[68:69]
	v_cmp_gt_i32_e64 s[0:1], 0, v1
	s_and_b64 s[2:3], s[68:69], s[2:3]
	s_and_b64 s[0:1], s[2:3], s[0:1]
	v_cmp_gt_i32_e64 s[66:67], 58, v1
	v_cndmask_b32_e64 v98, v98, v175, s[0:1]
	v_cmp_gt_i32_e64 s[0:1], 59, v1
	v_cmp_gt_i32_e64 s[64:65], 57, v1
	v_cmp_gt_i32_e64 s[62:63], 56, v1
	v_cndmask_b32_e64 v71, v71, v175, s[0:1]
	s_and_b64 s[0:1], s[0:1], s[66:67]
	v_cndmask_b32_e64 v70, v70, v175, s[0:1]
	s_and_b64 s[0:1], s[0:1], s[64:65]
	v_cmp_gt_i32_e64 s[60:61], 51, v1
	v_cndmask_b32_e64 v67, v67, v175, s[0:1]
	s_and_b64 s[0:1], s[0:1], s[62:63]
	v_cmp_gt_i32_e64 s[58:59], 50, v1
	v_cndmask_b32_e64 v66, v66, v175, s[0:1]
	s_and_b64 s[0:1], s[0:1], s[60:61]
	v_cmp_gt_i32_e64 s[56:57], 49, v1
	v_cndmask_b32_e64 v77, v77, v175, s[0:1]
	s_and_b64 s[0:1], s[0:1], s[58:59]
	v_cmp_gt_i32_e64 s[54:55], 48, v1
	v_cndmask_b32_e64 v76, v76, v175, s[0:1]
	s_and_b64 s[0:1], s[0:1], s[56:57]
	v_cmp_gt_i32_e64 s[52:53], 43, v1
	v_cndmask_b32_e64 v69, v69, v175, s[0:1]
	s_and_b64 s[0:1], s[0:1], s[54:55]
	v_cmp_gt_i32_e64 s[50:51], 42, v1
	v_cndmask_b32_e64 v68, v68, v175, s[0:1]
	s_and_b64 s[0:1], s[0:1], s[52:53]
	v_cmp_gt_i32_e64 s[48:49], 41, v1
	v_cndmask_b32_e64 v87, v87, v175, s[0:1]
	s_and_b64 s[0:1], s[0:1], s[50:51]
	v_cmp_gt_i32_e64 s[46:47], 40, v1
	v_cndmask_b32_e64 v86, v86, v175, s[0:1]
	s_and_b64 s[0:1], s[0:1], s[48:49]
	v_cmp_gt_i32_e64 s[44:45], 35, v1
	v_cndmask_b32_e64 v73, v73, v175, s[0:1]
	s_and_b64 s[0:1], s[0:1], s[46:47]
	v_cmp_gt_i32_e64 s[42:43], 34, v1
	v_cndmask_b32_e64 v72, v72, v175, s[0:1]
	s_and_b64 s[0:1], s[0:1], s[44:45]
	v_cmp_gt_i32_e64 s[40:41], 33, v1
	v_cndmask_b32_e64 v85, v85, v175, s[0:1]
	s_and_b64 s[0:1], s[0:1], s[42:43]
	v_cmp_gt_i32_e32 vcc, 32, v1
	v_cndmask_b32_e64 v84, v84, v175, s[0:1]
	s_and_b64 s[0:1], s[0:1], s[40:41]
	v_cndmask_b32_e64 v74, v74, v175, s[88:89]
	v_readlane_b32 s88, v242, 2
	s_and_b64 vcc, s[0:1], vcc
	v_cndmask_b32_e64 v81, v81, v175, s[94:95]
	v_cndmask_b32_e64 v80, v80, v175, s[92:93]
	s_movk_i32 s93, 0x6018
	s_mov_b32 s92, 0xf800000
	v_cndmask_b32_e64 v75, v75, v175, s[90:91]
	s_mov_b64 s[90:91], s[16:17]
	v_readlane_b32 s89, v242, 3
	v_cndmask_b32_e64 v107, v107, v175, s[86:87]
	v_readlane_b32 s86, v242, 0
	v_cndmask_b32_e64 v106, v106, v175, s[84:85]
	v_cndmask_b32_e64 v79, v79, v175, s[82:83]
	s_movk_i32 s83, 0x6000
	v_cndmask_b32_e64 v78, v78, v175, s[80:81]
	v_cndmask_b32_e64 v105, v105, v175, s[78:79]
	v_cndmask_b32_e64 v104, v104, v175, s[76:77]
	v_cndmask_b32_e64 v103, v103, v175, s[74:75]
	v_cndmask_b32_e64 v102, v102, v175, s[72:73]
	v_cndmask_b32_e64 v101, v101, v175, s[70:71]
	v_cndmask_b32_e64 v100, v100, v175, s[68:69]
	v_cndmask_b32_e64 v99, v99, v175, s[2:3]
	s_mov_b32 s56, s30
	v_cndmask_b32_e64 v83, v83, v175, s[0:1]
	v_cndmask_b32_e32 v82, v82, v175, vcc
	v_readlane_b32 s87, v242, 1
.LBB0_647:
	v_max_f32_e32 v1, v99, v99
	v_max_f32_e32 v88, v98, v98
	v_max_f32_e32 v1, v88, v1
	v_max3_f32 v1, v1, v100, v101
	v_max3_f32 v1, v1, v102, v103
	v_max3_f32 v1, v1, v104, v105
	v_max3_f32 v1, v1, v78, v79
	v_max3_f32 v1, v1, v106, v107
	v_max3_f32 v1, v1, v74, v75
	v_max3_f32 v1, v1, v80, v81
	v_max3_f32 v1, v1, v82, v83
	v_max3_f32 v1, v1, v84, v85
	v_max3_f32 v1, v1, v72, v73
	v_max3_f32 v1, v1, v86, v87
	v_max3_f32 v1, v1, v68, v69
	v_max3_f32 v1, v1, v76, v77
	v_max3_f32 v1, v1, v66, v67
	v_max3_f32 v1, v1, v70, v71
	v_mov_b32_e32 v88, v1
	s_nop 1
	v_permlane32_swap_b32_e32 v1, v88
	v_max_f32_e32 v88, v88, v88
	v_max_f32_e32 v1, v1, v1
	v_max_f32_e32 v1, v1, v88
	v_sub_f32_e32 v88, v1, v196
	v_cmp_ge_f32_e32 vcc, s24, v88
	v_max_f32_e32 v88, v196, v196
	v_max_f32_e32 v1, v88, v1
	v_sub_f32_e32 v88, v196, v1
	v_exp_f32_e32 v88, v88
	s_cmp_eq_u64 vcc, exec
	s_cselect_b64 s[40:41], -1, 0
	v_cndmask_b32_e64 v108, v88, 1.0, s[40:41]
	v_cmp_gt_f32_e32 vcc, 1.0, v108
	s_barrier
	s_waitcnt vmcnt(1)
	ds_write_b128 v193, v[154:157] offset:32768
	s_waitcnt vmcnt(0)
	ds_write_b128 v193, v[158:161] offset:40960
	ds_write_b128 v194, v[146:149]
	ds_write_b128 v195, v[150:153]
	s_cbranch_vccz .LBB0_651
	s_and_saveexec_b64 s[0:1], s[38:39]
	ds_write_b32 v185, v108 offset:128
	s_or_b64 exec, exec, s[0:1]
	s_waitcnt lgkmcnt(0)
	ds_read_b128 v[88:91], v184 offset:224
	ds_read_b128 v[92:95], v184 offset:192
	ds_read_b128 v[110:113], v184 offset:160
	ds_read_b128 v[202:205], v184 offset:128
	s_waitcnt lgkmcnt(3)
	v_mul_f32 v64, v64, v90
	v_mul_f32 v65, v65, v91
	s_waitcnt lgkmcnt(2)
	v_mul_f32 v60, v60, v94
	v_mul_f32 v61, v61, v95
	s_waitcnt lgkmcnt(1)
	v_mul_f32 v56, v56, v112
	v_mul_f32 v57, v57, v113
	s_waitcnt lgkmcnt(0)
	v_mul_f32 v52, v52, v204
	v_mul_f32 v53, v53, v205
	v_mul_f32 v62, v62, v88
	v_mul_f32 v63, v63, v89
	v_mul_f32 v58, v58, v92
	v_mul_f32 v59, v59, v93
	v_mul_f32 v54, v54, v110
	v_mul_f32 v55, v55, v111
	v_mul_f32 v50, v50, v202
	v_mul_f32 v51, v51, v203
	v_mul_f32 v48, v48, v90
	v_mul_f32 v49, v49, v91
	v_mul_f32 v44, v44, v94
	v_mul_f32 v45, v45, v95
	v_mul_f32 v40, v40, v112
	v_mul_f32 v41, v41, v113
	v_mul_f32 v36, v36, v204
	v_mul_f32 v37, v37, v205
	v_mul_f32 v46, v46, v88
	v_mul_f32 v47, v47, v89
	v_mul_f32 v42, v42, v92
	v_mul_f32 v43, v43, v93
	v_mul_f32 v38, v38, v110
	v_mul_f32 v39, v39, v111
	v_mul_f32 v34, v34, v202
	v_mul_f32 v35, v35, v203
	v_mul_f32 v32, v32, v90
	v_mul_f32 v33, v33, v91
	v_mul_f32 v28, v28, v94
	v_mul_f32 v29, v29, v95
	v_mul_f32 v24, v24, v112
	v_mul_f32 v25, v25, v113
	v_mul_f32 v20, v20, v204
	v_mul_f32 v21, v21, v205
	v_mul_f32 v30, v30, v88
	v_mul_f32 v31, v31, v89
	v_mul_f32 v26, v26, v92
	v_mul_f32 v27, v27, v93
	v_mul_f32 v22, v22, v110
	v_mul_f32 v23, v23, v111
	v_mul_f32 v18, v18, v202
	v_mul_f32 v19, v19, v203
	v_mul_f32 v16, v16, v90
	v_mul_f32 v17, v17, v91
	v_mul_f32 v12, v12, v94
	v_mul_f32 v13, v13, v95
	v_mul_f32 v8, v8, v112
	v_mul_f32 v9, v9, v113
	v_mul_f32 v4, v4, v204
	v_mul_f32 v5, v5, v205
	v_mul_f32 v14, v14, v88
	v_mul_f32 v15, v15, v89
	v_mul_f32 v10, v10, v92
	v_mul_f32 v11, v11, v93
	v_mul_f32 v6, v6, v110
	v_mul_f32 v7, v7, v111
	v_mul_f32 v2, v2, v202
	v_mul_f32 v3, v3, v203

.LBB0_653:
	v_sub_f32_e32 v104, v82, v1
	v_sub_f32_e32 v105, v83, v1
	v_sub_f32_e32 v208, v84, v1
	v_sub_f32_e32 v209, v85, v1
	v_sub_f32_e32 v210, v72, v1
	v_sub_f32_e32 v211, v73, v1
	v_sub_f32_e32 v212, v86, v1
	v_sub_f32_e32 v213, v87, v1
	v_sub_f32_e32 v214, v68, v1
	v_sub_f32_e32 v215, v69, v1
	v_sub_f32_e32 v216, v76, v1
	v_sub_f32_e32 v217, v77, v1
	v_sub_f32_e32 v218, v66, v1
	v_sub_f32_e32 v219, v67, v1
	v_sub_f32_e32 v220, v70, v1
	v_sub_f32_e32 v221, v71, v1
	ds_read_b128 v[228:231], v191 offset:32768
	ds_read_b128 v[232:235], v190 offset:32768
	ds_read_b128 v[236:239], v191 offset:40960
	ds_read_b128 v[248:251], v190 offset:40960
	ds_read_b128 v[252:255], v189 offset:32768
	s_waitcnt lgkmcnt(4)
	v_mfma_f32_32x32x16_bf16 v[82:97], v[228:231], v[142:145], 0
	ds_read_b128 v[228:231], v189 offset:40960
	s_waitcnt lgkmcnt(4)
	v_mfma_f32_32x32x16_bf16 v[82:97], v[232:235], v[138:141], v[82:97]
	ds_read_b128 v[232:235], v188 offset:32768
	s_waitcnt lgkmcnt(4)
	v_mfma_f32_32x32x16_bf16 v[66:81], v[236:239], v[142:145], 0
	ds_read_b128 v[236:239], v188 offset:40960
	s_waitcnt lgkmcnt(4)
	v_mfma_f32_32x32x16_bf16 v[66:81], v[248:251], v[138:141], v[66:81]
	ds_read_b128 v[248:251], v191 offset:32896
	s_waitcnt lgkmcnt(4)
	v_mfma_f32_32x32x16_bf16 v[82:97], v[252:255], v[134:137], v[82:97]
	ds_read_b128 v[252:255], v191 offset:41088
	s_waitcnt lgkmcnt(4)
	v_mfma_f32_32x32x16_bf16 v[66:81], v[228:231], v[134:137], v[66:81]
	ds_read_b128 v[228:231], v190 offset:32896
	s_waitcnt lgkmcnt(4)
	v_mfma_f32_32x32x16_bf16 v[82:97], v[232:235], v[130:133], v[82:97]
	ds_read_b128 v[232:235], v190 offset:41088
	s_waitcnt lgkmcnt(4)
	v_mfma_f32_32x32x16_bf16 v[66:81], v[236:239], v[130:133], v[66:81]
	ds_read_b128 v[236:239], v189 offset:32896
	s_waitcnt lgkmcnt(4)
	v_mfma_f32_32x32x16_bf16 v[82:97], v[248:251], v[126:129], v[82:97]
	ds_read_b128 v[248:251], v189 offset:41088
	s_waitcnt lgkmcnt(4)
	v_mfma_f32_32x32x16_bf16 v[66:81], v[252:255], v[126:129], v[66:81]
	ds_read_b128 v[252:255], v188 offset:32896
	s_waitcnt lgkmcnt(4)
	v_mfma_f32_32x32x16_bf16 v[82:97], v[228:231], v[122:125], v[82:97]
	ds_read_b128 v[228:231], v188 offset:41088
	s_waitcnt lgkmcnt(4)
	v_mfma_f32_32x32x16_bf16 v[66:81], v[232:235], v[122:125], v[66:81]
	s_waitcnt lgkmcnt(3)
	v_mfma_f32_32x32x16_bf16 v[82:97], v[236:239], v[118:121], v[82:97]
	s_waitcnt lgkmcnt(2)
	v_mfma_f32_32x32x16_bf16 v[66:81], v[248:251], v[118:121], v[66:81]
	s_waitcnt lgkmcnt(1)
	v_mfma_f32_32x32x16_bf16 v[82:97], v[252:255], v[114:117], v[82:97]
	s_waitcnt lgkmcnt(0)
	v_mfma_f32_32x32x16_bf16 v[66:81], v[228:231], v[114:117], v[66:81]
	v_exp_f32_e32 v222, v104
	v_add_f32_e32 v104, 0, v196
	v_add_f32_e32 v104, v203, v104
	v_add_f32_e32 v104, v112, v104
	v_add_f32_e32 v104, v202, v104
	v_add_f32_e32 v104, v110, v104
	v_add_f32_e32 v104, v113, v104
	v_add_f32_e32 v104, v109, v104
	v_add_f32_e32 v104, v111, v104
	v_add_f32_e32 v104, v103, v104
	v_add_f32_e32 v104, v107, v104
	v_add_f32_e32 v104, v101, v104
	v_add_f32_e32 v104, v106, v104
	v_add_f32_e32 v104, v99, v104
	v_exp_f32_e32 v223, v105
	v_add_f32_e32 v104, v102, v104
	v_exp_f32_e32 v208, v208
	v_add_f32_e32 v104, v98, v104
	v_exp_f32_e32 v209, v209
	v_add_f32_e32 v104, v100, v104
	v_exp_f32_e32 v210, v210
	v_add_f32_e32 v104, v222, v104
	v_exp_f32_e32 v211, v211
	v_add_f32_e32 v104, v223, v104
	v_exp_f32_e32 v212, v212
	v_add_f32_e32 v104, v208, v104
	v_exp_f32_e32 v213, v213
	v_add_f32_e32 v104, v209, v104
	v_exp_f32_e32 v214, v214
	v_add_f32_e32 v104, v210, v104
	v_exp_f32_e32 v215, v215
	v_add_f32_e32 v104, v211, v104
	v_exp_f32_e32 v216, v216
	v_add_f32_e32 v104, v212, v104
	v_exp_f32_e32 v217, v217
	v_add_f32_e32 v104, v213, v104
	v_exp_f32_e32 v218, v218
	v_add_f32_e32 v104, v214, v104
	v_exp_f32_e32 v219, v219
	v_add_f32_e32 v104, v215, v104
	v_exp_f32_e32 v220, v220
	v_add_f32_e32 v104, v216, v104
	v_exp_f32_e32 v221, v221
	v_add_f32_e32 v104, v217, v104
	v_add_f32_e32 v104, v218, v104
	v_add_f32_e32 v104, v219, v104
	v_add_f32_e32 v104, v220, v104
	v_add_f32_e32 v104, v221, v104
	v_mov_b32_e32 v105, v104
	v_cvt_pk_bf16_f32 v204, v196, v203
	v_cvt_pk_bf16_f32 v205, v112, v202
	v_cvt_pk_bf16_f32 v206, v110, v113
	v_cvt_pk_bf16_f32 v207, v109, v111
	v_cvt_pk_bf16_f32 v110, v103, v107
	v_cvt_pk_bf16_f32 v111, v101, v106
	v_cvt_pk_bf16_f32 v112, v99, v102
	v_cvt_pk_bf16_f32 v113, v98, v100
	v_cvt_pk_bf16_f32 v98, v222, v223
	v_cvt_pk_bf16_f32 v99, v208, v209
	v_cvt_pk_bf16_f32 v100, v210, v211
	v_cvt_pk_bf16_f32 v101, v212, v213
	s_nop 1
	v_permlane32_swap_b32_e32 v104, v105
	v_permlane32_swap_b32_e32 v98, v100
	v_permlane32_swap_b32_e32 v99, v101
	v_cvt_pk_bf16_f32 v208, v214, v215
	v_cvt_pk_bf16_f32 v209, v216, v217
	v_cvt_pk_bf16_f32 v210, v218, v219
	v_cvt_pk_bf16_f32 v211, v220, v221
	v_permlane32_swap_b32_e32 v204, v206
	v_permlane32_swap_b32_e32 v205, v207
	v_permlane32_swap_b32_e32 v110, v112
	v_permlane32_swap_b32_e32 v111, v113
	v_permlane32_swap_b32_e32 v208, v210
	v_permlane32_swap_b32_e32 v209, v211
	ds_read_b64_tr_b16 v[212:213], v183 offset:0x4000
	ds_read_b64_tr_b16 v[214:215], v183 offset:0x4800
	ds_read_b64_tr_b16 v[216:217], v183 offset:0x5000
	ds_read_b64_tr_b16 v[218:219], v183 offset:0x5800
	ds_read_b64_tr_b16 v[220:221], v183 offset:0x6000
	ds_read_b64_tr_b16 v[222:223], v183 offset:0x6800
	ds_read_b64_tr_b16 v[224:225], v183 offset:0x7000
	ds_read_b64_tr_b16 v[226:227], v183 offset:0x7800
	s_nop 0
	s_waitcnt lgkmcnt(6)
	v_mfma_f32_32x32x16_bf16 v[50:65], v[204:207], v[212:215], v[50:65]
	ds_read_b64_tr_b16 v[212:213], v183 offset:0x4200
	ds_read_b64_tr_b16 v[214:215], v183 offset:0x4a00
	s_waitcnt lgkmcnt(6)
	v_mfma_f32_32x32x16_bf16 v[50:65], v[110:113], v[216:219], v[50:65]
	ds_read_b64_tr_b16 v[216:217], v183 offset:0x5200
	ds_read_b64_tr_b16 v[218:219], v183 offset:0x5a00
	s_waitcnt lgkmcnt(6)
	v_mfma_f32_32x32x16_bf16 v[50:65], v[98:101], v[220:223], v[50:65]
	ds_read_b64_tr_b16 v[220:221], v183 offset:0x6200
	ds_read_b64_tr_b16 v[222:223], v183 offset:0x6a00
	s_waitcnt lgkmcnt(6)
	v_mfma_f32_32x32x16_bf16 v[50:65], v[208:211], v[224:227], v[50:65]
	ds_read_b64_tr_b16 v[224:225], v183 offset:0x7200
	ds_read_b64_tr_b16 v[226:227], v183 offset:0x7a00
	s_waitcnt lgkmcnt(6)
	v_mfma_f32_32x32x16_bf16 v[34:49], v[204:207], v[212:215], v[34:49]
	ds_read_b64_tr_b16 v[212:213], v183 offset:0x4400
	ds_read_b64_tr_b16 v[214:215], v183 offset:0x4c00
	s_waitcnt lgkmcnt(6)
	v_mfma_f32_32x32x16_bf16 v[34:49], v[110:113], v[216:219], v[34:49]
	ds_read_b64_tr_b16 v[216:217], v183 offset:0x5400
	ds_read_b64_tr_b16 v[218:219], v183 offset:0x5c00
	s_waitcnt lgkmcnt(6)
	v_mfma_f32_32x32x16_bf16 v[34:49], v[98:101], v[220:223], v[34:49]
	ds_read_b64_tr_b16 v[220:221], v183 offset:0x6400
	ds_read_b64_tr_b16 v[222:223], v183 offset:0x6c00
	s_waitcnt lgkmcnt(6)
	v_mfma_f32_32x32x16_bf16 v[34:49], v[208:211], v[224:227], v[34:49]
	ds_read_b64_tr_b16 v[224:225], v183 offset:0x7400
	ds_read_b64_tr_b16 v[226:227], v183 offset:0x7c00
	s_waitcnt lgkmcnt(6)
	v_mfma_f32_32x32x16_bf16 v[18:33], v[204:207], v[212:215], v[18:33]
	ds_read_b64_tr_b16 v[212:213], v183 offset:0x4600
	ds_read_b64_tr_b16 v[214:215], v183 offset:0x4e00
	s_waitcnt lgkmcnt(6)
	v_mfma_f32_32x32x16_bf16 v[18:33], v[110:113], v[216:219], v[18:33]
	ds_read_b64_tr_b16 v[216:217], v183 offset:0x5600
	ds_read_b64_tr_b16 v[218:219], v183 offset:0x5e00
	s_waitcnt lgkmcnt(6)
	v_mfma_f32_32x32x16_bf16 v[18:33], v[98:101], v[220:223], v[18:33]
	ds_read_b64_tr_b16 v[220:221], v183 offset:0x6600
	ds_read_b64_tr_b16 v[222:223], v183 offset:0x6e00
	s_waitcnt lgkmcnt(6)
	v_mfma_f32_32x32x16_bf16 v[18:33], v[208:211], v[224:227], v[18:33]
	ds_read_b64_tr_b16 v[224:225], v183 offset:0x7600
	ds_read_b64_tr_b16 v[226:227], v183 offset:0x7e00
	s_waitcnt lgkmcnt(6)
	v_mfma_f32_32x32x16_bf16 v[2:17], v[204:207], v[212:215], v[2:17]
	s_waitcnt lgkmcnt(4)
	v_mfma_f32_32x32x16_bf16 v[2:17], v[110:113], v[216:219], v[2:17]
	s_waitcnt lgkmcnt(2)
	v_mfma_f32_32x32x16_bf16 v[2:17], v[98:101], v[220:223], v[2:17]
	s_waitcnt lgkmcnt(0)
	v_mfma_f32_32x32x16_bf16 v[2:17], v[208:211], v[224:227], v[2:17]
	ds_read_b128 v[100:103], v198 offset:256
	ds_read_b128 v[110:113], v198 offset:288
	ds_read_b128 v[202:205], v198 offset:384
	ds_read_b128 v[206:209], v198 offset:416
	ds_read_b128 v[210:213], v198 offset:320
	ds_read_b128 v[214:217], v198 offset:352
	ds_read_b128 v[218:221], v198 offset:448
	ds_read_b128 v[222:225], v198 offset:480
	s_waitcnt lgkmcnt(7)
	v_xor_b32_e32 v103, 0x80000000, v103
	v_xor_b32_e32 v102, 0x80000000, v102
	s_waitcnt lgkmcnt(6)
	v_xor_b32_e32 v107, 0x80000000, v113
	v_xor_b32_e32 v106, 0x80000000, v112
	s_waitcnt lgkmcnt(3)
	v_xor_b32_e32 v113, 0x80000000, v213
	v_xor_b32_e32 v112, 0x80000000, v212
	s_waitcnt lgkmcnt(2)
	v_xor_b32_e32 v213, 0x80000000, v217
	v_xor_b32_e32 v212, 0x80000000, v216
	v_fma_f32 v98, v86, s12, -v110
	v_fma_f32 v99, v87, s12, -v111
	v_fma_f32 v86, v96, s12, v212
	v_fma_f32 v87, v97, s12, v213
	v_fma_f32 v88, v88, s12, v106
	v_fma_f32 v89, v89, s12, v107
	v_fma_f32 v84, v84, s12, v102
	v_fma_f32 v85, v85, s12, v103
	v_fma_f32 v96, v82, s12, -v100
	v_fma_f32 v97, v83, s12, -v101
	v_xor_b32_e32 v103, 0x80000000, v205
	v_xor_b32_e32 v102, 0x80000000, v204
	v_xor_b32_e32 v101, 0x80000000, v209
	v_xor_b32_e32 v100, 0x80000000, v208
	s_waitcnt lgkmcnt(1)
	v_xor_b32_e32 v107, 0x80000000, v221
	v_xor_b32_e32 v106, 0x80000000, v220
	s_waitcnt lgkmcnt(0)
	v_xor_b32_e32 v111, 0x80000000, v225
	v_xor_b32_e32 v110, 0x80000000, v224
	s_add_i32 s0, s11, 64
	v_fma_f32 v94, v94, s12, -v214
	v_fma_f32 v95, v95, s12, -v215
	v_fma_f32 v90, v90, s12, -v210
	v_fma_f32 v91, v91, s12, -v211
	v_fma_f32 v92, v92, s12, v112
	v_fma_f32 v93, v93, s12, v113
	v_fma_f32 v82, v78, s12, -v222
	v_fma_f32 v83, v79, s12, -v223
	v_fma_f32 v74, v74, s12, -v218
	v_fma_f32 v75, v75, s12, -v219
	v_fma_f32 v78, v70, s12, -v206
	v_fma_f32 v79, v71, s12, -v207
	v_fma_f32 v70, v80, s12, v110
	v_fma_f32 v71, v81, s12, v111
	v_fma_f32 v76, v76, s12, v106
	v_fma_f32 v77, v77, s12, v107
	v_fma_f32 v100, v72, s12, v100
	v_fma_f32 v101, v73, s12, v101
	v_fma_f32 v102, v68, s12, v102
	v_fma_f32 v103, v69, s12, v103
	s_cmp_le_i32 s0, s27
	v_fma_f32 v80, v66, s12, -v202
	v_fma_f32 v81, v67, s12, -v203
	s_cbranch_scc1 .LBB0_655
	v_cmp_gt_i32_e64 s[92:93], 26, v199
	v_cmp_gt_i32_e64 s[94:95], 27, v199
	v_cmp_gt_i32_e64 s[90:91], 25, v199
	s_and_b64 s[92:93], s[94:95], s[92:93]
	v_cmp_gt_i32_e64 s[88:89], 24, v199
	s_and_b64 s[90:91], s[92:93], s[90:91]
	v_cmp_gt_i32_e64 s[86:87], 19, v199
	s_and_b64 s[88:89], s[90:91], s[88:89]
	v_cmp_gt_i32_e64 s[84:85], 18, v199
	s_and_b64 s[86:87], s[88:89], s[86:87]
	v_cmp_gt_i32_e64 s[82:83], 17, v199
	s_and_b64 s[84:85], s[86:87], s[84:85]
	v_cmp_gt_i32_e64 s[80:81], 16, v199
	s_and_b64 s[82:83], s[84:85], s[82:83]
	v_cmp_gt_i32_e64 s[78:79], 11, v199
	s_and_b64 s[80:81], s[82:83], s[80:81]
	v_cmp_gt_i32_e64 s[76:77], 10, v199
	s_and_b64 s[78:79], s[80:81], s[78:79]
	v_cmp_gt_i32_e64 s[74:75], 9, v199
	s_and_b64 s[76:77], s[78:79], s[76:77]
	v_cmp_gt_i32_e64 s[72:73], 8, v199
	s_and_b64 s[74:75], s[76:77], s[74:75]
	v_cmp_gt_i32_e64 s[70:71], 3, v199
	s_and_b64 s[72:73], s[74:75], s[72:73]
	v_cmp_gt_i32_e64 s[68:69], 2, v199
	s_and_b64 s[70:71], s[72:73], s[70:71]
	v_cmp_gt_i32_e64 s[2:3], 1, v199
	s_and_b64 s[68:69], s[70:71], s[68:69]
	v_cmp_gt_i32_e64 s[0:1], 0, v199
	s_and_b64 s[2:3], s[68:69], s[2:3]
	s_and_b64 s[0:1], s[2:3], s[0:1]
	v_cmp_gt_i32_e64 s[66:67], 58, v199
	v_cndmask_b32_e64 v96, v96, v175, s[0:1]
	v_cmp_gt_i32_e64 s[0:1], 59, v199
	v_cmp_gt_i32_e64 s[64:65], 57, v199
	v_cmp_gt_i32_e64 s[62:63], 56, v199
	v_cndmask_b32_e64 v71, v71, v175, s[0:1]
	s_and_b64 s[0:1], s[0:1], s[66:67]
	v_cndmask_b32_e64 v70, v70, v175, s[0:1]
	s_and_b64 s[0:1], s[0:1], s[64:65]
	v_cmp_gt_i32_e64 s[60:61], 51, v199
	v_cndmask_b32_e64 v83, v83, v175, s[0:1]
	s_and_b64 s[0:1], s[0:1], s[62:63]
	v_cmp_gt_i32_e64 s[58:59], 50, v199
	v_cndmask_b32_e64 v82, v82, v175, s[0:1]
	s_and_b64 s[0:1], s[0:1], s[60:61]
	v_cmp_gt_i32_e64 s[56:57], 49, v199
	v_cndmask_b32_e64 v77, v77, v175, s[0:1]
	s_and_b64 s[0:1], s[0:1], s[58:59]
	v_cmp_gt_i32_e64 s[54:55], 48, v199
	v_cndmask_b32_e64 v76, v76, v175, s[0:1]
	s_and_b64 s[0:1], s[0:1], s[56:57]
	v_cmp_gt_i32_e64 s[52:53], 43, v199
	v_cndmask_b32_e64 v75, v75, v175, s[0:1]
	s_and_b64 s[0:1], s[0:1], s[54:55]
	v_cmp_gt_i32_e64 s[50:51], 42, v199
	v_cndmask_b32_e64 v74, v74, v175, s[0:1]
	s_and_b64 s[0:1], s[0:1], s[52:53]
	v_cmp_gt_i32_e64 s[48:49], 41, v199
	v_cndmask_b32_e64 v101, v101, v175, s[0:1]
	s_and_b64 s[0:1], s[0:1], s[50:51]
	v_cmp_gt_i32_e64 s[46:47], 40, v199
	v_cndmask_b32_e64 v100, v100, v175, s[0:1]
	s_and_b64 s[0:1], s[0:1], s[48:49]
	v_cmp_gt_i32_e64 s[44:45], 35, v199
	v_cndmask_b32_e64 v79, v79, v175, s[0:1]
	s_and_b64 s[0:1], s[0:1], s[46:47]
	v_cmp_gt_i32_e64 s[42:43], 34, v199
	v_cndmask_b32_e64 v78, v78, v175, s[0:1]
	s_and_b64 s[0:1], s[0:1], s[44:45]
	v_cmp_gt_i32_e64 s[40:41], 33, v199
	v_cndmask_b32_e64 v103, v103, v175, s[0:1]
	s_and_b64 s[0:1], s[0:1], s[42:43]
	v_cmp_gt_i32_e32 vcc, 32, v199
	v_cndmask_b32_e64 v102, v102, v175, s[0:1]
	s_and_b64 s[0:1], s[0:1], s[40:41]
	v_cndmask_b32_e64 v94, v94, v175, s[88:89]
	v_readlane_b32 s88, v242, 2
	s_and_b64 vcc, s[0:1], vcc
	v_cndmask_b32_e64 v87, v87, v175, s[94:95]
	v_cndmask_b32_e64 v86, v86, v175, s[92:93]
	s_movk_i32 s93, 0x6018
	s_mov_b32 s92, 0xf800000
	v_cndmask_b32_e64 v95, v95, v175, s[90:91]
	s_mov_b64 s[90:91], s[16:17]
	v_readlane_b32 s89, v242, 3
	v_cndmask_b32_e64 v93, v93, v175, s[86:87]
	v_readlane_b32 s86, v242, 0
	v_cndmask_b32_e64 v92, v92, v175, s[84:85]
	v_cndmask_b32_e64 v91, v91, v175, s[82:83]
	s_movk_i32 s83, 0x6000
	v_cndmask_b32_e64 v90, v90, v175, s[80:81]
	v_cndmask_b32_e64 v89, v89, v175, s[78:79]
	v_cndmask_b32_e64 v88, v88, v175, s[76:77]
	v_cndmask_b32_e64 v99, v99, v175, s[74:75]
	v_cndmask_b32_e64 v98, v98, v175, s[72:73]
	v_cndmask_b32_e64 v85, v85, v175, s[70:71]
	v_cndmask_b32_e64 v84, v84, v175, s[68:69]
	v_cndmask_b32_e64 v97, v97, v175, s[2:3]
	s_mov_b32 s56, s30
	v_cndmask_b32_e64 v81, v81, v175, s[0:1]
	v_cndmask_b32_e32 v80, v80, v175, vcc
	v_readlane_b32 s87, v242, 1

.LBB0_657:
	v_max_f32_e32 v67, v1, v1
	v_max_f32_e32 v66, v67, v66
	v_sub_f32_e32 v67, v1, v66
	v_exp_f32_e32 v67, v67
	s_waitcnt vmcnt(3)
	v_cndmask_b32_e64 v146, v67, 1.0, s[40:41]
	v_cmp_gt_f32_e32 vcc, 1.0, v146
	s_cbranch_vccz .LBB0_661
	s_and_saveexec_b64 s[0:1], s[38:39]
	ds_write_b32 v185, v146 offset:128
	s_or_b64 exec, exec, s[0:1]
	s_waitcnt lgkmcnt(0)
	ds_read_b128 v[110:113], v184 offset:224
	s_waitcnt vmcnt(2)
	ds_read_b128 v[148:151], v184 offset:192
	s_waitcnt vmcnt(1)
	ds_read_b128 v[152:155], v184 offset:160
	s_waitcnt vmcnt(0)
	ds_read_b128 v[156:159], v184 offset:128
	s_waitcnt lgkmcnt(3)
	v_mul_f32 v64, v64, v112
	v_mul_f32 v65, v65, v113
	s_waitcnt lgkmcnt(2)
	v_mul_f32 v60, v60, v150
	v_mul_f32 v61, v61, v151
	s_waitcnt lgkmcnt(1)
	v_mul_f32 v56, v56, v154
	v_mul_f32 v57, v57, v155
	s_waitcnt lgkmcnt(0)
	v_mul_f32 v52, v52, v158
	v_mul_f32 v53, v53, v159
	v_mul_f32 v62, v62, v110
	v_mul_f32 v63, v63, v111
	v_mul_f32 v58, v58, v148
	v_mul_f32 v59, v59, v149
	v_mul_f32 v54, v54, v152
	v_mul_f32 v55, v55, v153
	v_mul_f32 v50, v50, v156
	v_mul_f32 v51, v51, v157
	v_mul_f32 v48, v48, v112
	v_mul_f32 v49, v49, v113
	v_mul_f32 v44, v44, v150
	v_mul_f32 v45, v45, v151
	v_mul_f32 v40, v40, v154
	v_mul_f32 v41, v41, v155
	v_mul_f32 v36, v36, v158
	v_mul_f32 v37, v37, v159
	v_mul_f32 v46, v46, v110
	v_mul_f32 v47, v47, v111
	v_mul_f32 v42, v42, v148
	v_mul_f32 v43, v43, v149
	v_mul_f32 v38, v38, v152
	v_mul_f32 v39, v39, v153
	v_mul_f32 v34, v34, v156
	v_mul_f32 v35, v35, v157
	v_mul_f32 v32, v32, v112
	v_mul_f32 v33, v33, v113
	v_mul_f32 v28, v28, v150
	v_mul_f32 v29, v29, v151
	v_mul_f32 v24, v24, v154
	v_mul_f32 v25, v25, v155
	v_mul_f32 v20, v20, v158
	v_mul_f32 v21, v21, v159
	v_mul_f32 v30, v30, v110
	v_mul_f32 v31, v31, v111
	v_mul_f32 v26, v26, v148
	v_mul_f32 v27, v27, v149
	v_mul_f32 v22, v22, v152
	v_mul_f32 v23, v23, v153
	v_mul_f32 v18, v18, v156
	v_mul_f32 v19, v19, v157
	v_mul_f32 v16, v16, v112
	v_mul_f32 v17, v17, v113
	v_mul_f32 v12, v12, v150
	v_mul_f32 v13, v13, v151
	v_mul_f32 v8, v8, v154
	v_mul_f32 v9, v9, v155
	v_mul_f32 v4, v4, v158
	v_mul_f32 v5, v5, v159
	v_mul_f32 v14, v14, v110
	v_mul_f32 v15, v15, v111
	v_mul_f32 v10, v10, v148
	v_mul_f32 v11, v11, v149
	v_mul_f32 v6, v6, v152
	v_mul_f32 v7, v7, v153
	v_mul_f32 v2, v2, v156
	v_mul_f32 v3, v3, v157

.LBB0_664:
	ds_read_b128 v[82:85], v191 offset:49152
	ds_read_b128 v[86:89], v191 offset:57344
	s_waitcnt lgkmcnt(1)
	v_mfma_f32_32x32x16_bf16 v[98:113], v[82:85], v[142:145], 0
	s_waitcnt lgkmcnt(0)
	v_mfma_f32_32x32x16_bf16 v[82:97], v[86:89], v[142:145], 0
	ds_read_b128 v[142:145], v190 offset:49152
	s_waitcnt vmcnt(2)
	ds_read_b128 v[148:151], v190 offset:57344
	s_waitcnt lgkmcnt(1)
	v_mfma_f32_32x32x16_bf16 v[98:113], v[142:145], v[138:141], v[98:113]
	s_waitcnt lgkmcnt(0)
	v_mfma_f32_32x32x16_bf16 v[82:97], v[148:151], v[138:141], v[82:97]
	ds_read_b128 v[138:141], v189 offset:49152
	ds_read_b128 v[142:145], v189 offset:57344
	s_waitcnt lgkmcnt(1)
	v_mfma_f32_32x32x16_bf16 v[98:113], v[138:141], v[134:137], v[98:113]
	s_waitcnt lgkmcnt(0)
	v_mfma_f32_32x32x16_bf16 v[82:97], v[142:145], v[134:137], v[82:97]
	ds_read_b128 v[134:137], v188 offset:49152
	ds_read_b128 v[138:141], v188 offset:57344
	s_waitcnt lgkmcnt(1)
	v_mfma_f32_32x32x16_bf16 v[98:113], v[134:137], v[130:133], v[98:113]
	s_waitcnt lgkmcnt(0)
	v_mfma_f32_32x32x16_bf16 v[82:97], v[138:141], v[130:133], v[82:97]
	ds_read_b128 v[130:133], v191 offset:49280
	ds_read_b128 v[134:137], v191 offset:57472
	s_waitcnt lgkmcnt(1)
	v_mfma_f32_32x32x16_bf16 v[98:113], v[130:133], v[126:129], v[98:113]
	s_waitcnt lgkmcnt(0)
	v_mfma_f32_32x32x16_bf16 v[82:97], v[134:137], v[126:129], v[82:97]
	ds_read_b128 v[126:129], v190 offset:49280
	ds_read_b128 v[130:133], v190 offset:57472
	s_waitcnt lgkmcnt(1)
	v_mfma_f32_32x32x16_bf16 v[98:113], v[126:129], v[122:125], v[98:113]
	s_waitcnt lgkmcnt(0)
	v_mfma_f32_32x32x16_bf16 v[82:97], v[130:133], v[122:125], v[82:97]
	ds_read_b128 v[122:125], v189 offset:49280
	ds_read_b128 v[126:129], v189 offset:57472
	s_waitcnt lgkmcnt(1)
	v_mfma_f32_32x32x16_bf16 v[98:113], v[122:125], v[118:121], v[98:113]
	s_waitcnt lgkmcnt(0)
	v_mfma_f32_32x32x16_bf16 v[82:97], v[126:129], v[118:121], v[82:97]
	ds_read_b128 v[118:121], v188 offset:49280
	ds_read_b128 v[122:125], v188 offset:57472
	s_waitcnt lgkmcnt(1)
	v_mfma_f32_32x32x16_bf16 v[98:113], v[118:121], v[114:117], v[98:113]
	s_waitcnt lgkmcnt(0)
	v_mfma_f32_32x32x16_bf16 v[82:97], v[122:125], v[114:117], v[82:97]
	v_exp_f32_e32 v81, v1
	v_add_f32_e32 v1, 0, v215
	v_add_f32_e32 v1, v217, v1
	v_add_f32_e32 v1, v213, v1
	v_add_f32_e32 v1, v216, v1
	v_add_f32_e32 v1, v211, v1
	v_add_f32_e32 v1, v214, v1
	v_add_f32_e32 v1, v210, v1
	v_add_f32_e32 v1, v212, v1
	v_add_f32_e32 v1, v207, v1
	v_add_f32_e32 v1, v209, v1
	v_add_f32_e32 v1, v205, v1
	v_add_f32_e32 v1, v208, v1
	v_exp_f32_e32 v80, v80
	v_add_f32_e32 v1, v203, v1
	v_add_f32_e32 v1, v206, v1
	v_exp_f32_e32 v78, v78
	v_add_f32_e32 v1, v202, v1
	v_exp_f32_e32 v79, v79
	v_add_f32_e32 v1, v204, v1
	v_exp_f32_e32 v76, v76
	v_add_f32_e32 v1, v80, v1
	v_exp_f32_e32 v77, v77
	v_add_f32_e32 v1, v81, v1
	v_exp_f32_e32 v115, v74
	v_add_f32_e32 v1, v78, v1
	v_exp_f32_e32 v116, v75
	v_add_f32_e32 v1, v79, v1
	v_exp_f32_e32 v117, v72
	v_add_f32_e32 v1, v76, v1
	v_exp_f32_e32 v118, v73
	v_add_f32_e32 v1, v77, v1
	v_exp_f32_e32 v119, v70
	v_add_f32_e32 v1, v115, v1
	v_exp_f32_e32 v120, v71
	v_add_f32_e32 v1, v116, v1
	v_exp_f32_e32 v121, v68
	v_add_f32_e32 v1, v117, v1
	v_exp_f32_e32 v122, v69
	v_add_f32_e32 v1, v118, v1
	v_exp_f32_e32 v123, v66
	v_add_f32_e32 v1, v119, v1
	v_exp_f32_e32 v124, v67
	v_add_f32_e32 v1, v120, v1
	v_add_f32_e32 v1, v121, v1
	v_add_f32_e32 v1, v122, v1
	v_add_f32_e32 v1, v123, v1
	v_add_f32_e32 v1, v124, v1
	v_mov_b32_e32 v114, v1
	v_cvt_pk_bf16_f32 v66, v215, v217
	v_cvt_pk_bf16_f32 v67, v213, v216
	v_cvt_pk_bf16_f32 v68, v211, v214
	v_cvt_pk_bf16_f32 v69, v210, v212
	v_cvt_pk_bf16_f32 v70, v207, v209
	v_cvt_pk_bf16_f32 v71, v205, v208
	v_cvt_pk_bf16_f32 v72, v203, v206
	v_cvt_pk_bf16_f32 v73, v202, v204
	v_cvt_pk_bf16_f32 v74, v80, v81
	v_cvt_pk_bf16_f32 v75, v78, v79
	v_cvt_pk_bf16_f32 v76, v76, v77
	v_cvt_pk_bf16_f32 v77, v115, v116
	v_cvt_pk_bf16_f32 v78, v117, v118
	v_cvt_pk_bf16_f32 v79, v119, v120
	v_cvt_pk_bf16_f32 v80, v121, v122
	v_cvt_pk_bf16_f32 v81, v123, v124
	s_nop 1
	v_permlane32_swap_b32_e32 v1, v114
	v_permlane32_swap_b32_e32 v66, v68
	v_permlane32_swap_b32_e32 v67, v69
	v_permlane32_swap_b32_e32 v70, v72
	v_permlane32_swap_b32_e32 v71, v73
	v_permlane32_swap_b32_e32 v74, v76
	v_permlane32_swap_b32_e32 v75, v77
	v_permlane32_swap_b32_e32 v78, v80
	v_permlane32_swap_b32_e32 v79, v81
	ds_read_b64_tr_b16 v[116:117], v183 offset:0
	ds_read_b64_tr_b16 v[118:119], v183 offset:0x800
	ds_read_b64_tr_b16 v[120:121], v183 offset:0x1000
	ds_read_b64_tr_b16 v[122:123], v183 offset:0x1800
	ds_read_b64_tr_b16 v[124:125], v183 offset:0x2000
	ds_read_b64_tr_b16 v[126:127], v183 offset:0x2800
	ds_read_b64_tr_b16 v[128:129], v183 offset:0x3000
	ds_read_b64_tr_b16 v[130:131], v183 offset:0x3800
	s_nop 0
	s_waitcnt lgkmcnt(6)
	v_mfma_f32_32x32x16_bf16 v[50:65], v[66:69], v[116:119], v[50:65]
	ds_read_b64_tr_b16 v[116:117], v183 offset:0x200
	ds_read_b64_tr_b16 v[118:119], v183 offset:0xa00
	s_waitcnt lgkmcnt(6)
	v_mfma_f32_32x32x16_bf16 v[50:65], v[70:73], v[120:123], v[50:65]
	ds_read_b64_tr_b16 v[120:121], v183 offset:0x1200
	ds_read_b64_tr_b16 v[122:123], v183 offset:0x1a00
	s_waitcnt lgkmcnt(6)
	v_mfma_f32_32x32x16_bf16 v[50:65], v[74:77], v[124:127], v[50:65]
	ds_read_b64_tr_b16 v[124:125], v183 offset:0x2200
	ds_read_b64_tr_b16 v[126:127], v183 offset:0x2a00
	s_waitcnt lgkmcnt(6)
	v_mfma_f32_32x32x16_bf16 v[50:65], v[78:81], v[128:131], v[50:65]
	ds_read_b64_tr_b16 v[128:129], v183 offset:0x3200
	ds_read_b64_tr_b16 v[130:131], v183 offset:0x3a00
	s_waitcnt lgkmcnt(6)
	v_mfma_f32_32x32x16_bf16 v[34:49], v[66:69], v[116:119], v[34:49]
	ds_read_b64_tr_b16 v[116:117], v183 offset:0x400
	ds_read_b64_tr_b16 v[118:119], v183 offset:0xc00
	s_waitcnt lgkmcnt(6)
	v_mfma_f32_32x32x16_bf16 v[34:49], v[70:73], v[120:123], v[34:49]
	ds_read_b64_tr_b16 v[120:121], v183 offset:0x1400
	ds_read_b64_tr_b16 v[122:123], v183 offset:0x1c00
	s_waitcnt lgkmcnt(6)
	v_mfma_f32_32x32x16_bf16 v[34:49], v[74:77], v[124:127], v[34:49]
	ds_read_b64_tr_b16 v[124:125], v183 offset:0x2400
	ds_read_b64_tr_b16 v[126:127], v183 offset:0x2c00
	s_waitcnt lgkmcnt(6)
	v_mfma_f32_32x32x16_bf16 v[34:49], v[78:81], v[128:131], v[34:49]
	ds_read_b64_tr_b16 v[128:129], v183 offset:0x3400
	ds_read_b64_tr_b16 v[130:131], v183 offset:0x3c00
	s_waitcnt lgkmcnt(6)
	v_mfma_f32_32x32x16_bf16 v[18:33], v[66:69], v[116:119], v[18:33]
	ds_read_b64_tr_b16 v[116:117], v183 offset:0x600
	ds_read_b64_tr_b16 v[118:119], v183 offset:0xe00
	s_waitcnt lgkmcnt(6)
	v_mfma_f32_32x32x16_bf16 v[18:33], v[70:73], v[120:123], v[18:33]
	ds_read_b64_tr_b16 v[120:121], v183 offset:0x1600
	ds_read_b64_tr_b16 v[122:123], v183 offset:0x1e00
	s_waitcnt lgkmcnt(6)
	v_mfma_f32_32x32x16_bf16 v[18:33], v[74:77], v[124:127], v[18:33]
	ds_read_b64_tr_b16 v[124:125], v183 offset:0x2600
	ds_read_b64_tr_b16 v[126:127], v183 offset:0x2e00
	s_waitcnt lgkmcnt(6)
	v_mfma_f32_32x32x16_bf16 v[18:33], v[78:81], v[128:131], v[18:33]
	ds_read_b64_tr_b16 v[128:129], v183 offset:0x3600
	ds_read_b64_tr_b16 v[130:131], v183 offset:0x3e00
	s_waitcnt lgkmcnt(6)
	v_mfma_f32_32x32x16_bf16 v[2:17], v[66:69], v[116:119], v[2:17]
	s_lshl_b32 s1, s25, 6
	s_sub_i32 s0, s1, 64
	s_lshl_b32 s2, s0, 2
	s_add_i32 s2, s2, 0
	v_lshl_add_u32 v66, v186, 2, s2
	v_add_u32_e32 v66, 0x10800, v66
	s_add_i32 s1, s1, -1
	s_waitcnt lgkmcnt(4)
	v_mfma_f32_32x32x16_bf16 v[2:17], v[70:73], v[120:123], v[2:17]
	s_cmp_gt_i32 s1, s27
	s_waitcnt lgkmcnt(2)
	v_mfma_f32_32x32x16_bf16 v[2:17], v[74:77], v[124:127], v[2:17]
	s_waitcnt lgkmcnt(0)
	v_mfma_f32_32x32x16_bf16 v[2:17], v[78:81], v[128:131], v[2:17]
	ds_read_b128 v[116:119], v66 offset:128
	ds_read_b128 v[120:123], v66
	ds_read_b128 v[68:71], v66 offset:32
	ds_read_b128 v[124:127], v66 offset:160
	ds_read_b128 v[72:75], v66 offset:64
	ds_read_b128 v[128:131], v66 offset:192
	ds_read_b128 v[76:79], v66 offset:96
	ds_read_b128 v[132:135], v66 offset:224
	s_waitcnt lgkmcnt(6)
	v_xor_b32_e32 v81, 0x80000000, v123
	v_xor_b32_e32 v80, 0x80000000, v122
	s_waitcnt lgkmcnt(5)
	v_xor_b32_e32 v123, 0x80000000, v71
	v_xor_b32_e32 v122, 0x80000000, v70
	s_waitcnt lgkmcnt(1)
	v_xor_b32_e32 v79, 0x80000000, v79
	v_xor_b32_e32 v78, 0x80000000, v78
	v_xor_b32_e32 v137, 0x80000000, v75
	v_xor_b32_e32 v136, 0x80000000, v74
	v_fma_f32 v66, v110, s12, -v76
	v_fma_f32 v67, v111, s12, -v77
	v_fma_f32 v70, v106, s12, -v72
	v_fma_f32 v71, v107, s12, -v73
	v_fma_f32 v74, v102, s12, -v68
	v_fma_f32 v75, v103, s12, -v69
	v_fma_f32 v68, v112, s12, v78
	v_fma_f32 v69, v113, s12, v79
	v_fma_f32 v76, v104, s12, v122
	v_fma_f32 v77, v105, s12, v123
	v_fma_f32 v78, v100, s12, v80
	v_fma_f32 v79, v101, s12, v81
	v_xor_b32_e32 v101, 0x80000000, v119
	v_xor_b32_e32 v100, 0x80000000, v118
	v_xor_b32_e32 v103, 0x80000000, v127
	v_xor_b32_e32 v102, 0x80000000, v126
	v_xor_b32_e32 v105, 0x80000000, v131
	v_xor_b32_e32 v104, 0x80000000, v130
	s_waitcnt lgkmcnt(0)
	v_xor_b32_e32 v107, 0x80000000, v135
	v_xor_b32_e32 v106, 0x80000000, v134
	v_fma_f32 v72, v108, s12, v136
	v_fma_f32 v73, v109, s12, v137
	v_fma_f32 v80, v98, s12, -v120
	v_fma_f32 v81, v99, s12, -v121
	v_fma_f32 v94, v94, s12, -v132
	v_fma_f32 v95, v95, s12, -v133
	v_fma_f32 v90, v90, s12, -v128
	v_fma_f32 v91, v91, s12, -v129
	v_fma_f32 v98, v86, s12, -v124
	v_fma_f32 v99, v87, s12, -v125
	v_fma_f32 v86, v96, s12, v106
	v_fma_f32 v87, v97, s12, v107
	v_fma_f32 v92, v92, s12, v104
	v_fma_f32 v93, v93, s12, v105
	v_fma_f32 v88, v88, s12, v102
	v_fma_f32 v89, v89, s12, v103
	v_fma_f32 v84, v84, s12, v100
	v_fma_f32 v85, v85, s12, v101
	v_fma_f32 v82, v82, s12, -v116
	v_fma_f32 v83, v83, s12, -v117
	s_cbranch_scc0 .LBB0_666
	v_subrev_u32_e32 v96, s0, v187
	v_cmp_gt_i32_e64 s[92:93], 26, v96
	v_cmp_gt_i32_e64 s[94:95], 27, v96
	v_cmp_gt_i32_e64 s[90:91], 25, v96
	s_and_b64 s[92:93], s[94:95], s[92:93]
	v_cmp_gt_i32_e64 s[88:89], 24, v96
	s_and_b64 s[90:91], s[92:93], s[90:91]
	v_cmp_gt_i32_e64 s[86:87], 19, v96
	s_and_b64 s[88:89], s[90:91], s[88:89]
	v_cmp_gt_i32_e64 s[84:85], 18, v96
	s_and_b64 s[86:87], s[88:89], s[86:87]
	v_cmp_gt_i32_e64 s[82:83], 17, v96
	s_and_b64 s[84:85], s[86:87], s[84:85]
	v_cmp_gt_i32_e64 s[80:81], 16, v96
	s_and_b64 s[82:83], s[84:85], s[82:83]
	v_cmp_gt_i32_e64 s[78:79], 11, v96
	s_and_b64 s[80:81], s[82:83], s[80:81]
	v_cmp_gt_i32_e64 s[76:77], 10, v96
	s_and_b64 s[78:79], s[80:81], s[78:79]
	v_cmp_gt_i32_e64 s[74:75], 9, v96
	s_and_b64 s[76:77], s[78:79], s[76:77]
	v_cmp_gt_i32_e64 s[72:73], 8, v96
	s_and_b64 s[74:75], s[76:77], s[74:75]
	v_cmp_gt_i32_e64 s[70:71], 3, v96
	s_and_b64 s[72:73], s[74:75], s[72:73]
	v_cmp_gt_i32_e64 s[68:69], 2, v96
	s_and_b64 s[70:71], s[72:73], s[70:71]
	v_cmp_gt_i32_e64 s[2:3], 1, v96
	s_and_b64 s[68:69], s[70:71], s[68:69]
	v_cmp_gt_i32_e64 s[0:1], 0, v96
	s_and_b64 s[2:3], s[68:69], s[2:3]
	s_and_b64 s[0:1], s[2:3], s[0:1]
	v_cmp_gt_i32_e64 s[66:67], 58, v96
	v_cndmask_b32_e64 v80, v80, v175, s[0:1]
	v_cmp_gt_i32_e64 s[0:1], 59, v96
	v_cmp_gt_i32_e64 s[64:65], 57, v96
	v_cmp_gt_i32_e64 s[62:63], 56, v96
	v_cndmask_b32_e64 v87, v87, v175, s[0:1]
	s_and_b64 s[0:1], s[0:1], s[66:67]
	v_cndmask_b32_e64 v86, v86, v175, s[0:1]
	s_and_b64 s[0:1], s[0:1], s[64:65]
	v_cmp_gt_i32_e64 s[60:61], 51, v96
	v_cndmask_b32_e64 v95, v95, v175, s[0:1]
	s_and_b64 s[0:1], s[0:1], s[62:63]
	v_cmp_gt_i32_e64 s[58:59], 50, v96
	v_cndmask_b32_e64 v94, v94, v175, s[0:1]
	s_and_b64 s[0:1], s[0:1], s[60:61]
	v_cmp_gt_i32_e64 s[56:57], 49, v96
	v_cndmask_b32_e64 v93, v93, v175, s[0:1]
	s_and_b64 s[0:1], s[0:1], s[58:59]
	v_cmp_gt_i32_e64 s[54:55], 48, v96
	v_cndmask_b32_e64 v92, v92, v175, s[0:1]
	s_and_b64 s[0:1], s[0:1], s[56:57]
	v_cmp_gt_i32_e64 s[52:53], 43, v96
	v_cndmask_b32_e64 v91, v91, v175, s[0:1]
	s_and_b64 s[0:1], s[0:1], s[54:55]
	v_cmp_gt_i32_e64 s[50:51], 42, v96
	v_cndmask_b32_e64 v90, v90, v175, s[0:1]
	s_and_b64 s[0:1], s[0:1], s[52:53]
	v_cmp_gt_i32_e64 s[48:49], 41, v96
	v_cndmask_b32_e64 v89, v89, v175, s[0:1]
	s_and_b64 s[0:1], s[0:1], s[50:51]
	v_cmp_gt_i32_e64 s[46:47], 40, v96
	v_cndmask_b32_e64 v88, v88, v175, s[0:1]
	s_and_b64 s[0:1], s[0:1], s[48:49]
	v_cmp_gt_i32_e64 s[44:45], 35, v96
	v_cndmask_b32_e64 v99, v99, v175, s[0:1]
	s_and_b64 s[0:1], s[0:1], s[46:47]
	v_cmp_gt_i32_e64 s[42:43], 34, v96
	v_cndmask_b32_e64 v98, v98, v175, s[0:1]
	s_and_b64 s[0:1], s[0:1], s[44:45]
	v_cmp_gt_i32_e64 s[40:41], 33, v96
	v_cndmask_b32_e64 v85, v85, v175, s[0:1]
	s_and_b64 s[0:1], s[0:1], s[42:43]
	v_cmp_gt_i32_e32 vcc, 32, v96
	v_cndmask_b32_e64 v84, v84, v175, s[0:1]
	s_and_b64 s[0:1], s[0:1], s[40:41]
	v_cndmask_b32_e64 v66, v66, v175, s[88:89]
	v_readlane_b32 s88, v242, 2
	s_and_b64 vcc, s[0:1], vcc
	v_cndmask_b32_e64 v69, v69, v175, s[94:95]
	v_cndmask_b32_e64 v68, v68, v175, s[92:93]
	s_movk_i32 s93, 0x6018
	s_mov_b32 s92, 0xf800000
	v_cndmask_b32_e64 v67, v67, v175, s[90:91]
	s_mov_b64 s[90:91], s[16:17]
	v_readlane_b32 s89, v242, 3
	v_cndmask_b32_e64 v73, v73, v175, s[86:87]
	v_readlane_b32 s86, v242, 0
	v_cndmask_b32_e64 v72, v72, v175, s[84:85]
	v_cndmask_b32_e64 v71, v71, v175, s[82:83]
	s_movk_i32 s83, 0x6000
	v_cndmask_b32_e64 v70, v70, v175, s[80:81]
	v_cndmask_b32_e64 v77, v77, v175, s[78:79]
	v_cndmask_b32_e64 v76, v76, v175, s[76:77]
	v_cndmask_b32_e64 v75, v75, v175, s[74:75]
	v_cndmask_b32_e64 v74, v74, v175, s[72:73]
	v_cndmask_b32_e64 v79, v79, v175, s[70:71]
	v_cndmask_b32_e64 v78, v78, v175, s[68:69]
	v_cndmask_b32_e64 v81, v81, v175, s[2:3]
	s_mov_b32 s56, s30
	v_cndmask_b32_e64 v83, v83, v175, s[0:1]
	v_cndmask_b32_e32 v82, v82, v175, vcc
	v_readlane_b32 s87, v242, 1
.LBB0_666:
	v_max_f32_e32 v96, v81, v81
	v_max_f32_e32 v97, v80, v80
	v_max_f32_e32 v96, v97, v96
	v_max3_f32 v96, v96, v78, v79
	v_max3_f32 v96, v96, v74, v75
	v_max3_f32 v96, v96, v76, v77
	v_max3_f32 v96, v96, v70, v71
	v_max3_f32 v96, v96, v72, v73
	v_max3_f32 v96, v96, v66, v67
	v_max3_f32 v96, v96, v68, v69
	v_max3_f32 v96, v96, v82, v83
	v_max3_f32 v96, v96, v84, v85
	v_max3_f32 v96, v96, v98, v99
	v_max3_f32 v96, v96, v88, v89
	v_max3_f32 v96, v96, v90, v91
	v_max3_f32 v96, v96, v92, v93
	v_max3_f32 v96, v96, v94, v95
	v_max3_f32 v96, v96, v86, v87
	v_mov_b32_e32 v97, v96
	s_nop 1
	v_permlane32_swap_b32_e32 v96, v97
	v_max_f32_e32 v97, v97, v97
	v_max_f32_e32 v96, v96, v96
	v_max_f32_e32 v96, v96, v97
	v_sub_f32_e32 v97, v96, v196
	v_cmp_ge_f32_e32 vcc, s24, v97
	v_max_f32_e32 v97, v196, v196
	v_max_f32_e32 v97, v97, v96
	v_sub_f32_e32 v96, v196, v97
	v_exp_f32_e32 v96, v96
	s_cmp_eq_u64 vcc, exec
	s_cselect_b64 s[40:41], -1, 0
	v_readlane_b32 s25, v243, 63
	v_cndmask_b32_e64 v96, v96, 1.0, s[40:41]
	v_cmp_gt_f32_e32 vcc, 1.0, v96
	s_cbranch_vccz .LBB0_670
	s_and_saveexec_b64 s[0:1], s[38:39]
	ds_write_b32 v185, v96 offset:128
	s_or_b64 exec, exec, s[0:1]
	s_waitcnt lgkmcnt(0)
	ds_read_b128 v[100:103], v184 offset:224
	ds_read_b128 v[104:107], v184 offset:192
	ds_read_b128 v[108:111], v184 offset:160
	ds_read_b128 v[116:119], v184 offset:128
	s_waitcnt lgkmcnt(3)
	v_mul_f32 v64, v64, v102
	v_mul_f32 v65, v65, v103
	s_waitcnt lgkmcnt(2)
	v_mul_f32 v60, v60, v106
	v_mul_f32 v61, v61, v107
	s_waitcnt lgkmcnt(1)
	v_mul_f32 v56, v56, v110
	v_mul_f32 v57, v57, v111
	s_waitcnt lgkmcnt(0)
	v_mul_f32 v52, v52, v118
	v_mul_f32 v53, v53, v119
	v_mul_f32 v62, v62, v100
	v_mul_f32 v63, v63, v101
	v_mul_f32 v58, v58, v104
	v_mul_f32 v59, v59, v105
	v_mul_f32 v54, v54, v108
	v_mul_f32 v55, v55, v109
	v_mul_f32 v50, v50, v116
	v_mul_f32 v51, v51, v117
	v_mul_f32 v48, v48, v102
	v_mul_f32 v49, v49, v103
	v_mul_f32 v44, v44, v106
	v_mul_f32 v45, v45, v107
	v_mul_f32 v40, v40, v110
	v_mul_f32 v41, v41, v111
	v_mul_f32 v36, v36, v118
	v_mul_f32 v37, v37, v119
	v_mul_f32 v46, v46, v100
	v_mul_f32 v47, v47, v101
	v_mul_f32 v42, v42, v104
	v_mul_f32 v43, v43, v105
	v_mul_f32 v38, v38, v108
	v_mul_f32 v39, v39, v109
	v_mul_f32 v34, v34, v116
	v_mul_f32 v35, v35, v117
	v_mul_f32 v32, v32, v102
	v_mul_f32 v33, v33, v103
	v_mul_f32 v28, v28, v106
	v_mul_f32 v29, v29, v107
	v_mul_f32 v24, v24, v110
	v_mul_f32 v25, v25, v111
	v_mul_f32 v20, v20, v118
	v_mul_f32 v21, v21, v119
	v_mul_f32 v30, v30, v100
	v_mul_f32 v31, v31, v101
	v_mul_f32 v26, v26, v104
	v_mul_f32 v27, v27, v105
	v_mul_f32 v22, v22, v108
	v_mul_f32 v23, v23, v109
	v_mul_f32 v18, v18, v116
	v_mul_f32 v19, v19, v117
	v_mul_f32 v16, v16, v102
	v_mul_f32 v17, v17, v103
	v_mul_f32 v12, v12, v106
	v_mul_f32 v13, v13, v107
	v_mul_f32 v8, v8, v110
	v_mul_f32 v9, v9, v111
	v_mul_f32 v4, v4, v118
	v_mul_f32 v5, v5, v119
	v_mul_f32 v14, v14, v100
	v_mul_f32 v15, v15, v101
	v_mul_f32 v10, v10, v104
	v_mul_f32 v11, v11, v105
	v_mul_f32 v6, v6, v108
	v_mul_f32 v7, v7, v109
	v_mul_f32 v2, v2, v116
	v_mul_f32 v3, v3, v117

.LBB0_821:
	v_and_b32_e32 v149, 63, v150
	v_lshlrev_b32_e32 v53, 4, v149
	v_lshlrev_b32_e32 v51, 3, v149
	v_and_b32_e32 v53, 0xc0, v53
	v_lshlrev_b32_e32 v54, 1, v149
	v_and_or_b32 v53, v51, 24, v53
	v_and_b32_e32 v54, 32, v54
	v_and_b32_e32 v51, 0x100, v51
	v_or3_b32 v51, v53, v54, v51
	v_add_u32_e32 v153, 0, v51
	v_max_f32_e32 v51, v19, v19
	v_max_f32_e32 v53, v18, v18
	v_max_f32_e32 v51, v53, v51
	v_max3_f32 v51, v51, v20, v21
	v_max3_f32 v51, v51, v22, v23
	v_max3_f32 v51, v51, v24, v25
	v_max3_f32 v51, v51, v26, v27
	v_max3_f32 v51, v51, v28, v29
	v_max3_f32 v51, v51, v30, v31
	v_max3_f32 v51, v51, v32, v33
	v_max3_f32 v51, v51, v2, v3
	v_max3_f32 v51, v51, v4, v5
	v_max3_f32 v51, v51, v6, v7
	v_max3_f32 v51, v51, v8, v9
	v_max3_f32 v51, v51, v10, v11
	v_max3_f32 v51, v51, v12, v13
	v_max3_f32 v51, v51, v14, v15
	v_max3_f32 v51, v51, v16, v17
	v_mov_b32_e32 v53, v51
	s_nop 1
	v_permlane32_swap_b32_e32 v51, v53
	s_lshl_b32 s0, s8, 2
	v_max_f32_e32 v53, v53, v53
	v_max_f32_e32 v51, v51, v51
	s_sub_i32 s27, 32, s0
	s_and_b32 s0, s13, 0x3fffffc0
	v_max_f32_e32 v51, v51, v53
	s_lshl_b32 s0, s0, 2
	v_add_f32_e32 v53, 0x7149f2ca, v51
	s_add_i32 s0, s0, 0
	v_mul_f32_e32 v53, 0x3e38aa3b, v53
	s_add_i32 s0, s0, 0x10000
	v_cmp_ge_f32_e32 vcc, s24, v53
	s_cmp_eq_u64 vcc, exec
	v_max_f32_e32 v51, 0xf149f2ca, v51
	s_cselect_b64 vcc, -1, 0
	v_cndmask_b32_e32 v168, v51, v177, vcc
	v_sub_f32_e32 v53, 0xf149f2ca, v51
	v_mul_f32_e32 v54, 0xbe38aa3b, v168
	v_mul_f32_e32 v53, 0x3e38aa3b, v53
	v_mov_b32_e32 v51, v54
	v_exp_f32_e32 v53, v53
	v_fmamk_f32 v18, v18, 0x3e38aa3b, v54
	v_fmamk_f32 v19, v19, 0x3e38aa3b, v54
	v_fmamk_f32 v20, v20, 0x3e38aa3b, v54
	v_fmamk_f32 v21, v21, 0x3e38aa3b, v54
	v_fmamk_f32 v22, v22, 0x3e38aa3b, v54
	v_fmamk_f32 v23, v23, 0x3e38aa3b, v54
	v_fmamk_f32 v24, v24, 0x3e38aa3b, v54
	v_fmamk_f32 v25, v25, 0x3e38aa3b, v54
	v_fmamk_f32 v26, v26, 0x3e38aa3b, v54
	v_fmamk_f32 v27, v27, 0x3e38aa3b, v54
	v_fmamk_f32 v28, v28, 0x3e38aa3b, v54
	v_fmamk_f32 v29, v29, 0x3e38aa3b, v54
	v_fmamk_f32 v30, v30, 0x3e38aa3b, v54
	v_fmamk_f32 v31, v31, 0x3e38aa3b, v54
	v_fmamk_f32 v32, v32, 0x3e38aa3b, v54
	v_fmac_f32_e32 v51, 0x3e38aa3b, v33
	v_exp_f32_e32 v197, v18
	v_exp_f32_e32 v199, v19
	v_exp_f32_e32 v195, v20
	v_exp_f32_e32 v198, v21
	v_exp_f32_e32 v193, v22
	v_exp_f32_e32 v196, v23
	v_exp_f32_e32 v192, v24
	v_exp_f32_e32 v194, v25
	v_exp_f32_e32 v189, v26
	v_exp_f32_e32 v191, v27
	v_exp_f32_e32 v187, v28
	v_exp_f32_e32 v190, v29
	v_exp_f32_e32 v185, v30
	v_exp_f32_e32 v188, v31
	v_exp_f32_e32 v184, v32
	v_exp_f32_e32 v186, v51
	v_cndmask_b32_e64 v167, v53, 1.0, vcc
	v_fma_f32 v132, v16, s10, v54
	v_fma_f32 v133, v17, s10, v54
	v_fma_f32 v134, v14, s10, v54
	v_fma_f32 v135, v15, s10, v54
	v_fma_f32 v136, v12, s10, v54
	v_fma_f32 v137, v13, s10, v54
	v_fma_f32 v138, v10, s10, v54
	v_fma_f32 v139, v11, s10, v54
	v_fma_f32 v140, v8, s10, v54
	v_fma_f32 v141, v9, s10, v54
	v_fma_f32 v142, v6, s10, v54
	v_fma_f32 v143, v7, s10, v54
	v_fma_f32 v144, v4, s10, v54
	v_fma_f32 v145, v5, s10, v54
	v_fma_f32 v146, v2, s10, v54
	v_fma_f32 v147, v3, s10, v54
	v_mov_b32_e32 v17, 0
	s_cmp_lt_i32 s27, 3
	v_cmp_gt_u32_e64 s[38:39], 32, v149
	v_lshl_add_u32 v155, v151, 2, s0
	v_lshl_add_u32 v154, v52, 2, s0
	s_mov_b32 s26, 0x2aaaaaab
	s_waitcnt vmcnt(1)
	ds_write_b128 v164, v[42:45] offset:49152
	s_waitcnt vmcnt(0)
	ds_write_b128 v164, v[46:49] offset:57344
	ds_write_b128 v165, v[34:37] offset:16384
	ds_write_b128 v166, v[38:41] offset:16384
	s_waitcnt lgkmcnt(0)
	s_barrier
	s_cbranch_scc1 .LBB0_841
	s_lshl_b32 s0, s9, 8
	s_add_i32 s0, s0, s34
	s_addk_i32 s0, 0x680
	v_add_u32_e32 v2, s0, v151
	v_mov_b32_e32 v51, v163
	v_sub_u32_e32 v2, v2, v52
	s_lshl_b32 s0, s11, 8
	v_mov_b32_e32 v157, 0
	v_lshl_add_u64 v[130:131], s[22:23], 0, v[50:51]
	s_mov_b32 s8, 2
	v_subrev_u32_e32 v169, s0, v2
	s_movk_i32 s9, 0x7f
	v_mov_b32_e32 v50, 0
	v_mov_b32_e32 v51, v157
	v_mov_b32_e32 v52, v157
	v_mov_b32_e32 v53, v157
	v_mov_b32_e32 v54, v157
	v_mov_b32_e32 v55, v157
	v_mov_b32_e32 v56, v157
	v_mov_b32_e32 v57, v157
	v_mov_b32_e32 v58, v157
	v_mov_b32_e32 v59, v157
	v_mov_b32_e32 v60, v157
	v_mov_b32_e32 v61, v157
	v_mov_b32_e32 v62, v157
	v_mov_b32_e32 v63, v157
	v_mov_b32_e32 v64, v157
	v_mov_b32_e32 v65, v157
	v_mov_b32_e32 v34, 0
	v_mov_b32_e32 v35, v157
	v_mov_b32_e32 v36, v157
	v_mov_b32_e32 v37, v157
	v_mov_b32_e32 v38, v157
	v_mov_b32_e32 v39, v157
	v_mov_b32_e32 v40, v157
	v_mov_b32_e32 v41, v157
	v_mov_b32_e32 v42, v157
	v_mov_b32_e32 v43, v157
	v_mov_b32_e32 v44, v157
	v_mov_b32_e32 v45, v157
	v_mov_b32_e32 v46, v157
	v_mov_b32_e32 v47, v157
	v_mov_b32_e32 v48, v157
	v_mov_b32_e32 v49, v157
	v_mov_b32_e32 v18, 0
	v_mov_b32_e32 v19, v157
	v_mov_b32_e32 v20, v157
	v_mov_b32_e32 v21, v157
	v_mov_b32_e32 v22, v157
	v_mov_b32_e32 v23, v157
	v_mov_b32_e32 v24, v157
	v_mov_b32_e32 v25, v157
	v_mov_b32_e32 v26, v157
	v_mov_b32_e32 v27, v157
	v_mov_b32_e32 v28, v157
	v_mov_b32_e32 v29, v157
	v_mov_b32_e32 v30, v157
	v_mov_b32_e32 v31, v157
	v_mov_b32_e32 v32, v157
	v_mov_b32_e32 v33, v157
	v_mov_b32_e32 v2, 0
	v_mov_b32_e32 v3, v157
	v_mov_b32_e32 v4, v157
	v_mov_b32_e32 v5, v157
	v_mov_b32_e32 v6, v157
	v_mov_b32_e32 v7, v157
	v_mov_b32_e32 v8, v157
	v_mov_b32_e32 v9, v157
	v_mov_b32_e32 v10, v157
	v_mov_b32_e32 v11, v157
	v_mov_b32_e32 v12, v157
	v_mov_b32_e32 v13, v157
	v_mov_b32_e32 v14, v157
	v_mov_b32_e32 v15, v157
	v_mov_b32_e32 v16, v157
	v_mov_b32_e32 v17, v157

.LBB0_825:
	v_max_f32_e32 v132, v83, v83
	v_max_f32_e32 v133, v82, v82
	v_max_f32_e32 v132, v133, v132
	v_max3_f32 v132, v132, v84, v85
	v_max3_f32 v132, v132, v86, v87
	v_max3_f32 v132, v132, v88, v89
	v_max3_f32 v132, v132, v90, v91
	v_max3_f32 v132, v132, v92, v93
	v_max3_f32 v132, v132, v94, v95
	v_max3_f32 v132, v132, v96, v97
	v_max3_f32 v132, v132, v66, v67
	v_max3_f32 v132, v132, v68, v69
	v_max3_f32 v132, v132, v70, v71
	v_max3_f32 v132, v132, v72, v73
	v_max3_f32 v132, v132, v74, v75
	v_max3_f32 v132, v132, v76, v77
	v_max3_f32 v132, v132, v78, v79
	v_max3_f32 v132, v132, v80, v81
	v_mov_b32_e32 v133, v132
	s_nop 1
	v_permlane32_swap_b32_e32 v132, v133
	v_max_f32_e32 v133, v133, v133
	v_max_f32_e32 v132, v132, v132
	v_max_f32_e32 v132, v132, v133
	v_sub_f32_e32 v133, v132, v168
	v_mul_f32_e32 v133, 0x3e38aa3b, v133
	v_cmp_ge_f32_e32 vcc, s24, v133
	v_max_f32_e32 v133, v168, v168
	v_max_f32_e32 v132, v133, v132
	v_sub_f32_e32 v133, v168, v132
	v_mul_f32_e32 v133, 0x3e38aa3b, v133
	v_exp_f32_e32 v133, v133
	s_cmp_eq_u64 vcc, exec
	s_cselect_b64 s[40:41], -1, 0
	v_cndmask_b32_e64 v181, v133, 1.0, s[40:41]
	v_cmp_gt_f32_e32 vcc, 1.0, v181
	s_barrier
	s_waitcnt vmcnt(2)
	ds_write_b128 v164, v[122:125] offset:32768
	s_waitcnt vmcnt(0)
	ds_write_b128 v164, v[126:129] offset:40960
	ds_write_b128 v165, v[114:117]
	ds_write_b128 v166, v[118:121]
	s_cbranch_vccz .LBB0_829
	s_and_saveexec_b64 s[0:1], s[38:39]
	ds_write_b32 v155, v181 offset:128
	s_or_b64 exec, exec, s[0:1]
	s_waitcnt lgkmcnt(0)
	ds_read_b128 v[134:137], v154 offset:224
	ds_read_b128 v[138:141], v154 offset:192
	ds_read_b128 v[142:145], v154 offset:160
	ds_read_b128 v[184:187], v154 offset:128
	s_waitcnt lgkmcnt(3)
	v_mul_f32 v64, v64, v136
	v_mul_f32 v65, v65, v137
	s_waitcnt lgkmcnt(2)
	v_mul_f32 v60, v60, v140
	v_mul_f32 v61, v61, v141
	s_waitcnt lgkmcnt(1)
	v_mul_f32 v56, v56, v144
	v_mul_f32 v57, v57, v145
	s_waitcnt lgkmcnt(0)
	v_mul_f32 v52, v52, v186
	v_mul_f32 v53, v53, v187
	v_mul_f32 v62, v62, v134
	v_mul_f32 v63, v63, v135
	v_mul_f32 v58, v58, v138
	v_mul_f32 v59, v59, v139
	v_mul_f32 v54, v54, v142
	v_mul_f32 v55, v55, v143
	v_mul_f32 v50, v50, v184
	v_mul_f32 v51, v51, v185
	v_mul_f32 v48, v48, v136
	v_mul_f32 v49, v49, v137
	v_mul_f32 v44, v44, v140
	v_mul_f32 v45, v45, v141
	v_mul_f32 v40, v40, v144
	v_mul_f32 v41, v41, v145
	v_mul_f32 v36, v36, v186
	v_mul_f32 v37, v37, v187
	v_mul_f32 v46, v46, v134
	v_mul_f32 v47, v47, v135
	v_mul_f32 v42, v42, v138
	v_mul_f32 v43, v43, v139
	v_mul_f32 v38, v38, v142
	v_mul_f32 v39, v39, v143
	v_mul_f32 v34, v34, v184
	v_mul_f32 v35, v35, v185
	v_mul_f32 v32, v32, v136
	v_mul_f32 v33, v33, v137
	v_mul_f32 v28, v28, v140
	v_mul_f32 v29, v29, v141
	v_mul_f32 v24, v24, v144
	v_mul_f32 v25, v25, v145
	v_mul_f32 v20, v20, v186
	v_mul_f32 v21, v21, v187
	v_mul_f32 v30, v30, v134
	v_mul_f32 v31, v31, v135
	v_mul_f32 v26, v26, v138
	v_mul_f32 v27, v27, v139
	v_mul_f32 v22, v22, v142
	v_mul_f32 v23, v23, v143
	v_mul_f32 v18, v18, v184
	v_mul_f32 v19, v19, v185
	v_mul_f32 v16, v16, v136
	v_mul_f32 v17, v17, v137
	v_mul_f32 v12, v12, v140
	v_mul_f32 v13, v13, v141
	v_mul_f32 v8, v8, v144
	v_mul_f32 v9, v9, v145
	v_mul_f32 v4, v4, v186
	v_mul_f32 v5, v5, v187
	v_mul_f32 v14, v14, v134
	v_mul_f32 v15, v15, v135
	v_mul_f32 v10, v10, v138
	v_mul_f32 v11, v11, v139
	v_mul_f32 v6, v6, v142
	v_mul_f32 v7, v7, v143
	v_mul_f32 v2, v2, v184
	v_mul_f32 v3, v3, v185

.LBB0_835:
	s_waitcnt vmcnt(3)
	v_max_f32_e32 v114, v132, v132
	v_max_f32_e32 v115, v114, v133
	v_sub_f32_e32 v114, v132, v115
	v_mul_f32_e32 v114, 0x3e38aa3b, v114
	v_exp_f32_e32 v114, v114
	s_nop 0
	v_cndmask_b32_e64 v114, v114, 1.0, s[40:41]
	v_cmp_gt_f32_e32 vcc, 1.0, v114
	s_cbranch_vccz .LBB0_839
	s_and_saveexec_b64 s[0:1], s[38:39]
	ds_write_b32 v155, v114 offset:128
	s_or_b64 exec, exec, s[0:1]
	s_waitcnt lgkmcnt(0)
	s_waitcnt vmcnt(1)
	ds_read_b128 v[116:119], v154 offset:224
	ds_read_b128 v[120:123], v154 offset:192
	s_waitcnt vmcnt(0)
	ds_read_b128 v[124:127], v154 offset:160
	ds_read_b128 v[134:137], v154 offset:128
	s_waitcnt lgkmcnt(3)
	v_mul_f32 v64, v64, v118
	v_mul_f32 v65, v65, v119
	s_waitcnt lgkmcnt(2)
	v_mul_f32 v60, v60, v122
	v_mul_f32 v61, v61, v123
	s_waitcnt lgkmcnt(1)
	v_mul_f32 v56, v56, v126
	v_mul_f32 v57, v57, v127
	s_waitcnt lgkmcnt(0)
	v_mul_f32 v52, v52, v136
	v_mul_f32 v53, v53, v137
	v_mul_f32 v62, v62, v116
	v_mul_f32 v63, v63, v117
	v_mul_f32 v58, v58, v120
	v_mul_f32 v59, v59, v121
	v_mul_f32 v54, v54, v124
	v_mul_f32 v55, v55, v125
	v_mul_f32 v50, v50, v134
	v_mul_f32 v51, v51, v135
	v_mul_f32 v48, v48, v118
	v_mul_f32 v49, v49, v119
	v_mul_f32 v44, v44, v122
	v_mul_f32 v45, v45, v123
	v_mul_f32 v40, v40, v126
	v_mul_f32 v41, v41, v127
	v_mul_f32 v36, v36, v136
	v_mul_f32 v37, v37, v137
	v_mul_f32 v46, v46, v116
	v_mul_f32 v47, v47, v117
	v_mul_f32 v42, v42, v120
	v_mul_f32 v43, v43, v121
	v_mul_f32 v38, v38, v124
	v_mul_f32 v39, v39, v125
	v_mul_f32 v34, v34, v134
	v_mul_f32 v35, v35, v135
	v_mul_f32 v32, v32, v118
	v_mul_f32 v33, v33, v119
	v_mul_f32 v28, v28, v122
	v_mul_f32 v29, v29, v123
	v_mul_f32 v24, v24, v126
	v_mul_f32 v25, v25, v127
	v_mul_f32 v20, v20, v136
	v_mul_f32 v21, v21, v137
	v_mul_f32 v30, v30, v116
	v_mul_f32 v31, v31, v117
	v_mul_f32 v26, v26, v120
	v_mul_f32 v27, v27, v121
	v_mul_f32 v22, v22, v124
	v_mul_f32 v23, v23, v125
	v_mul_f32 v18, v18, v134
	v_mul_f32 v19, v19, v135
	v_mul_f32 v16, v16, v118
	v_mul_f32 v17, v17, v119
	v_mul_f32 v12, v12, v122
	v_mul_f32 v13, v13, v123
	v_mul_f32 v8, v8, v126
	v_mul_f32 v9, v9, v127
	v_mul_f32 v4, v4, v136
	v_mul_f32 v5, v5, v137
	v_mul_f32 v14, v14, v116
	v_mul_f32 v15, v15, v117
	v_mul_f32 v10, v10, v120
	v_mul_f32 v11, v11, v121
	v_mul_f32 v6, v6, v124
	v_mul_f32 v7, v7, v125
	v_mul_f32 v2, v2, v134
	v_mul_f32 v3, v3, v135
.LBB0_839:
	v_cndmask_b32_e64 v168, v115, v132, s[40:41]
	v_mul_f32_e32 v116, 0xbe38aa3b, v168
	v_mov_b32_e32 v115, v116
	v_fmamk_f32 v82, v82, 0x3e38aa3b, v116
	v_fmamk_f32 v83, v83, 0x3e38aa3b, v116
	v_fmamk_f32 v84, v84, 0x3e38aa3b, v116
	v_fmamk_f32 v85, v85, 0x3e38aa3b, v116
	v_fmamk_f32 v86, v86, 0x3e38aa3b, v116
	v_fmamk_f32 v87, v87, 0x3e38aa3b, v116
	v_fmamk_f32 v88, v88, 0x3e38aa3b, v116
	v_fmamk_f32 v89, v89, 0x3e38aa3b, v116
	v_fmamk_f32 v90, v90, 0x3e38aa3b, v116
	v_fmamk_f32 v91, v91, 0x3e38aa3b, v116
	v_fmamk_f32 v92, v92, 0x3e38aa3b, v116
	v_fmamk_f32 v93, v93, 0x3e38aa3b, v116
	v_fmamk_f32 v94, v94, 0x3e38aa3b, v116
	v_fmamk_f32 v95, v95, 0x3e38aa3b, v116
	v_fmamk_f32 v96, v96, 0x3e38aa3b, v116
	v_fmac_f32_e32 v115, 0x3e38aa3b, v97
	v_exp_f32_e32 v197, v82
	v_exp_f32_e32 v199, v83
	v_exp_f32_e32 v195, v84
	v_exp_f32_e32 v198, v85
	v_exp_f32_e32 v193, v86
	v_exp_f32_e32 v196, v87
	v_exp_f32_e32 v192, v88
	v_exp_f32_e32 v194, v89
	v_exp_f32_e32 v189, v90
	v_exp_f32_e32 v191, v91
	v_exp_f32_e32 v187, v92
	v_exp_f32_e32 v190, v93
	v_exp_f32_e32 v185, v94
	v_exp_f32_e32 v188, v95
	v_exp_f32_e32 v184, v96
	v_exp_f32_e32 v186, v115
	v_fma_f32 v146, v66, s10, v116
	v_fma_f32 v147, v67, s10, v116
	v_add_f32_e32 v66, v179, v180
	v_fmac_f32_e32 v66, v167, v157
	v_add_f32_e32 v157, v182, v183
	s_addk_i32 s9, 0x80
	s_add_i32 s8, s8, 2
	v_fma_f32 v132, v80, s10, v116
	v_fma_f32 v133, v81, s10, v116
	v_fma_f32 v134, v78, s10, v116
	v_fma_f32 v135, v79, s10, v116
	v_fma_f32 v136, v76, s10, v116
	v_fma_f32 v137, v77, s10, v116
	v_fma_f32 v138, v74, s10, v116
	v_fma_f32 v139, v75, s10, v116
	v_fma_f32 v140, v72, s10, v116
	v_fma_f32 v141, v73, s10, v116
	v_fma_f32 v142, v70, s10, v116
	v_fma_f32 v143, v71, s10, v116
	v_fma_f32 v144, v68, s10, v116
	v_fma_f32 v145, v69, s10, v116
	v_fmac_f32_e32 v157, v66, v181
	s_cmp_ge_i32 s8, s27
	v_add_u32_e32 v169, 0xffffff80, v169
	s_waitcnt lgkmcnt(0)
	s_barrier
	s_cbranch_scc1 .LBB0_842
	v_mov_b32_e32 v167, v114
	s_branch .LBB0_823

.LBB0_844:
	v_max_f32_e32 v100, v83, v83
	v_max_f32_e32 v101, v82, v82
	v_max_f32_e32 v100, v101, v100
	v_max3_f32 v100, v100, v84, v85
	v_max3_f32 v100, v100, v86, v87
	v_max3_f32 v100, v100, v88, v89
	v_max3_f32 v100, v100, v90, v91
	v_max3_f32 v100, v100, v92, v93
	v_max3_f32 v100, v100, v94, v95
	v_max3_f32 v100, v100, v96, v97
	v_max3_f32 v100, v100, v66, v67
	v_max3_f32 v100, v100, v68, v69
	v_max3_f32 v100, v100, v70, v71
	v_max3_f32 v100, v100, v72, v73
	v_max3_f32 v100, v100, v74, v75
	v_max3_f32 v100, v100, v76, v77
	v_max3_f32 v100, v100, v78, v79
	v_max3_f32 v100, v100, v80, v81
	v_mov_b32_e32 v101, v100
	s_nop 1
	v_permlane32_swap_b32_e32 v100, v101
	v_max_f32_e32 v101, v101, v101
	v_max_f32_e32 v100, v100, v100
	v_max_f32_e32 v100, v100, v101
	v_sub_f32_e32 v101, v100, v168
	v_mul_f32_e32 v101, 0x3e38aa3b, v101
	v_cmp_ge_f32_e32 vcc, s24, v101
	v_max_f32_e32 v101, v168, v168
	v_max_f32_e32 v101, v101, v100
	v_sub_f32_e32 v100, v168, v101
	v_mul_f32_e32 v100, 0x3e38aa3b, v100
	v_exp_f32_e32 v100, v100
	s_cmp_eq_u64 vcc, exec
	s_cselect_b64 s[38:39], -1, 0
	v_readlane_b32 s88, v242, 2
	v_cndmask_b32_e64 v100, v100, 1.0, s[38:39]
	v_readlane_b32 s25, v243, 63
	v_readlane_b32 s86, v242, 0
	v_readlane_b32 s89, v242, 3
	s_mov_b64 s[90:91], s[16:17]
	s_movk_i32 s83, 0x6000
	s_mov_b32 s92, 0xf800000
	s_movk_i32 s93, 0x6018
	s_mov_b32 s56, s30
	v_cmp_gt_f32_e32 vcc, 1.0, v100
	v_readlane_b32 s87, v242, 1
	s_cbranch_vccz .LBB0_848
	v_cmp_gt_u32_e32 vcc, 32, v149
	s_and_saveexec_b64 s[0:1], vcc
	ds_write_b32 v155, v100 offset:128
	s_or_b64 exec, exec, s[0:1]
	s_waitcnt lgkmcnt(0)
	ds_read_b128 v[102:105], v154 offset:224
	ds_read_b128 v[106:109], v154 offset:192
	ds_read_b128 v[110:113], v154 offset:160
	ds_read_b128 v[116:119], v154 offset:128
	s_waitcnt lgkmcnt(3)
	v_mul_f32 v64, v64, v104
	v_mul_f32 v65, v65, v105
	s_waitcnt lgkmcnt(2)
	v_mul_f32 v60, v60, v108
	v_mul_f32 v61, v61, v109
	s_waitcnt lgkmcnt(1)
	v_mul_f32 v56, v56, v112
	v_mul_f32 v57, v57, v113
	s_waitcnt lgkmcnt(0)
	v_mul_f32 v52, v52, v118
	v_mul_f32 v53, v53, v119
	v_mul_f32 v62, v62, v102
	v_mul_f32 v63, v63, v103
	v_mul_f32 v58, v58, v106
	v_mul_f32 v59, v59, v107
	v_mul_f32 v54, v54, v110
	v_mul_f32 v55, v55, v111
	v_mul_f32 v50, v50, v116
	v_mul_f32 v51, v51, v117
	v_mul_f32 v48, v48, v104
	v_mul_f32 v49, v49, v105
	v_mul_f32 v44, v44, v108
	v_mul_f32 v45, v45, v109
	v_mul_f32 v40, v40, v112
	v_mul_f32 v41, v41, v113
	v_mul_f32 v36, v36, v118
	v_mul_f32 v37, v37, v119
	v_mul_f32 v46, v46, v102
	v_mul_f32 v47, v47, v103
	v_mul_f32 v42, v42, v106
	v_mul_f32 v43, v43, v107
	v_mul_f32 v38, v38, v110
	v_mul_f32 v39, v39, v111
	v_mul_f32 v34, v34, v116
	v_mul_f32 v35, v35, v117
	v_mul_f32 v32, v32, v104
	v_mul_f32 v33, v33, v105
	v_mul_f32 v28, v28, v108
	v_mul_f32 v29, v29, v109
	v_mul_f32 v24, v24, v112
	v_mul_f32 v25, v25, v113
	v_mul_f32 v20, v20, v118
	v_mul_f32 v21, v21, v119
	v_mul_f32 v30, v30, v102
	v_mul_f32 v31, v31, v103
	v_mul_f32 v26, v26, v106
	v_mul_f32 v27, v27, v107
	v_mul_f32 v22, v22, v110
	v_mul_f32 v23, v23, v111
	v_mul_f32 v18, v18, v116
	v_mul_f32 v19, v19, v117
	v_mul_f32 v16, v16, v104
	v_mul_f32 v17, v17, v105
	v_mul_f32 v12, v12, v108
	v_mul_f32 v13, v13, v109
	v_mul_f32 v8, v8, v112
	v_mul_f32 v9, v9, v113
	v_mul_f32 v4, v4, v118
	v_mul_f32 v5, v5, v119
	v_mul_f32 v14, v14, v102
	v_mul_f32 v15, v15, v103
	v_mul_f32 v10, v10, v106
	v_mul_f32 v11, v11, v107
	v_mul_f32 v6, v6, v110
	v_mul_f32 v7, v7, v111
	v_mul_f32 v2, v2, v116
	v_mul_f32 v3, v3, v117

.LBB0_1414:
	s_ashr_i32 s4, s34, 5
	v_readlane_b32 s0, v243, 52
	s_add_i32 s0, s4, s0
	s_ashr_i32 s1, s0, 31
	s_and_b32 s2, s29, 0xe0000
	s_lshl_b64 s[0:1], s[0:1], 20
	s_or_b32 s0, s0, s2
	s_lshl_b64 s[0:1], s[0:1], 1
	v_readlane_b32 s2, v245, 20
	s_add_u32 s2, s2, s0
	v_readlane_b32 s3, v245, 23
	s_addc_u32 s5, s3, s1
	s_and_b32 s3, s28, 0x180
	s_waitcnt vmcnt(0)
	v_mov_b32_e32 v155, v0
	s_lshl_b32 s3, s3, 1
	s_add_u32 s18, s2, s3
	v_ashrrev_i32_e32 v146, 4, v155
	v_lshlrev_b32_e32 v2, 3, v155
	v_and_b32_e32 v4, 0xfffff0, v146
	v_lshlrev_b32_e32 v5, 1, v146
	s_addc_u32 s19, s5, 0
	s_ashr_i32 s5, s4, 31
	v_and_b32_e32 v3, 0x78, v2
	v_and_or_b32 v4, v5, 8, v4
	v_lshrrev_b32_e32 v5, 1, v146
	v_and_b32_e32 v6, 3, v146
	v_add_u32_e32 v8, 32, v146
	s_lshl_b64 s[4:5], s[4:5], 19
	v_and_or_b32 v5, v5, 4, v6
	s_waitcnt vmcnt(0) lgkmcnt(0)
	v_lshlrev_b32_e32 v50, 1, v3
	v_and_b32_e32 v3, 0xfffff0, v8
	v_lshlrev_b32_e32 v6, 1, v8
	s_add_u32 s2, s22, s4
	v_and_or_b32 v3, v6, 8, v3
	s_addc_u32 s5, s23, s5
	v_lshrrev_b32_e32 v4, 1, v4
	v_bfe_u32 v2, v2, 5, 2
	v_lshrrev_b32_e32 v3, 1, v3
	s_add_u32 s4, s2, s3
	v_readfirstlane_b32 s2, v155
	v_or_b32_e32 v4, v4, v2
	v_or_b32_e32 v2, v3, v2
	s_addc_u32 s5, s5, 0
	s_ashr_i32 s35, s2, 6
	v_and_b32_e32 v1, 63, v155
	s_and_b32 s2, s2, 0x3fffffc0
	v_lshlrev_b32_e32 v6, 9, v2
	v_lshlrev_b32_e32 v2, 8, v146
	v_and_b32_e32 v3, 0x70, v155
	v_lshlrev_b32_e32 v154, 4, v155
	s_lshl_b32 s2, s2, 2
	v_bitop3_b32 v20, v50, v2, v3 bitop3:0xde
	v_lshlrev_b32_e32 v2, 3, v1
	v_and_b32_e32 v3, 0xc0, v154
	v_lshlrev_b32_e32 v7, 1, v155
	v_and_b32_e32 v156, 31, v155
	s_add_i32 s42, s2, 0
	v_and_or_b32 v3, v2, 24, v3
	v_and_b32_e32 v7, 32, v7
	v_and_b32_e32 v2, 0x100, v2
	s_lshl_b32 s2, s35, 5
	v_or3_b32 v7, v3, v7, v2
	v_or_b32_e32 v2, s2, v156
	v_ashrrev_i32_e32 v3, 31, v2
	v_bfe_u32 v157, v155, 5, 1
	v_lshlrev_b64 v[2:3], 10, v[2:3]
	v_lshl_add_u64 v[2:3], s[18:19], 0, v[2:3]
	v_lshlrev_b32_e32 v162, 4, v157
	v_lshl_add_u64 v[2:3], v[2:3], 0, v[162:163]
	v_ashrrev_i32_e32 v147, 31, v146
	v_ashrrev_i32_e32 v9, 31, v8
	v_lshlrev_b32_e32 v4, 9, v4
	v_lshlrev_b32_e32 v5, 6, v5
	global_load_dwordx4 v[126:129], v[2:3], off
	global_load_dwordx4 v[122:125], v[2:3], off offset:32
	global_load_dwordx4 v[118:121], v[2:3], off offset:64
	global_load_dwordx4 v[114:117], v[2:3], off offset:96
	global_load_dwordx4 v[110:113], v[2:3], off offset:128
	global_load_dwordx4 v[106:109], v[2:3], off offset:160
	global_load_dwordx4 v[102:105], v[2:3], off offset:192
	global_load_dwordx4 v[98:101], v[2:3], off offset:224
	v_and_b32_e32 v2, 48, v50
	v_lshlrev_b64 v[52:53], 11, v[146:147]
	v_lshlrev_b64 v[8:9], 11, v[8:9]
	v_or3_b32 v21, v4, v5, v2
	v_or3_b32 v22, v6, v5, v2
	v_mov_b32_e32 v51, v163
	v_lshl_add_u64 v[2:3], s[4:5], 0, v[52:53]
	v_lshl_add_u64 v[8:9], s[4:5], 0, v[8:9]
	v_lshl_add_u64 v[2:3], v[2:3], 0, v[50:51]
	v_lshl_add_u64 v[16:17], v[8:9], 0, v[50:51]
	v_add_u32_e32 v158, 0, v7
	global_load_dwordx4 v[4:7], v[2:3], off offset:1024
	global_load_dwordx4 v[8:11], v[16:17], off offset:1024
	global_load_dwordx4 v[12:15], v[2:3], off
	s_nop 0
	global_load_dwordx4 v[16:19], v[16:17], off
	v_add_u32_e32 v165, 0, v20
	v_add_u32_e32 v166, 0, v21
	s_mov_b64 s[8:9], 0x20000
	v_add_u32_e32 v167, 0, v22
	s_add_i32 s42, s42, 0x10000
	s_waitcnt vmcnt(1)
	ds_write_b128 v165, v[12:15] offset:32768
	s_waitcnt vmcnt(0)
	ds_write_b128 v165, v[16:19] offset:40960
	ds_write_b128 v166, v[4:7]
	v_lshl_add_u64 v[4:5], v[2:3], 0, s[8:9]
	s_mov_b64 s[8:9], 0x30000
	ds_write_b128 v167, v[8:11]
	s_waitcnt lgkmcnt(0)
	s_barrier
	global_load_dwordx4 v[34:37], v[4:5], off offset:1024
	v_lshl_add_u64 v[4:5], v[2:3], 0, s[8:9]
	s_mov_b32 s8, 0x20000
	global_load_dwordx4 v[38:41], v[4:5], off offset:1024
	v_add_co_u32_e32 v4, vcc, s8, v2
	s_mov_b32 s8, 0x30000
	s_nop 0
	v_addc_co_u32_e32 v5, vcc, 0, v3, vcc
	v_add_co_u32_e32 v2, vcc, s8, v2
	global_load_dwordx4 v[42:45], v[4:5], off
	s_nop 0
	v_addc_co_u32_e32 v3, vcc, 0, v3, vcc
	global_load_dwordx4 v[46:49], v[2:3], off
	s_movk_i32 s8, 0x70
	v_and_b32_e32 v2, 0x70, v154
	v_lshl_add_u32 v3, v156, 8, 0
	v_bitop3_b32 v4, v162, v154, s8 bitop3:0x78
	v_add_u32_e32 v168, v3, v4
	v_bitop3_b32 v4, v162, v2, 32 bitop3:0x36
	s_movk_i32 s8, 0x60
	v_add_u32_e32 v164, v3, v4
	v_bitop3_b32 v4, v162, v2, 64 bitop3:0x36
	v_bitop3_b32 v2, v162, v2, s8 bitop3:0x36
	v_add_u32_e32 v161, v3, v4
	v_add_u32_e32 v160, v3, v2
	ds_read_b128 v[2:5], v168 offset:32768
	ds_read_b128 v[18:21], v168 offset:40960
	s_waitcnt lgkmcnt(1)
	v_mfma_f32_32x32x16_bf16 v[2:17], v[2:5], v[126:129], 0
	ds_read_b128 v[54:57], v164 offset:32768
	ds_read_b128 v[58:61], v164 offset:40960
	v_lshl_add_u64 v[148:149], s[4:5], 0, v[50:51]
	s_mov_b64 s[4:5], 0x40000
	v_cmp_gt_u32_e64 s[38:39], 32, v1
	v_lshl_add_u32 v159, v156, 2, s42
	s_waitcnt lgkmcnt(2)
	v_mfma_f32_32x32x16_bf16 v[18:33], v[18:21], v[126:129], 0
	s_waitcnt lgkmcnt(1)
	v_mfma_f32_32x32x16_bf16 v[2:17], v[54:57], v[122:125], v[2:17]
	s_waitcnt lgkmcnt(0)
	v_mfma_f32_32x32x16_bf16 v[18:33], v[58:61], v[122:125], v[18:33]
	ds_read_b128 v[54:57], v161 offset:32768
	ds_read_b128 v[58:61], v161 offset:40960
	s_waitcnt lgkmcnt(1)
	v_mfma_f32_32x32x16_bf16 v[2:17], v[54:57], v[118:121], v[2:17]
	s_waitcnt lgkmcnt(0)
	v_mfma_f32_32x32x16_bf16 v[18:33], v[58:61], v[118:121], v[18:33]
	ds_read_b128 v[54:57], v160 offset:32768
	ds_read_b128 v[58:61], v160 offset:40960
	s_waitcnt lgkmcnt(1)
	v_mfma_f32_32x32x16_bf16 v[2:17], v[54:57], v[114:117], v[2:17]
	s_waitcnt lgkmcnt(0)
	v_mfma_f32_32x32x16_bf16 v[18:33], v[58:61], v[114:117], v[18:33]
	ds_read_b128 v[54:57], v168 offset:32896
	ds_read_b128 v[58:61], v168 offset:41088
	s_waitcnt lgkmcnt(1)
	v_mfma_f32_32x32x16_bf16 v[2:17], v[54:57], v[110:113], v[2:17]
	s_waitcnt lgkmcnt(0)
	v_mfma_f32_32x32x16_bf16 v[18:33], v[58:61], v[110:113], v[18:33]
	ds_read_b128 v[54:57], v164 offset:32896
	ds_read_b128 v[58:61], v164 offset:41088
	s_waitcnt lgkmcnt(1)
	v_mfma_f32_32x32x16_bf16 v[2:17], v[54:57], v[106:109], v[2:17]
	s_waitcnt lgkmcnt(0)
	v_mfma_f32_32x32x16_bf16 v[18:33], v[58:61], v[106:109], v[18:33]
	ds_read_b128 v[54:57], v161 offset:32896
	ds_read_b128 v[58:61], v161 offset:41088
	s_waitcnt lgkmcnt(1)
	v_mfma_f32_32x32x16_bf16 v[2:17], v[54:57], v[102:105], v[2:17]
	s_waitcnt lgkmcnt(0)
	v_mfma_f32_32x32x16_bf16 v[18:33], v[58:61], v[102:105], v[18:33]
	ds_read_b128 v[54:57], v160 offset:32896
	ds_read_b128 v[58:61], v160 offset:41088
	s_waitcnt vmcnt(1)
	ds_write_b128 v165, v[42:45] offset:49152
	s_waitcnt vmcnt(0)
	ds_write_b128 v165, v[46:49] offset:57344
	ds_write_b128 v166, v[34:37] offset:16384
	ds_write_b128 v167, v[38:41] offset:16384
	v_lshl_add_u64 v[34:35], v[148:149], 0, v[52:53]
	v_lshl_add_u64 v[36:37], v[34:35], 0, s[4:5]
	s_mov_b64 s[4:5], 0x50000
	s_waitcnt lgkmcnt(0)
	s_barrier
	v_mfma_f32_32x32x16_bf16 v[2:17], v[54:57], v[98:101], v[2:17]
	global_load_dwordx4 v[130:133], v[36:37], off offset:1024
	v_lshl_add_u64 v[36:37], v[34:35], 0, s[4:5]
	s_mov_b32 s4, 0x40000
	global_load_dwordx4 v[134:137], v[36:37], off offset:1024
	s_nop 7
	v_max_f32_e32 v54, v3, v3
	v_max_f32_e32 v55, v2, v2
	v_mfma_f32_32x32x16_bf16 v[18:33], v[58:61], v[98:101], v[18:33]
	v_max_f32_e32 v54, v55, v54
	v_max3_f32 v54, v54, v4, v5
	v_max3_f32 v54, v54, v6, v7
	v_max3_f32 v54, v54, v8, v9
	v_max3_f32 v54, v54, v10, v11
	v_max3_f32 v54, v54, v12, v13
	v_max3_f32 v54, v54, v14, v15
	v_max3_f32 v54, v54, v16, v17
	s_nop 3
	v_max3_f32 v54, v54, v18, v19
	v_max3_f32 v54, v54, v20, v21
	v_max3_f32 v54, v54, v22, v23
	v_max3_f32 v54, v54, v24, v25
	v_max3_f32 v54, v54, v26, v27
	v_max3_f32 v54, v54, v28, v29
	v_max3_f32 v54, v54, v30, v31
	v_max3_f32 v54, v54, v32, v33
	v_mov_b32_e32 v55, v54
	s_nop 1
	v_permlane32_swap_b32_e32 v54, v55
	v_max_f32_e32 v55, v55, v55
	v_max_f32_e32 v54, v54, v54
	v_max_f32_e32 v54, v54, v55
	v_add_f32_e32 v55, 0x7149f2ca, v54
	v_mul_f32_e32 v55, 0x3e0293ee, v55
	v_cmp_ge_f32_e32 vcc, s24, v55
	s_cmp_eq_u64 vcc, exec
	v_add_co_u32_e32 v36, vcc, s4, v34
	s_mov_b32 s4, 0x50000
	s_nop 0
	v_addc_co_u32_e32 v37, vcc, 0, v35, vcc
	v_add_co_u32_e32 v34, vcc, s4, v34
	global_load_dwordx4 v[138:141], v[36:37], off
	s_nop 0
	v_addc_co_u32_e32 v35, vcc, 0, v35, vcc
	global_load_dwordx4 v[142:145], v[34:35], off
	s_cselect_b64 s[36:37], -1, 0
	v_max_f32_e32 v151, 0xf149f2ca, v54
	v_cndmask_b32_e64 v150, v151, v177, s[36:37]
	v_mul_f32_e32 v54, 0xbe0293ee, v150
	v_fmamk_f32 v2, v2, 0x3e0293ee, v54
	v_fmamk_f32 v3, v3, 0x3e0293ee, v54
	v_fmamk_f32 v4, v4, 0x3e0293ee, v54
	v_fmamk_f32 v5, v5, 0x3e0293ee, v54
	v_fmamk_f32 v6, v6, 0x3e0293ee, v54
	v_fmamk_f32 v7, v7, 0x3e0293ee, v54
	v_fmamk_f32 v8, v8, 0x3e0293ee, v54
	v_fmamk_f32 v9, v9, 0x3e0293ee, v54
	v_fmamk_f32 v55, v10, 0x3e0293ee, v54
	v_fmamk_f32 v56, v11, 0x3e0293ee, v54
	v_fmamk_f32 v57, v12, 0x3e0293ee, v54
	v_fmamk_f32 v58, v13, 0x3e0293ee, v54
	v_fmamk_f32 v59, v14, 0x3e0293ee, v54
	v_fmamk_f32 v60, v15, 0x3e0293ee, v54
	v_fmamk_f32 v61, v16, 0x3e0293ee, v54
	v_fmamk_f32 v62, v17, 0x3e0293ee, v54
	v_exp_f32_e32 v10, v2
	v_exp_f32_e32 v11, v3
	v_exp_f32_e32 v12, v4
	v_exp_f32_e32 v13, v5
	v_exp_f32_e32 v14, v6
	v_exp_f32_e32 v15, v7
	v_exp_f32_e32 v16, v8
	v_exp_f32_e32 v17, v9
	v_exp_f32_e32 v2, v55
	v_exp_f32_e32 v3, v56
	v_exp_f32_e32 v4, v57
	v_exp_f32_e32 v5, v58
	v_exp_f32_e32 v6, v59
	v_exp_f32_e32 v7, v60
	v_exp_f32_e32 v8, v61
	v_exp_f32_e32 v9, v62
	v_fmamk_f32 v18, v18, 0x3e0293ee, v54
	v_fmamk_f32 v19, v19, 0x3e0293ee, v54
	v_fmamk_f32 v20, v20, 0x3e0293ee, v54
	v_fmamk_f32 v21, v21, 0x3e0293ee, v54
	v_fmamk_f32 v22, v22, 0x3e0293ee, v54
	v_fmamk_f32 v23, v23, 0x3e0293ee, v54
	v_fmamk_f32 v24, v24, 0x3e0293ee, v54
	v_fmamk_f32 v25, v25, 0x3e0293ee, v54
	v_fmamk_f32 v26, v26, 0x3e0293ee, v54
	v_fmamk_f32 v27, v27, 0x3e0293ee, v54
	v_fmamk_f32 v28, v28, 0x3e0293ee, v54
	v_fmamk_f32 v29, v29, 0x3e0293ee, v54
	v_fmamk_f32 v30, v30, 0x3e0293ee, v54
	v_fmamk_f32 v31, v31, 0x3e0293ee, v54
	v_fmamk_f32 v32, v32, 0x3e0293ee, v54
	v_fmac_f32_e32 v54, 0x3e0293ee, v33
	ds_read_b128 v[228:231], v168 offset:49152
	ds_read_b128 v[232:235], v168 offset:57344
	ds_read_b128 v[236:239], v164 offset:49152
	ds_read_b128 v[248:251], v164 offset:57344
	ds_read_b128 v[252:255], v161 offset:49152
	s_waitcnt lgkmcnt(4)
	v_mfma_f32_32x32x16_bf16 v[82:97], v[228:231], v[126:129], 0
	ds_read_b128 v[228:231], v161 offset:57344
	s_waitcnt lgkmcnt(4)
	v_mfma_f32_32x32x16_bf16 v[66:81], v[232:235], v[126:129], 0
	ds_read_b128 v[232:235], v160 offset:49152
	s_waitcnt lgkmcnt(4)
	v_mfma_f32_32x32x16_bf16 v[82:97], v[236:239], v[122:125], v[82:97]
	ds_read_b128 v[236:239], v160 offset:57344
	s_waitcnt lgkmcnt(4)
	v_mfma_f32_32x32x16_bf16 v[66:81], v[248:251], v[122:125], v[66:81]
	ds_read_b128 v[248:251], v168 offset:49280
	s_waitcnt lgkmcnt(4)
	v_mfma_f32_32x32x16_bf16 v[82:97], v[252:255], v[118:121], v[82:97]
	ds_read_b128 v[252:255], v168 offset:57472
	s_waitcnt lgkmcnt(4)
	v_mfma_f32_32x32x16_bf16 v[66:81], v[228:231], v[118:121], v[66:81]
	ds_read_b128 v[228:231], v164 offset:49280
	s_waitcnt lgkmcnt(4)
	v_mfma_f32_32x32x16_bf16 v[82:97], v[232:235], v[114:117], v[82:97]
	ds_read_b128 v[232:235], v164 offset:57472
	s_waitcnt lgkmcnt(4)
	v_mfma_f32_32x32x16_bf16 v[66:81], v[236:239], v[114:117], v[66:81]
	ds_read_b128 v[236:239], v161 offset:49280
	s_waitcnt lgkmcnt(4)
	v_mfma_f32_32x32x16_bf16 v[82:97], v[248:251], v[110:113], v[82:97]
	ds_read_b128 v[248:251], v161 offset:57472
	s_waitcnt lgkmcnt(4)
	v_mfma_f32_32x32x16_bf16 v[66:81], v[252:255], v[110:113], v[66:81]
	ds_read_b128 v[252:255], v160 offset:49280
	s_waitcnt lgkmcnt(4)
	v_mfma_f32_32x32x16_bf16 v[82:97], v[228:231], v[106:109], v[82:97]
	ds_read_b128 v[228:231], v160 offset:57472
	s_waitcnt lgkmcnt(4)
	v_mfma_f32_32x32x16_bf16 v[66:81], v[232:235], v[106:109], v[66:81]
	s_waitcnt lgkmcnt(3)
	v_mfma_f32_32x32x16_bf16 v[82:97], v[236:239], v[102:105], v[82:97]
	s_waitcnt lgkmcnt(2)
	v_mfma_f32_32x32x16_bf16 v[66:81], v[248:251], v[102:105], v[66:81]
	s_waitcnt lgkmcnt(1)
	v_mfma_f32_32x32x16_bf16 v[82:97], v[252:255], v[98:101], v[82:97]
	s_waitcnt lgkmcnt(0)
	v_mfma_f32_32x32x16_bf16 v[66:81], v[228:231], v[98:101], v[66:81]
	v_add_f32_e32 v34, 0, v10
	v_add_f32_e32 v34, v11, v34
	v_add_f32_e32 v34, v12, v34
	v_add_f32_e32 v34, v13, v34
	v_add_f32_e32 v34, v14, v34
	v_add_f32_e32 v34, v15, v34
	v_add_f32_e32 v34, v16, v34
	v_add_f32_e32 v34, v17, v34
	v_add_f32_e32 v34, v2, v34
	v_add_f32_e32 v34, v3, v34
	v_add_f32_e32 v34, v4, v34
	v_add_f32_e32 v34, v5, v34
	v_exp_f32_e32 v18, v18
	v_add_f32_e32 v34, v6, v34
	v_exp_f32_e32 v19, v19
	v_add_f32_e32 v34, v7, v34
	v_exp_f32_e32 v20, v20
	v_add_f32_e32 v34, v8, v34
	v_exp_f32_e32 v21, v21
	v_add_f32_e32 v34, v9, v34
	v_exp_f32_e32 v22, v22
	v_add_f32_e32 v34, v18, v34
	v_exp_f32_e32 v23, v23
	v_add_f32_e32 v34, v19, v34
	v_exp_f32_e32 v24, v24
	v_add_f32_e32 v34, v20, v34
	v_exp_f32_e32 v25, v25
	v_add_f32_e32 v34, v21, v34
	v_exp_f32_e32 v26, v26
	v_add_f32_e32 v34, v22, v34
	v_exp_f32_e32 v27, v27
	v_add_f32_e32 v34, v23, v34
	v_exp_f32_e32 v28, v28
	v_add_f32_e32 v34, v24, v34
	v_exp_f32_e32 v29, v29
	v_add_f32_e32 v34, v25, v34
	v_exp_f32_e32 v30, v30
	v_add_f32_e32 v34, v26, v34
	v_exp_f32_e32 v31, v31
	v_add_f32_e32 v34, v27, v34
	v_exp_f32_e32 v32, v32
	v_add_f32_e32 v34, v28, v34
	v_exp_f32_e32 v33, v54
	v_add_f32_e32 v34, v29, v34
	v_add_f32_e32 v34, v30, v34
	v_add_f32_e32 v34, v31, v34
	v_add_f32_e32 v34, v32, v34
	v_add_f32_e32 v169, v33, v34
	v_mov_b32_e32 v179, v169
	v_cvt_pk_bf16_f32 v50, v10, v11
	v_cvt_pk_bf16_f32 v51, v12, v13
	v_cvt_pk_bf16_f32 v52, v14, v15
	v_cvt_pk_bf16_f32 v53, v16, v17
	v_cvt_pk_bf16_f32 v180, v2, v3
	v_cvt_pk_bf16_f32 v181, v4, v5
	v_cvt_pk_bf16_f32 v182, v6, v7
	s_nop 1
	v_permlane32_swap_b32_e32 v169, v179
	v_permlane32_swap_b32_e32 v50, v52
	v_permlane32_swap_b32_e32 v51, v53
	v_cvt_pk_bf16_f32 v183, v8, v9
	v_permlane32_swap_b32_e32 v180, v182
	v_cvt_pk_bf16_f32 v184, v18, v19
	v_cvt_pk_bf16_f32 v185, v20, v21
	v_cvt_pk_bf16_f32 v186, v22, v23
	v_cvt_pk_bf16_f32 v187, v24, v25
	v_cvt_pk_bf16_f32 v188, v26, v27
	v_cvt_pk_bf16_f32 v189, v28, v29
	v_cvt_pk_bf16_f32 v190, v30, v31
	v_cvt_pk_bf16_f32 v191, v32, v33
	v_permlane32_swap_b32_e32 v181, v183
	v_permlane32_swap_b32_e32 v184, v186
	v_permlane32_swap_b32_e32 v185, v187
	v_permlane32_swap_b32_e32 v188, v190
	v_permlane32_swap_b32_e32 v189, v191
	ds_read_b64_tr_b16 v[2:3], v158 offset:0
	ds_read_b64_tr_b16 v[4:5], v158 offset:0x800
	ds_read_b64_tr_b16 v[18:19], v158 offset:0x1000
	ds_read_b64_tr_b16 v[20:21], v158 offset:0x1800
	ds_read_b64_tr_b16 v[22:23], v158 offset:0x2000
	ds_read_b64_tr_b16 v[24:25], v158 offset:0x2800
	ds_read_b64_tr_b16 v[26:27], v158 offset:0x3000
	ds_read_b64_tr_b16 v[28:29], v158 offset:0x3800
	s_nop 0
	s_waitcnt lgkmcnt(6)
	v_mfma_f32_32x32x16_bf16 v[2:17], v[50:53], v[2:5], 0
	s_waitcnt lgkmcnt(4)
	v_mfma_f32_32x32x16_bf16 v[2:17], v[180:183], v[18:21], v[2:17]
	ds_read_b64_tr_b16 v[18:19], v158 offset:0x200
	ds_read_b64_tr_b16 v[20:21], v158 offset:0xa00
	ds_read_b64_tr_b16 v[34:35], v158 offset:0x1200
	ds_read_b64_tr_b16 v[36:37], v158 offset:0x1a00
	ds_read_b64_tr_b16 v[38:39], v158 offset:0x2200
	ds_read_b64_tr_b16 v[40:41], v158 offset:0x2a00
	ds_read_b64_tr_b16 v[42:43], v158 offset:0x3200
	s_waitcnt lgkmcnt(9)
	v_mfma_f32_32x32x16_bf16 v[2:17], v[184:187], v[22:25], v[2:17]
	ds_read_b64_tr_b16 v[44:45], v158 offset:0x3a00
	s_waitcnt lgkmcnt(8)
	v_mfma_f32_32x32x16_bf16 v[2:17], v[188:191], v[26:29], v[2:17]
	s_waitcnt lgkmcnt(6)
	v_mfma_f32_32x32x16_bf16 v[18:33], v[50:53], v[18:21], 0
	s_waitcnt lgkmcnt(4)
	v_mfma_f32_32x32x16_bf16 v[18:33], v[180:183], v[34:37], v[18:33]
	ds_read_b64_tr_b16 v[34:35], v158 offset:0x400
	ds_read_b64_tr_b16 v[36:37], v158 offset:0xc00
	ds_read_b64_tr_b16 v[54:55], v158 offset:0x1400
	ds_read_b64_tr_b16 v[56:57], v158 offset:0x1c00
	ds_read_b64_tr_b16 v[58:59], v158 offset:0x2400
	ds_read_b64_tr_b16 v[60:61], v158 offset:0x2c00
	ds_read_b64_tr_b16 v[62:63], v158 offset:0x3400
	s_waitcnt lgkmcnt(9)
	v_mfma_f32_32x32x16_bf16 v[18:33], v[184:187], v[38:41], v[18:33]
	ds_read_b64_tr_b16 v[64:65], v158 offset:0x3c00
	s_waitcnt lgkmcnt(8)
	v_mfma_f32_32x32x16_bf16 v[18:33], v[188:191], v[42:45], v[18:33]
	s_waitcnt lgkmcnt(6)
	v_mfma_f32_32x32x16_bf16 v[34:49], v[50:53], v[34:37], 0
	s_waitcnt lgkmcnt(4)
	v_mfma_f32_32x32x16_bf16 v[34:49], v[180:183], v[54:57], v[34:49]
	ds_read_b64_tr_b16 v[54:55], v158 offset:0x600
	ds_read_b64_tr_b16 v[56:57], v158 offset:0xe00
	ds_read_b64_tr_b16 v[192:193], v158 offset:0x1600
	ds_read_b64_tr_b16 v[194:195], v158 offset:0x1e00
	ds_read_b64_tr_b16 v[196:197], v158 offset:0x2600
	ds_read_b64_tr_b16 v[198:199], v158 offset:0x2e00
	ds_read_b64_tr_b16 v[200:201], v158 offset:0x3600
	s_waitcnt lgkmcnt(9)
	v_mfma_f32_32x32x16_bf16 v[34:49], v[184:187], v[58:61], v[34:49]
	ds_read_b64_tr_b16 v[202:203], v158 offset:0x3e00
	s_waitcnt lgkmcnt(8)
	v_mfma_f32_32x32x16_bf16 v[34:49], v[188:191], v[62:65], v[34:49]
	s_waitcnt lgkmcnt(6)
	v_mfma_f32_32x32x16_bf16 v[50:65], v[50:53], v[54:57], 0
	s_waitcnt lgkmcnt(4)
	v_mfma_f32_32x32x16_bf16 v[50:65], v[180:183], v[192:195], v[50:65]
	s_waitcnt lgkmcnt(2)
	v_mfma_f32_32x32x16_bf16 v[50:65], v[184:187], v[196:199], v[50:65]
	s_waitcnt lgkmcnt(0)
	v_mfma_f32_32x32x16_bf16 v[50:65], v[188:191], v[200:203], v[50:65]
	v_max_f32_e32 v152, v83, v83
	v_max_f32_e32 v153, v82, v82
	v_max_f32_e32 v152, v153, v152
	v_max3_f32 v152, v152, v84, v85
	v_max3_f32 v152, v152, v86, v87
	v_max3_f32 v152, v152, v88, v89
	v_max3_f32 v152, v152, v90, v91
	v_max3_f32 v152, v152, v92, v93
	v_max3_f32 v152, v152, v94, v95
	v_max3_f32 v152, v152, v96, v97
	v_max3_f32 v152, v152, v66, v67
	v_max3_f32 v152, v152, v68, v69
	v_max3_f32 v152, v152, v70, v71
	v_max3_f32 v152, v152, v72, v73
	v_max3_f32 v152, v152, v74, v75
	v_max3_f32 v152, v152, v76, v77
	v_max3_f32 v152, v152, v78, v79
	v_max3_f32 v152, v152, v80, v81
	v_mov_b32_e32 v153, v152
	s_nop 1
	v_permlane32_swap_b32_e32 v152, v153
	v_max_f32_e32 v153, v153, v153
	v_max_f32_e32 v152, v152, v152
	v_max_f32_e32 v152, v152, v153
	v_sub_f32_e32 v153, v152, v150
	v_mul_f32_e32 v153, 0x3e0293ee, v153
	v_max_f32_e32 v152, v150, v152
	v_cmp_ge_f32_e32 vcc, s24, v153
	v_sub_f32_e32 v153, v150, v152
	v_mul_f32_e32 v153, 0x3e0293ee, v153
	v_exp_f32_e32 v153, v153
	s_cmp_eq_u64 vcc, exec
	s_cselect_b64 s[40:41], -1, 0
	v_cndmask_b32_e64 v180, v153, 1.0, s[40:41]
	v_cmp_gt_f32_e32 vcc, 1.0, v180
	s_barrier
	s_waitcnt vmcnt(1)
	ds_write_b128 v165, v[138:141] offset:32768
	s_waitcnt vmcnt(0)
	ds_write_b128 v165, v[142:145] offset:40960
	ds_write_b128 v166, v[130:133]
	ds_write_b128 v167, v[134:137]
	s_cbranch_vccz .LBB0_1418
	s_and_saveexec_b64 s[4:5], s[38:39]
	ds_write_b32 v159, v180 offset:128
	s_or_b64 exec, exec, s[4:5]
	s_waitcnt lgkmcnt(0)
	v_add_u32_e32 v142, s42, v162
	ds_read_b128 v[130:133], v142 offset:224
	ds_read_b128 v[134:137], v142 offset:192
	ds_read_b128 v[138:141], v142 offset:160
	ds_read_b128 v[142:145], v142 offset:128
	s_waitcnt lgkmcnt(3)
	v_mul_f32 v14, v14, v130
	v_mul_f32 v15, v15, v131
	s_waitcnt lgkmcnt(2)
	v_mul_f32 v10, v10, v134
	v_mul_f32 v11, v11, v135
	s_waitcnt lgkmcnt(1)
	v_mul_f32 v6, v6, v138
	v_mul_f32 v7, v7, v139
	v_mul_f32 v16, v16, v132
	v_mul_f32 v17, v17, v133
	v_mul_f32 v12, v12, v136
	v_mul_f32 v13, v13, v137
	v_mul_f32 v8, v8, v140
	v_mul_f32 v9, v9, v141
	s_waitcnt lgkmcnt(0)
	v_mul_f32 v4, v4, v144
	v_mul_f32 v5, v5, v145
	v_mul_f32 v2, v2, v142
	v_mul_f32 v3, v3, v143
	v_mul_f32 v30, v30, v130
	v_mul_f32 v31, v31, v131
	v_mul_f32 v26, v26, v134
	v_mul_f32 v27, v27, v135
	v_mul_f32 v22, v22, v138
	v_mul_f32 v23, v23, v139
	v_mul_f32 v32, v32, v132
	v_mul_f32 v33, v33, v133
	v_mul_f32 v28, v28, v136
	v_mul_f32 v29, v29, v137
	v_mul_f32 v24, v24, v140
	v_mul_f32 v25, v25, v141
	v_mul_f32 v20, v20, v144
	v_mul_f32 v21, v21, v145
	v_mul_f32 v18, v18, v142
	v_mul_f32 v19, v19, v143
	v_mul_f32 v46, v46, v130
	v_mul_f32 v47, v47, v131
	v_mul_f32 v42, v42, v134
	v_mul_f32 v43, v43, v135
	v_mul_f32 v38, v38, v138
	v_mul_f32 v39, v39, v139
	v_mul_f32 v48, v48, v132
	v_mul_f32 v49, v49, v133
	v_mul_f32 v44, v44, v136
	v_mul_f32 v45, v45, v137
	v_mul_f32 v40, v40, v140
	v_mul_f32 v41, v41, v141
	v_mul_f32 v36, v36, v144
	v_mul_f32 v37, v37, v145
	v_mul_f32 v34, v34, v142
	v_mul_f32 v35, v35, v143
	v_mul_f32 v62, v62, v130
	v_mul_f32 v63, v63, v131
	v_mul_f32 v58, v58, v134
	v_mul_f32 v59, v59, v135
	v_mul_f32 v54, v54, v138
	v_mul_f32 v55, v55, v139
	v_mul_f32 v64, v64, v132
	v_mul_f32 v65, v65, v133
	v_mul_f32 v60, v60, v136
	v_mul_f32 v61, v61, v137
	v_mul_f32 v56, v56, v140
	v_mul_f32 v57, v57, v141
	v_mul_f32 v52, v52, v144
	v_mul_f32 v53, v53, v145
	v_mul_f32 v50, v50, v142
	v_mul_f32 v51, v51, v143
.LBB0_1418:
	v_cndmask_b32_e64 v184, v152, v150, s[40:41]
	v_mul_f32_e32 v182, 0xbe0293ee, v184
	v_fmamk_f32 v183, v66, 0x3e0293ee, v182
	v_fmamk_f32 v66, v83, 0x3e0293ee, v182
	v_fmamk_f32 v197, v67, 0x3e0293ee, v182
	v_fmamk_f32 v67, v84, 0x3e0293ee, v182
	v_exp_f32_e32 v196, v66
	v_exp_f32_e32 v192, v67
	v_lshlrev_b64 v[66:67], 11, v[146:147]
	v_sub_f32_e32 v130, 0xf149f2ca, v151
	v_fmamk_f32 v198, v68, 0x3e0293ee, v182
	v_fmamk_f32 v68, v85, 0x3e0293ee, v182
	v_fmamk_f32 v199, v69, 0x3e0293ee, v182
	v_fmamk_f32 v69, v86, 0x3e0293ee, v182
	v_lshl_add_u64 v[66:67], v[148:149], 0, v[66:67]
	s_mov_b64 s[4:5], 0x60000
	v_mul_f32_e32 v130, 0x3e0293ee, v130
	v_fmamk_f32 v200, v70, 0x3e0293ee, v182
	v_fmamk_f32 v70, v87, 0x3e0293ee, v182
	v_fmamk_f32 v201, v71, 0x3e0293ee, v182
	v_fmamk_f32 v71, v88, 0x3e0293ee, v182
	v_exp_f32_e32 v195, v68
	v_exp_f32_e32 v190, v69
	v_lshl_add_u64 v[68:69], v[66:67], 0, s[4:5]
	s_mov_b64 s[4:5], 0x70000
	v_exp_f32_e32 v181, v130
	v_exp_f32_e32 v193, v70
	v_exp_f32_e32 v189, v71
	s_waitcnt lgkmcnt(0)
	s_barrier
	v_lshl_add_u64 v[70:71], v[66:67], 0, s[4:5]
	global_load_dwordx4 v[130:133], v[68:69], off offset:1024
	global_load_dwordx4 v[134:137], v[70:71], off offset:1024
	v_add_co_u32_e32 v68, vcc, 0x60000, v66
	s_mov_b32 s4, 0x70000
	s_nop 0
	v_addc_co_u32_e32 v69, vcc, 0, v67, vcc
	v_add_co_u32_e32 v66, vcc, s4, v66
	v_fmamk_f32 v82, v82, 0x3e0293ee, v182
	s_nop 0
	v_addc_co_u32_e32 v67, vcc, 0, v67, vcc
	global_load_dwordx4 v[138:141], v[68:69], off
	global_load_dwordx4 v[142:145], v[66:67], off
	v_fmamk_f32 v202, v72, 0x3e0293ee, v182
	v_fmamk_f32 v72, v89, 0x3e0293ee, v182
	v_fmamk_f32 v203, v73, 0x3e0293ee, v182
	v_fmamk_f32 v73, v90, 0x3e0293ee, v182
	v_fmamk_f32 v204, v74, 0x3e0293ee, v182
	v_fmamk_f32 v74, v91, 0x3e0293ee, v182
	v_fmamk_f32 v205, v75, 0x3e0293ee, v182
	v_fmamk_f32 v75, v92, 0x3e0293ee, v182
	v_fmamk_f32 v206, v76, 0x3e0293ee, v182
	v_fmamk_f32 v76, v93, 0x3e0293ee, v182
	v_fmamk_f32 v207, v77, 0x3e0293ee, v182
	v_fmamk_f32 v77, v94, 0x3e0293ee, v182
	v_fmamk_f32 v208, v78, 0x3e0293ee, v182
	v_fmamk_f32 v78, v95, 0x3e0293ee, v182
	v_fmamk_f32 v83, v96, 0x3e0293ee, v182
	v_fmamk_f32 v84, v97, 0x3e0293ee, v182
	v_fmamk_f32 v209, v79, 0x3e0293ee, v182
	v_fmamk_f32 v210, v80, 0x3e0293ee, v182
	v_fmac_f32_e32 v182, 0x3e0293ee, v81
	v_exp_f32_e32 v194, v82
	v_exp_f32_e32 v191, v72
	v_exp_f32_e32 v150, v73
	v_exp_f32_e32 v188, v74
	v_exp_f32_e32 v151, v75
	v_exp_f32_e32 v187, v76
	v_exp_f32_e32 v152, v77
	v_exp_f32_e32 v186, v78
	v_exp_f32_e32 v153, v83
	v_exp_f32_e32 v185, v84
	ds_read_b128 v[228:231], v168 offset:32768
	ds_read_b128 v[232:235], v164 offset:32768
	ds_read_b128 v[236:239], v168 offset:40960
	ds_read_b128 v[248:251], v164 offset:40960
	ds_read_b128 v[252:255], v161 offset:32768
	s_waitcnt lgkmcnt(4)
	v_mfma_f32_32x32x16_bf16 v[82:97], v[228:231], v[126:129], 0
	ds_read_b128 v[228:231], v161 offset:40960
	s_waitcnt lgkmcnt(4)
	v_mfma_f32_32x32x16_bf16 v[82:97], v[232:235], v[122:125], v[82:97]
	ds_read_b128 v[232:235], v160 offset:32768
	s_waitcnt lgkmcnt(4)
	v_mfma_f32_32x32x16_bf16 v[66:81], v[236:239], v[126:129], 0
	ds_read_b128 v[236:239], v160 offset:40960
	s_waitcnt lgkmcnt(4)
	v_mfma_f32_32x32x16_bf16 v[66:81], v[248:251], v[122:125], v[66:81]
	ds_read_b128 v[248:251], v168 offset:32896
	s_waitcnt lgkmcnt(4)
	v_mfma_f32_32x32x16_bf16 v[82:97], v[252:255], v[118:121], v[82:97]
	ds_read_b128 v[252:255], v168 offset:41088
	s_waitcnt lgkmcnt(4)
	v_mfma_f32_32x32x16_bf16 v[66:81], v[228:231], v[118:121], v[66:81]
	ds_read_b128 v[228:231], v164 offset:32896
	s_waitcnt lgkmcnt(4)
	v_mfma_f32_32x32x16_bf16 v[82:97], v[232:235], v[114:117], v[82:97]
	ds_read_b128 v[232:235], v164 offset:41088
	s_waitcnt lgkmcnt(4)
	v_mfma_f32_32x32x16_bf16 v[66:81], v[236:239], v[114:117], v[66:81]
	ds_read_b128 v[236:239], v161 offset:32896
	s_waitcnt lgkmcnt(4)
	v_mfma_f32_32x32x16_bf16 v[82:97], v[248:251], v[110:113], v[82:97]
	ds_read_b128 v[248:251], v161 offset:41088
	s_waitcnt lgkmcnt(4)
	v_mfma_f32_32x32x16_bf16 v[66:81], v[252:255], v[110:113], v[66:81]
	ds_read_b128 v[252:255], v160 offset:32896
	s_waitcnt lgkmcnt(4)
	v_mfma_f32_32x32x16_bf16 v[82:97], v[228:231], v[106:109], v[82:97]
	ds_read_b128 v[228:231], v160 offset:41088
	s_waitcnt lgkmcnt(4)
	v_mfma_f32_32x32x16_bf16 v[66:81], v[232:235], v[106:109], v[66:81]
	s_waitcnt lgkmcnt(3)
	v_mfma_f32_32x32x16_bf16 v[82:97], v[236:239], v[102:105], v[82:97]
	s_waitcnt lgkmcnt(2)
	v_mfma_f32_32x32x16_bf16 v[66:81], v[248:251], v[102:105], v[66:81]
	s_waitcnt lgkmcnt(1)
	v_mfma_f32_32x32x16_bf16 v[82:97], v[252:255], v[98:101], v[82:97]
	s_waitcnt lgkmcnt(0)
	v_mfma_f32_32x32x16_bf16 v[66:81], v[228:231], v[98:101], v[66:81]
	v_add_f32_e32 v146, 0, v194
	v_add_f32_e32 v146, v196, v146
	v_add_f32_e32 v146, v192, v146
	v_add_f32_e32 v146, v195, v146
	v_add_f32_e32 v146, v190, v146
	v_add_f32_e32 v146, v193, v146
	v_add_f32_e32 v146, v189, v146
	v_add_f32_e32 v146, v191, v146
	v_add_f32_e32 v146, v150, v146
	v_add_f32_e32 v146, v188, v146
	v_add_f32_e32 v146, v151, v146
	v_add_f32_e32 v146, v187, v146
	v_exp_f32_e32 v211, v183
	v_add_f32_e32 v146, v152, v146
	v_exp_f32_e32 v197, v197
	v_add_f32_e32 v146, v186, v146
	v_exp_f32_e32 v198, v198
	v_add_f32_e32 v146, v153, v146
	v_exp_f32_e32 v199, v199
	v_add_f32_e32 v146, v185, v146
	v_exp_f32_e32 v200, v200
	v_add_f32_e32 v146, v211, v146
	v_exp_f32_e32 v201, v201
	v_add_f32_e32 v146, v197, v146
	v_exp_f32_e32 v202, v202
	v_add_f32_e32 v146, v198, v146
	v_exp_f32_e32 v203, v203
	v_add_f32_e32 v146, v199, v146
	v_exp_f32_e32 v204, v204
	v_add_f32_e32 v146, v200, v146
	v_exp_f32_e32 v205, v205
	v_add_f32_e32 v146, v201, v146
	v_exp_f32_e32 v206, v206
	v_add_f32_e32 v146, v202, v146
	v_exp_f32_e32 v207, v207
	v_add_f32_e32 v146, v203, v146
	v_exp_f32_e32 v208, v208
	v_add_f32_e32 v146, v204, v146
	v_exp_f32_e32 v209, v209
	v_add_f32_e32 v146, v205, v146
	v_exp_f32_e32 v210, v210
	v_add_f32_e32 v146, v206, v146
	v_exp_f32_e32 v212, v182
	v_add_f32_e32 v146, v207, v146
	v_add_f32_e32 v146, v208, v146
	v_add_f32_e32 v146, v209, v146
	v_add_f32_e32 v146, v210, v146
	v_add_f32_e32 v182, v212, v146
	v_mov_b32_e32 v183, v182
	v_cvt_pk_bf16_f32 v146, v194, v196
	v_cvt_pk_bf16_f32 v147, v192, v195
	v_cvt_pk_bf16_f32 v148, v190, v193
	v_cvt_pk_bf16_f32 v149, v189, v191
	s_nop 1
	v_permlane32_swap_b32_e32 v182, v183
	v_permlane32_swap_b32_e32 v146, v148
	v_permlane32_swap_b32_e32 v147, v149
	v_cvt_pk_bf16_f32 v150, v150, v188
	v_cvt_pk_bf16_f32 v151, v151, v187
	v_cvt_pk_bf16_f32 v152, v152, v186
	v_cvt_pk_bf16_f32 v153, v153, v185
	v_cvt_pk_bf16_f32 v186, v211, v197
	v_cvt_pk_bf16_f32 v187, v198, v199
	v_cvt_pk_bf16_f32 v188, v200, v201
	v_cvt_pk_bf16_f32 v189, v202, v203
	v_cvt_pk_bf16_f32 v190, v204, v205
	v_cvt_pk_bf16_f32 v191, v206, v207
	v_cvt_pk_bf16_f32 v192, v208, v209
	v_cvt_pk_bf16_f32 v193, v210, v212
	s_nop 0
	v_permlane32_swap_b32_e32 v150, v152
	v_permlane32_swap_b32_e32 v151, v153
	v_permlane32_swap_b32_e32 v186, v188
	v_permlane32_swap_b32_e32 v187, v189
	v_permlane32_swap_b32_e32 v190, v192
	v_permlane32_swap_b32_e32 v191, v193
	ds_read_b64_tr_b16 v[194:195], v158 offset:0x4000
	ds_read_b64_tr_b16 v[196:197], v158 offset:0x4800
	ds_read_b64_tr_b16 v[198:199], v158 offset:0x5000
	ds_read_b64_tr_b16 v[200:201], v158 offset:0x5800
	ds_read_b64_tr_b16 v[202:203], v158 offset:0x6000
	ds_read_b64_tr_b16 v[204:205], v158 offset:0x6800
	ds_read_b64_tr_b16 v[206:207], v158 offset:0x7000
	ds_read_b64_tr_b16 v[208:209], v158 offset:0x7800
	s_nop 0
	s_waitcnt lgkmcnt(6)
	v_mfma_f32_32x32x16_bf16 v[2:17], v[146:149], v[194:197], v[2:17]
	ds_read_b64_tr_b16 v[194:195], v158 offset:0x4200
	ds_read_b64_tr_b16 v[196:197], v158 offset:0x4a00
	s_waitcnt lgkmcnt(6)
	v_mfma_f32_32x32x16_bf16 v[2:17], v[150:153], v[198:201], v[2:17]
	ds_read_b64_tr_b16 v[198:199], v158 offset:0x5200
	ds_read_b64_tr_b16 v[200:201], v158 offset:0x5a00
	s_waitcnt lgkmcnt(6)
	v_mfma_f32_32x32x16_bf16 v[2:17], v[186:189], v[202:205], v[2:17]
	ds_read_b64_tr_b16 v[202:203], v158 offset:0x6200
	ds_read_b64_tr_b16 v[204:205], v158 offset:0x6a00
	s_waitcnt lgkmcnt(6)
	v_mfma_f32_32x32x16_bf16 v[2:17], v[190:193], v[206:209], v[2:17]
	ds_read_b64_tr_b16 v[206:207], v158 offset:0x7200
	ds_read_b64_tr_b16 v[208:209], v158 offset:0x7a00
	s_waitcnt lgkmcnt(6)
	v_mfma_f32_32x32x16_bf16 v[18:33], v[146:149], v[194:197], v[18:33]
	ds_read_b64_tr_b16 v[194:195], v158 offset:0x4400
	ds_read_b64_tr_b16 v[196:197], v158 offset:0x4c00
	s_waitcnt lgkmcnt(6)
	v_mfma_f32_32x32x16_bf16 v[18:33], v[150:153], v[198:201], v[18:33]
	ds_read_b64_tr_b16 v[198:199], v158 offset:0x5400
	ds_read_b64_tr_b16 v[200:201], v158 offset:0x5c00
	s_waitcnt lgkmcnt(6)
	v_mfma_f32_32x32x16_bf16 v[18:33], v[186:189], v[202:205], v[18:33]
	ds_read_b64_tr_b16 v[202:203], v158 offset:0x6400
	ds_read_b64_tr_b16 v[204:205], v158 offset:0x6c00
	s_waitcnt lgkmcnt(6)
	v_mfma_f32_32x32x16_bf16 v[18:33], v[190:193], v[206:209], v[18:33]
	ds_read_b64_tr_b16 v[206:207], v158 offset:0x7400
	ds_read_b64_tr_b16 v[208:209], v158 offset:0x7c00
	s_waitcnt lgkmcnt(6)
	v_mfma_f32_32x32x16_bf16 v[34:49], v[146:149], v[194:197], v[34:49]
	ds_read_b64_tr_b16 v[194:195], v158 offset:0x4600
	ds_read_b64_tr_b16 v[196:197], v158 offset:0x4e00
	s_waitcnt lgkmcnt(6)
	v_mfma_f32_32x32x16_bf16 v[34:49], v[150:153], v[198:201], v[34:49]
	ds_read_b64_tr_b16 v[198:199], v158 offset:0x5600
	ds_read_b64_tr_b16 v[200:201], v158 offset:0x5e00
	s_waitcnt lgkmcnt(6)
	v_mfma_f32_32x32x16_bf16 v[34:49], v[186:189], v[202:205], v[34:49]
	ds_read_b64_tr_b16 v[202:203], v158 offset:0x6600
	ds_read_b64_tr_b16 v[204:205], v158 offset:0x6e00
	s_waitcnt lgkmcnt(6)
	v_mfma_f32_32x32x16_bf16 v[34:49], v[190:193], v[206:209], v[34:49]
	ds_read_b64_tr_b16 v[206:207], v158 offset:0x7600
	ds_read_b64_tr_b16 v[208:209], v158 offset:0x7e00
	s_waitcnt lgkmcnt(6)
	v_mfma_f32_32x32x16_bf16 v[50:65], v[146:149], v[194:197], v[50:65]
	s_waitcnt lgkmcnt(4)
	v_mfma_f32_32x32x16_bf16 v[50:65], v[150:153], v[198:201], v[50:65]
	s_waitcnt lgkmcnt(2)
	v_mfma_f32_32x32x16_bf16 v[50:65], v[186:189], v[202:205], v[50:65]
	s_waitcnt lgkmcnt(0)
	v_mfma_f32_32x32x16_bf16 v[50:65], v[190:193], v[206:209], v[50:65]
	v_max_f32_e32 v146, v83, v83
	v_max_f32_e32 v147, v82, v82
	v_max_f32_e32 v146, v147, v146
	v_max3_f32 v146, v146, v84, v85
	v_max3_f32 v146, v146, v86, v87
	v_max3_f32 v146, v146, v88, v89
	v_max3_f32 v146, v146, v90, v91
	v_max3_f32 v146, v146, v92, v93
	v_max3_f32 v146, v146, v94, v95
	v_max3_f32 v146, v146, v96, v97
	v_max3_f32 v146, v146, v66, v67
	v_max3_f32 v146, v146, v68, v69
	v_max3_f32 v146, v146, v70, v71
	v_max3_f32 v146, v146, v72, v73
	v_max3_f32 v146, v146, v74, v75
	v_max3_f32 v146, v146, v76, v77
	v_max3_f32 v146, v146, v78, v79
	v_max3_f32 v146, v146, v80, v81
	v_mov_b32_e32 v147, v146
	s_nop 1
	v_permlane32_swap_b32_e32 v146, v147
	v_max_f32_e32 v147, v147, v147
	v_max_f32_e32 v146, v146, v146
	v_max_f32_e32 v146, v146, v147
	v_sub_f32_e32 v147, v146, v184
	v_mul_f32_e32 v147, 0x3e0293ee, v147
	v_cmp_ge_f32_e32 vcc, s24, v147
	v_max_f32_e32 v147, v184, v184
	v_max_f32_e32 v147, v147, v146
	v_sub_f32_e32 v146, v184, v147
	v_mul_f32_e32 v146, 0x3e0293ee, v146
	v_exp_f32_e32 v146, v146
	s_cmp_eq_u64 vcc, exec
	s_cselect_b64 s[40:41], -1, 0
	v_cndmask_b32_e64 v146, v146, 1.0, s[40:41]
	v_cmp_gt_f32_e32 vcc, 1.0, v146
	s_barrier
	s_waitcnt vmcnt(1)
	ds_write_b128 v165, v[138:141] offset:49152
	s_waitcnt vmcnt(0)
	ds_write_b128 v165, v[142:145] offset:57344
	ds_write_b128 v166, v[130:133] offset:16384
	ds_write_b128 v167, v[134:137] offset:16384
	s_cbranch_vccz .LBB0_1422
	s_and_saveexec_b64 s[4:5], s[38:39]
	ds_write_b32 v159, v146 offset:128
	s_or_b64 exec, exec, s[4:5]
	s_waitcnt lgkmcnt(0)
	v_add_u32_e32 v142, s42, v162
	ds_read_b128 v[130:133], v142 offset:224
	ds_read_b128 v[134:137], v142 offset:192
	ds_read_b128 v[138:141], v142 offset:160
	ds_read_b128 v[142:145], v142 offset:128
	s_waitcnt lgkmcnt(3)
	v_mul_f32 v14, v14, v130
	v_mul_f32 v15, v15, v131
	s_waitcnt lgkmcnt(2)
	v_mul_f32 v10, v10, v134
	v_mul_f32 v11, v11, v135
	s_waitcnt lgkmcnt(1)
	v_mul_f32 v6, v6, v138
	v_mul_f32 v7, v7, v139
	v_mul_f32 v16, v16, v132
	v_mul_f32 v17, v17, v133
	v_mul_f32 v12, v12, v136
	v_mul_f32 v13, v13, v137
	v_mul_f32 v8, v8, v140
	v_mul_f32 v9, v9, v141
	s_waitcnt lgkmcnt(0)
	v_mul_f32 v4, v4, v144
	v_mul_f32 v5, v5, v145
	v_mul_f32 v2, v2, v142
	v_mul_f32 v3, v3, v143
	v_mul_f32 v30, v30, v130
	v_mul_f32 v31, v31, v131
	v_mul_f32 v26, v26, v134
	v_mul_f32 v27, v27, v135
	v_mul_f32 v22, v22, v138
	v_mul_f32 v23, v23, v139
	v_mul_f32 v32, v32, v132
	v_mul_f32 v33, v33, v133
	v_mul_f32 v28, v28, v136
	v_mul_f32 v29, v29, v137
	v_mul_f32 v24, v24, v140
	v_mul_f32 v25, v25, v141
	v_mul_f32 v20, v20, v144
	v_mul_f32 v21, v21, v145
	v_mul_f32 v18, v18, v142
	v_mul_f32 v19, v19, v143
	v_mul_f32 v46, v46, v130
	v_mul_f32 v47, v47, v131
	v_mul_f32 v42, v42, v134
	v_mul_f32 v43, v43, v135
	v_mul_f32 v38, v38, v138
	v_mul_f32 v39, v39, v139
	v_mul_f32 v48, v48, v132
	v_mul_f32 v49, v49, v133
	v_mul_f32 v44, v44, v136
	v_mul_f32 v45, v45, v137
	v_mul_f32 v40, v40, v140
	v_mul_f32 v41, v41, v141
	v_mul_f32 v36, v36, v144
	v_mul_f32 v37, v37, v145
	v_mul_f32 v34, v34, v142
	v_mul_f32 v35, v35, v143
	v_mul_f32 v62, v62, v130
	v_mul_f32 v63, v63, v131
	v_mul_f32 v58, v58, v134
	v_mul_f32 v59, v59, v135
	v_mul_f32 v54, v54, v138
	v_mul_f32 v55, v55, v139
	v_mul_f32 v64, v64, v132
	v_mul_f32 v65, v65, v133
	v_mul_f32 v60, v60, v136
	v_mul_f32 v61, v61, v137
	v_mul_f32 v56, v56, v140
	v_mul_f32 v57, v57, v141
	v_mul_f32 v52, v52, v144
	v_mul_f32 v53, v53, v145
	v_mul_f32 v50, v50, v142
	v_mul_f32 v51, v51, v143
.LBB0_1422:
	v_cndmask_b32_e64 v130, v147, v184, s[40:41]
	v_mul_f32_e32 v148, 0xbe0293ee, v130
	v_fmamk_f32 v82, v82, 0x3e0293ee, v148
	v_fmamk_f32 v149, v66, 0x3e0293ee, v148
	v_fmamk_f32 v66, v83, 0x3e0293ee, v148
	v_fmamk_f32 v150, v67, 0x3e0293ee, v148
	v_fmamk_f32 v67, v84, 0x3e0293ee, v148
	v_fmamk_f32 v151, v68, 0x3e0293ee, v148
	v_fmamk_f32 v68, v85, 0x3e0293ee, v148
	v_fmamk_f32 v152, v69, 0x3e0293ee, v148
	v_fmamk_f32 v69, v86, 0x3e0293ee, v148
	v_fmamk_f32 v153, v70, 0x3e0293ee, v148
	v_fmamk_f32 v70, v87, 0x3e0293ee, v148
	v_fmamk_f32 v165, v71, 0x3e0293ee, v148
	v_fmamk_f32 v71, v88, 0x3e0293ee, v148
	v_fmamk_f32 v166, v72, 0x3e0293ee, v148
	v_fmamk_f32 v72, v89, 0x3e0293ee, v148
	v_fmamk_f32 v167, v73, 0x3e0293ee, v148
	v_fmamk_f32 v73, v90, 0x3e0293ee, v148
	v_fmamk_f32 v184, v74, 0x3e0293ee, v148
	v_fmamk_f32 v74, v91, 0x3e0293ee, v148
	v_fmamk_f32 v185, v75, 0x3e0293ee, v148
	v_fmamk_f32 v75, v92, 0x3e0293ee, v148
	v_fmamk_f32 v186, v76, 0x3e0293ee, v148
	v_fmamk_f32 v76, v93, 0x3e0293ee, v148
	v_fmamk_f32 v187, v77, 0x3e0293ee, v148
	v_fmamk_f32 v77, v94, 0x3e0293ee, v148
	v_fmamk_f32 v188, v78, 0x3e0293ee, v148
	v_fmamk_f32 v78, v95, 0x3e0293ee, v148
	v_fmamk_f32 v83, v96, 0x3e0293ee, v148
	v_fmamk_f32 v84, v97, 0x3e0293ee, v148
	v_exp_f32_e32 v144, v82
	v_exp_f32_e32 v147, v66
	v_exp_f32_e32 v142, v67
	v_exp_f32_e32 v145, v68
	v_exp_f32_e32 v140, v69
	v_exp_f32_e32 v143, v70
	v_exp_f32_e32 v139, v71
	v_exp_f32_e32 v141, v72
	v_exp_f32_e32 v136, v73
	v_exp_f32_e32 v138, v74
	v_exp_f32_e32 v134, v75
	v_exp_f32_e32 v137, v76
	v_exp_f32_e32 v132, v77
	v_exp_f32_e32 v135, v78
	v_exp_f32_e32 v131, v83
	v_exp_f32_e32 v133, v84
	v_fmamk_f32 v189, v79, 0x3e0293ee, v148
	v_fmamk_f32 v190, v80, 0x3e0293ee, v148
	v_fmac_f32_e32 v148, 0x3e0293ee, v81
	s_waitcnt lgkmcnt(0)
	s_barrier
	ds_read_b128 v[228:231], v168 offset:49152
	ds_read_b128 v[232:235], v168 offset:57344
	ds_read_b128 v[236:239], v164 offset:49152
	ds_read_b128 v[248:251], v164 offset:57344
	ds_read_b128 v[252:255], v161 offset:49152
	s_waitcnt lgkmcnt(4)
	v_mfma_f32_32x32x16_bf16 v[82:97], v[228:231], v[126:129], 0
	ds_read_b128 v[228:231], v161 offset:57344
	s_waitcnt lgkmcnt(4)
	v_mfma_f32_32x32x16_bf16 v[66:81], v[232:235], v[126:129], 0
	ds_read_b128 v[232:235], v160 offset:49152
	s_waitcnt lgkmcnt(4)
	v_mfma_f32_32x32x16_bf16 v[82:97], v[236:239], v[122:125], v[82:97]
	ds_read_b128 v[236:239], v160 offset:57344
	s_waitcnt lgkmcnt(4)
	v_mfma_f32_32x32x16_bf16 v[66:81], v[248:251], v[122:125], v[66:81]
	ds_read_b128 v[248:251], v168 offset:49280
	s_waitcnt lgkmcnt(4)
	v_mfma_f32_32x32x16_bf16 v[82:97], v[252:255], v[118:121], v[82:97]
	ds_read_b128 v[252:255], v168 offset:57472
	s_waitcnt lgkmcnt(4)
	v_mfma_f32_32x32x16_bf16 v[66:81], v[228:231], v[118:121], v[66:81]
	ds_read_b128 v[228:231], v164 offset:49280
	s_waitcnt lgkmcnt(4)
	v_mfma_f32_32x32x16_bf16 v[82:97], v[232:235], v[114:117], v[82:97]
	ds_read_b128 v[232:235], v164 offset:57472
	s_waitcnt lgkmcnt(4)
	v_mfma_f32_32x32x16_bf16 v[66:81], v[236:239], v[114:117], v[66:81]
	ds_read_b128 v[236:239], v161 offset:49280
	s_waitcnt lgkmcnt(4)
	v_mfma_f32_32x32x16_bf16 v[82:97], v[248:251], v[110:113], v[82:97]
	ds_read_b128 v[248:251], v161 offset:57472
	s_waitcnt lgkmcnt(4)
	v_mfma_f32_32x32x16_bf16 v[66:81], v[252:255], v[110:113], v[66:81]
	ds_read_b128 v[252:255], v160 offset:49280
	s_waitcnt lgkmcnt(4)
	v_mfma_f32_32x32x16_bf16 v[82:97], v[228:231], v[106:109], v[82:97]
	ds_read_b128 v[228:231], v160 offset:57472
	s_waitcnt lgkmcnt(4)
	v_mfma_f32_32x32x16_bf16 v[66:81], v[232:235], v[106:109], v[66:81]
	s_waitcnt lgkmcnt(3)
	v_mfma_f32_32x32x16_bf16 v[82:97], v[236:239], v[102:105], v[82:97]
	s_waitcnt lgkmcnt(2)
	v_mfma_f32_32x32x16_bf16 v[66:81], v[248:251], v[102:105], v[66:81]
	s_waitcnt lgkmcnt(1)
	v_mfma_f32_32x32x16_bf16 v[82:97], v[252:255], v[98:101], v[82:97]
	s_waitcnt lgkmcnt(0)
	v_mfma_f32_32x32x16_bf16 v[66:81], v[228:231], v[98:101], v[66:81]
	v_add_f32_e32 v98, 0, v144
	v_add_f32_e32 v98, v147, v98
	v_add_f32_e32 v98, v142, v98
	v_add_f32_e32 v98, v145, v98
	v_add_f32_e32 v98, v140, v98
	v_add_f32_e32 v98, v143, v98
	v_add_f32_e32 v98, v139, v98
	v_add_f32_e32 v98, v141, v98
	v_add_f32_e32 v98, v136, v98
	v_add_f32_e32 v98, v138, v98
	v_add_f32_e32 v98, v134, v98
	v_add_f32_e32 v98, v137, v98
	v_exp_f32_e32 v108, v149
	v_add_f32_e32 v98, v132, v98
	v_exp_f32_e32 v109, v150
	v_add_f32_e32 v98, v135, v98
	v_exp_f32_e32 v110, v151
	v_add_f32_e32 v98, v131, v98
	v_exp_f32_e32 v111, v152
	v_add_f32_e32 v98, v133, v98
	v_exp_f32_e32 v112, v153
	v_add_f32_e32 v98, v108, v98
	v_exp_f32_e32 v113, v165
	v_add_f32_e32 v98, v109, v98
	v_exp_f32_e32 v114, v166
	v_add_f32_e32 v98, v110, v98
	v_exp_f32_e32 v115, v167
	v_add_f32_e32 v98, v111, v98
	v_exp_f32_e32 v116, v184
	v_add_f32_e32 v98, v112, v98
	v_exp_f32_e32 v117, v185
	v_add_f32_e32 v98, v113, v98
	v_exp_f32_e32 v118, v186
	v_add_f32_e32 v98, v114, v98
	v_exp_f32_e32 v119, v187
	v_add_f32_e32 v98, v115, v98
	v_exp_f32_e32 v120, v188
	v_add_f32_e32 v98, v116, v98
	v_exp_f32_e32 v121, v189
	v_add_f32_e32 v98, v117, v98
	v_exp_f32_e32 v122, v190
	v_add_f32_e32 v98, v118, v98
	v_exp_f32_e32 v123, v148
	v_add_f32_e32 v98, v119, v98
	v_add_f32_e32 v98, v120, v98
	v_add_f32_e32 v98, v121, v98
	v_add_f32_e32 v98, v122, v98
	v_add_f32_e32 v102, v123, v98
	v_mov_b32_e32 v103, v102
	v_cvt_pk_bf16_f32 v98, v144, v147
	v_cvt_pk_bf16_f32 v99, v142, v145
	v_cvt_pk_bf16_f32 v100, v140, v143
	v_cvt_pk_bf16_f32 v101, v139, v141
	s_nop 1
	v_permlane32_swap_b32_e32 v102, v103
	v_permlane32_swap_b32_e32 v98, v100
	v_permlane32_swap_b32_e32 v99, v101
	v_cvt_pk_bf16_f32 v104, v136, v138
	v_cvt_pk_bf16_f32 v105, v134, v137
	v_cvt_pk_bf16_f32 v106, v132, v135
	v_cvt_pk_bf16_f32 v107, v131, v133
	v_cvt_pk_bf16_f32 v108, v108, v109
	v_cvt_pk_bf16_f32 v109, v110, v111
	v_cvt_pk_bf16_f32 v110, v112, v113
	v_cvt_pk_bf16_f32 v111, v114, v115
	v_cvt_pk_bf16_f32 v112, v116, v117
	v_cvt_pk_bf16_f32 v113, v118, v119
	v_cvt_pk_bf16_f32 v114, v120, v121
	v_cvt_pk_bf16_f32 v115, v122, v123
	s_nop 0
	v_permlane32_swap_b32_e32 v104, v106
	v_permlane32_swap_b32_e32 v105, v107
	v_permlane32_swap_b32_e32 v108, v110
	v_permlane32_swap_b32_e32 v109, v111
	v_permlane32_swap_b32_e32 v112, v114
	v_permlane32_swap_b32_e32 v113, v115
	ds_read_b64_tr_b16 v[116:117], v158 offset:0
	ds_read_b64_tr_b16 v[118:119], v158 offset:0x800
	ds_read_b64_tr_b16 v[120:121], v158 offset:0x1000
	ds_read_b64_tr_b16 v[122:123], v158 offset:0x1800
	ds_read_b64_tr_b16 v[124:125], v158 offset:0x2000
	ds_read_b64_tr_b16 v[126:127], v158 offset:0x2800
	ds_read_b64_tr_b16 v[132:133], v158 offset:0x3000
	ds_read_b64_tr_b16 v[134:135], v158 offset:0x3800
	s_nop 0
	s_waitcnt lgkmcnt(6)
	v_mfma_f32_32x32x16_bf16 v[2:17], v[98:101], v[116:119], v[2:17]
	ds_read_b64_tr_b16 v[116:117], v158 offset:0x200
	ds_read_b64_tr_b16 v[118:119], v158 offset:0xa00
	s_waitcnt lgkmcnt(6)
	v_mfma_f32_32x32x16_bf16 v[2:17], v[104:107], v[120:123], v[2:17]
	ds_read_b64_tr_b16 v[120:121], v158 offset:0x1200
	ds_read_b64_tr_b16 v[122:123], v158 offset:0x1a00
	s_waitcnt lgkmcnt(6)
	v_mfma_f32_32x32x16_bf16 v[2:17], v[108:111], v[124:127], v[2:17]
	ds_read_b64_tr_b16 v[124:125], v158 offset:0x2200
	ds_read_b64_tr_b16 v[126:127], v158 offset:0x2a00
	s_waitcnt lgkmcnt(6)
	v_mfma_f32_32x32x16_bf16 v[2:17], v[112:115], v[132:135], v[2:17]
	ds_read_b64_tr_b16 v[132:133], v158 offset:0x3200
	ds_read_b64_tr_b16 v[134:135], v158 offset:0x3a00
	s_waitcnt lgkmcnt(6)
	v_mfma_f32_32x32x16_bf16 v[18:33], v[98:101], v[116:119], v[18:33]
	ds_read_b64_tr_b16 v[116:117], v158 offset:0x400
	ds_read_b64_tr_b16 v[118:119], v158 offset:0xc00
	s_waitcnt lgkmcnt(6)
	v_mfma_f32_32x32x16_bf16 v[18:33], v[104:107], v[120:123], v[18:33]
	ds_read_b64_tr_b16 v[120:121], v158 offset:0x1400
	ds_read_b64_tr_b16 v[122:123], v158 offset:0x1c00
	s_waitcnt lgkmcnt(6)
	v_mfma_f32_32x32x16_bf16 v[18:33], v[108:111], v[124:127], v[18:33]
	ds_read_b64_tr_b16 v[124:125], v158 offset:0x2400
	ds_read_b64_tr_b16 v[126:127], v158 offset:0x2c00
	s_waitcnt lgkmcnt(6)
	v_mfma_f32_32x32x16_bf16 v[18:33], v[112:115], v[132:135], v[18:33]
	ds_read_b64_tr_b16 v[132:133], v158 offset:0x3400
	ds_read_b64_tr_b16 v[134:135], v158 offset:0x3c00
	s_waitcnt lgkmcnt(6)
	v_mfma_f32_32x32x16_bf16 v[34:49], v[98:101], v[116:119], v[34:49]
	ds_read_b64_tr_b16 v[116:117], v158 offset:0x600
	ds_read_b64_tr_b16 v[118:119], v158 offset:0xe00
	s_waitcnt lgkmcnt(6)
	v_mfma_f32_32x32x16_bf16 v[34:49], v[104:107], v[120:123], v[34:49]
	ds_read_b64_tr_b16 v[120:121], v158 offset:0x1600
	ds_read_b64_tr_b16 v[122:123], v158 offset:0x1e00
	s_waitcnt lgkmcnt(6)
	v_mfma_f32_32x32x16_bf16 v[34:49], v[108:111], v[124:127], v[34:49]
	ds_read_b64_tr_b16 v[124:125], v158 offset:0x2600
	ds_read_b64_tr_b16 v[126:127], v158 offset:0x2e00
	s_waitcnt lgkmcnt(6)
	v_mfma_f32_32x32x16_bf16 v[34:49], v[112:115], v[132:135], v[34:49]
	ds_read_b64_tr_b16 v[132:133], v158 offset:0x3600
	ds_read_b64_tr_b16 v[134:135], v158 offset:0x3e00
	s_waitcnt lgkmcnt(6)
	v_mfma_f32_32x32x16_bf16 v[50:65], v[98:101], v[116:119], v[50:65]
	v_max_f32_e32 v98, v83, v83
	v_max_f32_e32 v99, v82, v82
	v_max_f32_e32 v98, v99, v98
	v_max3_f32 v98, v98, v84, v85
	v_max3_f32 v98, v98, v86, v87
	v_max3_f32 v98, v98, v88, v89
	v_max3_f32 v98, v98, v90, v91
	v_max3_f32 v98, v98, v92, v93
	v_max3_f32 v98, v98, v94, v95
	v_max3_f32 v98, v98, v96, v97
	s_waitcnt lgkmcnt(4)
	v_mfma_f32_32x32x16_bf16 v[50:65], v[104:107], v[120:123], v[50:65]
	v_max3_f32 v98, v98, v66, v67
	v_max3_f32 v98, v98, v68, v69
	v_max3_f32 v98, v98, v70, v71
	v_max3_f32 v98, v98, v72, v73
	v_max3_f32 v98, v98, v74, v75
	v_max3_f32 v98, v98, v76, v77
	v_max3_f32 v98, v98, v78, v79
	v_max3_f32 v98, v98, v80, v81
	s_waitcnt lgkmcnt(2)
	v_mfma_f32_32x32x16_bf16 v[50:65], v[108:111], v[124:127], v[50:65]
	v_mov_b32_e32 v99, v98
	s_nop 1
	v_permlane32_swap_b32_e32 v98, v99
	v_max_f32_e32 v99, v99, v99
	v_max_f32_e32 v98, v98, v98
	v_max_f32_e32 v98, v98, v99
	v_sub_f32_e32 v99, v98, v130
	v_mul_f32_e32 v99, 0x3e0293ee, v99
	v_cmp_ge_f32_e32 vcc, s24, v99
	v_max_f32_e32 v99, v130, v130
	v_max_f32_e32 v99, v99, v98
	s_waitcnt lgkmcnt(0)
	v_mfma_f32_32x32x16_bf16 v[50:65], v[112:115], v[132:135], v[50:65]
	v_sub_f32_e32 v98, v130, v99
	v_mul_f32_e32 v98, 0x3e0293ee, v98
	v_exp_f32_e32 v98, v98
	s_cmp_eq_u64 vcc, exec
	s_cselect_b64 s[40:41], -1, 0
	v_cndmask_b32_e64 v98, v98, 1.0, s[40:41]
	v_cmp_gt_f32_e32 vcc, 1.0, v98
	s_cbranch_vccz .LBB0_1426
	s_and_saveexec_b64 s[4:5], s[38:39]
	ds_write_b32 v159, v98 offset:128
	s_or_b64 exec, exec, s[4:5]
	s_waitcnt lgkmcnt(0)
	v_add_u32_e32 v100, s42, v162
	ds_read_b128 v[104:107], v100 offset:224
	ds_read_b128 v[108:111], v100 offset:192
	ds_read_b128 v[112:115], v100 offset:160
	ds_read_b128 v[116:119], v100 offset:128
	s_waitcnt lgkmcnt(3)
	v_mul_f32 v14, v14, v104
	v_mul_f32 v15, v15, v105
	s_waitcnt lgkmcnt(2)
	v_mul_f32 v10, v10, v108
	v_mul_f32 v11, v11, v109
	s_waitcnt lgkmcnt(1)
	v_mul_f32 v6, v6, v112
	v_mul_f32 v7, v7, v113
	v_mul_f32 v16, v16, v106
	v_mul_f32 v17, v17, v107
	v_mul_f32 v12, v12, v110
	v_mul_f32 v13, v13, v111
	v_mul_f32 v8, v8, v114
	v_mul_f32 v9, v9, v115
	s_waitcnt lgkmcnt(0)
	v_mul_f32 v4, v4, v118
	v_mul_f32 v5, v5, v119
	v_mul_f32 v2, v2, v116
	v_mul_f32 v3, v3, v117
	v_mul_f32 v30, v30, v104
	v_mul_f32 v31, v31, v105
	v_mul_f32 v26, v26, v108
	v_mul_f32 v27, v27, v109
	v_mul_f32 v22, v22, v112
	v_mul_f32 v23, v23, v113
	v_mul_f32 v32, v32, v106
	v_mul_f32 v33, v33, v107
	v_mul_f32 v28, v28, v110
	v_mul_f32 v29, v29, v111
	v_mul_f32 v24, v24, v114
	v_mul_f32 v25, v25, v115
	v_mul_f32 v20, v20, v118
	v_mul_f32 v21, v21, v119
	v_mul_f32 v18, v18, v116
	v_mul_f32 v19, v19, v117
	v_mul_f32 v46, v46, v104
	v_mul_f32 v47, v47, v105
	v_mul_f32 v42, v42, v108
	v_mul_f32 v43, v43, v109
	v_mul_f32 v38, v38, v112
	v_mul_f32 v39, v39, v113
	v_mul_f32 v48, v48, v106
	v_mul_f32 v49, v49, v107
	v_mul_f32 v44, v44, v110
	v_mul_f32 v45, v45, v111
	v_mul_f32 v40, v40, v114
	v_mul_f32 v41, v41, v115
	v_mul_f32 v36, v36, v118
	v_mul_f32 v37, v37, v119
	v_mul_f32 v34, v34, v116
	v_mul_f32 v35, v35, v117
	v_mul_f32 v62, v62, v104
	v_mul_f32 v63, v63, v105
	v_mul_f32 v58, v58, v108
	v_mul_f32 v59, v59, v109
	v_mul_f32 v54, v54, v112
	v_mul_f32 v55, v55, v113
	v_mul_f32 v64, v64, v106
	v_mul_f32 v65, v65, v107
	v_mul_f32 v60, v60, v110
	v_mul_f32 v61, v61, v111
	v_mul_f32 v56, v56, v114
	v_mul_f32 v57, v57, v115
	v_mul_f32 v52, v52, v118
	v_mul_f32 v53, v53, v119
	v_mul_f32 v50, v50, v116
	v_mul_f32 v51, v51, v117
